# GEMM K-loops: graduated lgkmcnt waits inside the MFMA clusters
# baseline (speedup 1.0000x reference)
; #define PG8_STAGE(bufoff, gbase, voff) do { _Pragma("unroll") for (int _i = 0; _i < 2; ++_i) \
;     __builtin_amdgcn_global_load_lds((const unsigned*)((const char*)(gbase) + (voff)[_i]), (LAS unsigned*)(lds + (bufoff) + ldsw + _i * 8192), 16, 0, 0); } while (0)
; #define PG8_LDA(dst, b, h) do { _Pragma("unroll") for (int m = 0; m < 4; ++m) _Pragma("unroll") for (int k = 0; k < 2; ++k) dst[m][k] = *(const LAS bf16x8*)(lds + PG8_SA(b, h) + aoff + m * 2048 + k * 1024); } while (0)
; #define PG8_LDB(dst, b, h) do { _Pragma("unroll") for (int n = 0; n < 2; ++n) _Pragma("unroll") for (int k = 0; k < 2; ++k) dst[n][k] = *(const LAS bf16x8*)(lds + PG8_SB(b, h) + boff + n * 2048 + k * 1024); } while (0)
; #define PG8_MMA(ai, bj, At, Bt) do { __builtin_amdgcn_s_setprio(1); _Pragma("unroll") for (int m = 0; m < 4; ++m) _Pragma("unroll") for (int n = 0; n < 2; ++n) _Pragma("unroll") for (int k = 0; k < 2; ++k) \
;     acc[ai][bj][m][n] = __builtin_amdgcn_mfma_f32_16x16x32_bf16(Bt[n][k], At[m][k], acc[ai][bj][m][n], 0, 0, 0); __builtin_amdgcn_s_setprio(0); } while (0)
; #define PG8_WAIT_L(n) asm volatile("s_waitcnt lgkmcnt(" #n ")" ::: "memory")
; #define PG8_BAR __builtin_amdgcn_s_barrier()
; #define PG8_SCHED __builtin_amdgcn_sched_barrier(0)
; template <class Epi, class Sched>
; DI void gemm_phase(LAS unsigned char* lds, const Gemm g, const Sched& S, const Epi& E) {
;     ...
;       const bool last = (t == nt - 2);
;       const char* a1 = cA + (size_t)(t + 1) * kstep;
;       const char* a2 = last ? nA : cA + (size_t)(t + 2) * kstep; const char* b2 = last ? nB : cB + (size_t)(t + 2) * kstep;
;       const char* a3 = a2 + kstep; const char* b3 = b2 + kstep;
;       PG8_LDB(B0, 0, 0); PG8_SCHED; PG8_LDA(At, 0, 0); PG8_STAGE(PG8_SA(1, 1), a1 + hstep, voffA);
;       PG8_WAIT_L(8); PG8_BAR; PG8_WAIT_L(0); PG8_MMA(0, 0, At, B0); PG8_BAR; PG8_SCHED;
;       PG8_LDB(B1, 0, 1); PG8_STAGE(PG8_SB(0, 0), b2, voffB);
;       PG8_BAR; PG8_WAIT_L(0); PG8_MMA(0, 1, At, B1); PG8_BAR;
;       PG8_LDA(At, 0, 1); PG8_STAGE(PG8_SA(0, 0), a2, voffA);
;       PG8_BAR; PG8_WAIT_L(0); PG8_MMA(1, 0, At, B0); PG8_BAR; PG8_SCHED;
.LBB0_370:
	s_add_u32 s4, s2, 0xfffc0080
	s_addc_u32 s5, s3, -1
	s_add_i32 s51, 0, 0x10000
	ds_read_b128 v[128:131], v228
	ds_read_b128 v[146:149], v228 offset:1024
	ds_read_b128 v[150:153], v228 offset:2048
	ds_read_b128 v[160:163], v228 offset:3072
	s_cmp_eq_u32 s50, 12
	s_cselect_b32 s21, s15, s5
	s_cselect_b32 s20, s29, s4
	s_cselect_b32 s5, s13, s49
	s_cselect_b32 s4, s36, s37
	s_add_i32 m0, s40, 0xc000
	ds_read_b128 v[164:167], v158
	ds_read_b128 v[168:171], v158 offset:1024
	ds_read_b128 v[172:175], v158 offset:2048
	ds_read_b128 v[176:179], v158 offset:3072
	ds_read_b128 v[196:199], v158 offset:4096
	ds_read_b128 v[200:203], v158 offset:5120
	ds_read_b128 v[204:207], v158 offset:6144
	ds_read_b128 v[208:211], v158 offset:7168
	global_load_lds_dwordx4 v140, s[2:3]
	s_add_i32 m0, s40, 0xe000
	s_nop 0
	global_load_lds_dwordx4 v142, s[2:3]
	s_waitcnt lgkmcnt(8)
	s_barrier
	s_waitcnt lgkmcnt(7)
	v_mfma_f32_16x16x32_bf16 v[124:127], v[128:131], v[164:167], v[124:127]
	v_mfma_f32_16x16x32_bf16 v[120:123], v[150:153], v[164:167], v[120:123]
	s_waitcnt lgkmcnt(5)
	v_mfma_f32_16x16x32_bf16 v[108:111], v[128:131], v[172:175], v[108:111]
	v_mfma_f32_16x16x32_bf16 v[104:107], v[150:153], v[172:175], v[104:107]
	s_waitcnt lgkmcnt(3)
	v_mfma_f32_16x16x32_bf16 v[92:95], v[128:131], v[196:199], v[92:95]
	v_mfma_f32_16x16x32_bf16 v[88:91], v[150:153], v[196:199], v[88:91]
	s_waitcnt lgkmcnt(1)
	v_mfma_f32_16x16x32_bf16 v[76:79], v[128:131], v[204:207], v[76:79]
	v_mfma_f32_16x16x32_bf16 v[72:75], v[150:153], v[204:207], v[72:75]
	v_mfma_f32_16x16x32_bf16 v[124:127], v[146:149], v[168:171], v[124:127]
	v_mfma_f32_16x16x32_bf16 v[120:123], v[160:163], v[168:171], v[120:123]
	v_mfma_f32_16x16x32_bf16 v[108:111], v[146:149], v[176:179], v[108:111]
	v_mfma_f32_16x16x32_bf16 v[104:107], v[160:163], v[176:179], v[104:107]
	v_mfma_f32_16x16x32_bf16 v[92:95], v[146:149], v[200:203], v[92:95]
	v_mfma_f32_16x16x32_bf16 v[88:91], v[160:163], v[200:203], v[88:91]
	s_waitcnt lgkmcnt(0)
	v_mfma_f32_16x16x32_bf16 v[76:79], v[146:149], v[208:211], v[76:79]
	v_mfma_f32_16x16x32_bf16 v[72:75], v[160:163], v[208:211], v[72:75]
	s_barrier
	s_add_i32 s54, 0, 0x14000
	s_add_i32 s51, s51, s34
	s_add_u32 vcc_lo, s4, s0
	s_addc_u32 vcc_hi, s5, s1
	s_mov_b32 m0, s51
	ds_read_b128 v[212:215], v229
	ds_read_b128 v[216:219], v229 offset:1024
	ds_read_b128 v[220:223], v229 offset:2048
	ds_read_b128 v[224:227], v229 offset:3072
	global_load_lds_dwordx4 v136, s[4:5]
	s_add_i32 m0, s51, 0x2000
	s_nop 0
	global_load_lds_dwordx4 v132, s[4:5]
	s_barrier
	s_waitcnt lgkmcnt(3)
	v_mfma_f32_16x16x32_bf16 v[116:119], v[212:215], v[164:167], v[116:119]
	s_waitcnt lgkmcnt(1)
	v_mfma_f32_16x16x32_bf16 v[112:115], v[220:223], v[164:167], v[112:115]
	v_mfma_f32_16x16x32_bf16 v[100:103], v[212:215], v[172:175], v[100:103]
	v_mfma_f32_16x16x32_bf16 v[96:99], v[220:223], v[172:175], v[96:99]
	v_mfma_f32_16x16x32_bf16 v[84:87], v[212:215], v[196:199], v[84:87]
	v_mfma_f32_16x16x32_bf16 v[80:83], v[220:223], v[196:199], v[80:83]
	v_mfma_f32_16x16x32_bf16 v[68:71], v[212:215], v[204:207], v[68:71]
	v_mfma_f32_16x16x32_bf16 v[64:67], v[220:223], v[204:207], v[64:67]
	v_mfma_f32_16x16x32_bf16 v[116:119], v[216:219], v[168:171], v[116:119]
	s_waitcnt lgkmcnt(0)
	v_mfma_f32_16x16x32_bf16 v[112:115], v[224:227], v[168:171], v[112:115]
	v_mfma_f32_16x16x32_bf16 v[100:103], v[216:219], v[176:179], v[100:103]
	v_mfma_f32_16x16x32_bf16 v[96:99], v[224:227], v[176:179], v[96:99]
	v_mfma_f32_16x16x32_bf16 v[84:87], v[216:219], v[200:203], v[84:87]
	v_mfma_f32_16x16x32_bf16 v[80:83], v[224:227], v[200:203], v[80:83]
	v_mfma_f32_16x16x32_bf16 v[68:71], v[216:219], v[208:211], v[68:71]
	v_mfma_f32_16x16x32_bf16 v[64:67], v[224:227], v[208:211], v[64:67]
	s_mov_b32 m0, s40
	s_add_u32 s100, s20, s0
	s_addc_u32 s101, s21, s1
	s_barrier
	ds_read_b128 v[164:167], v158 offset:16384
	ds_read_b128 v[168:171], v158 offset:17408
	ds_read_b128 v[172:175], v158 offset:18432
	ds_read_b128 v[176:179], v158 offset:19456
	ds_read_b128 v[196:199], v158 offset:20480
	ds_read_b128 v[200:203], v158 offset:21504
	ds_read_b128 v[204:207], v158 offset:22528
	ds_read_b128 v[208:211], v158 offset:23552
	global_load_lds_dwordx4 v138, s[20:21]
	s_mov_b32 m0, s41
	s_nop 0
	global_load_lds_dwordx4 v134, s[20:21]
	s_barrier
	s_waitcnt lgkmcnt(7)
	v_mfma_f32_16x16x32_bf16 v[60:63], v[128:131], v[164:167], v[60:63]
	v_mfma_f32_16x16x32_bf16 v[56:59], v[150:153], v[164:167], v[56:59]
	s_waitcnt lgkmcnt(5)
	v_mfma_f32_16x16x32_bf16 v[44:47], v[128:131], v[172:175], v[44:47]
	v_mfma_f32_16x16x32_bf16 v[40:43], v[150:153], v[172:175], v[40:43]
	s_waitcnt lgkmcnt(3)
	v_mfma_f32_16x16x32_bf16 v[28:31], v[128:131], v[196:199], v[28:31]
	v_mfma_f32_16x16x32_bf16 v[24:27], v[150:153], v[196:199], v[24:27]
	s_waitcnt lgkmcnt(1)
	v_mfma_f32_16x16x32_bf16 v[12:15], v[128:131], v[204:207], v[12:15]
	v_mfma_f32_16x16x32_bf16 v[8:11], v[150:153], v[204:207], v[8:11]
	v_mfma_f32_16x16x32_bf16 v[60:63], v[146:149], v[168:171], v[60:63]
	v_mfma_f32_16x16x32_bf16 v[56:59], v[160:163], v[168:171], v[56:59]
	v_mfma_f32_16x16x32_bf16 v[44:47], v[146:149], v[176:179], v[44:47]
	v_mfma_f32_16x16x32_bf16 v[40:43], v[160:163], v[176:179], v[40:43]
	v_mfma_f32_16x16x32_bf16 v[28:31], v[146:149], v[200:203], v[28:31]
	v_mfma_f32_16x16x32_bf16 v[24:27], v[160:163], v[200:203], v[24:27]
	s_waitcnt lgkmcnt(0)
	v_mfma_f32_16x16x32_bf16 v[12:15], v[146:149], v[208:211], v[12:15]
	v_mfma_f32_16x16x32_bf16 v[8:11], v[160:163], v[208:211], v[8:11]
	s_barrier
; #define PG8_STAGE(bufoff, gbase, voff) do { _Pragma("unroll") for (int _i = 0; _i < 2; ++_i) \
;     __builtin_amdgcn_global_load_lds((const unsigned*)((const char*)(gbase) + (voff)[_i]), (LAS unsigned*)(lds + (bufoff) + ldsw + _i * 8192), 16, 0, 0); } while (0)
; #define PG8_LDA(dst, b, h) do { _Pragma("unroll") for (int m = 0; m < 4; ++m) _Pragma("unroll") for (int k = 0; k < 2; ++k) dst[m][k] = *(const LAS bf16x8*)(lds + PG8_SA(b, h) + aoff + m * 2048 + k * 1024); } while (0)
; #define PG8_LDB(dst, b, h) do { _Pragma("unroll") for (int n = 0; n < 2; ++n) _Pragma("unroll") for (int k = 0; k < 2; ++k) dst[n][k] = *(const LAS bf16x8*)(lds + PG8_SB(b, h) + boff + n * 2048 + k * 1024); } while (0)
; #define PG8_MMA(ai, bj, At, Bt) do { __builtin_amdgcn_s_setprio(1); _Pragma("unroll") for (int m = 0; m < 4; ++m) _Pragma("unroll") for (int n = 0; n < 2; ++n) _Pragma("unroll") for (int k = 0; k < 2; ++k) \
;     acc[ai][bj][m][n] = __builtin_amdgcn_mfma_f32_16x16x32_bf16(Bt[n][k], At[m][k], acc[ai][bj][m][n], 0, 0, 0); __builtin_amdgcn_s_setprio(0); } while (0)
; #define PG8_WAIT_V(n) asm volatile("s_waitcnt vmcnt(" #n ")" ::: "memory")
; #define PG8_WAIT_L(n) asm volatile("s_waitcnt lgkmcnt(" #n ")" ::: "memory")
; #define PG8_BAR __builtin_amdgcn_s_barrier()
; #define PG8_SCHED __builtin_amdgcn_sched_barrier(0)
; template <class Epi, class Sched>
; DI void gemm_phase(LAS unsigned char* lds, const Gemm g, const Sched& S, const Epi& E) {
;     ...
;       PG8_STAGE(PG8_SB(0, 1), b2 + hstep, voffB);
;       PG8_WAIT_V(6); PG8_BAR; PG8_MMA(1, 1, At, B1); PG8_BAR;
;       PG8_LDB(B0, 1, 0); PG8_SCHED; PG8_LDA(At, 1, 0); PG8_STAGE(PG8_SA(0, 1), a2 + hstep, voffA);
;       PG8_WAIT_L(8); PG8_BAR; PG8_WAIT_L(0); PG8_MMA(0, 0, At, B0); PG8_BAR; PG8_SCHED;
;       PG8_LDB(B1, 1, 1); PG8_STAGE(PG8_SB(1, 0), b3, voffB);
;       PG8_BAR; PG8_WAIT_L(0); PG8_MMA(0, 1, At, B1); PG8_BAR;
	s_add_u32 s52, s4, 0x40000
	s_addc_u32 s53, s5, 0
	s_add_i32 s51, s54, s34
	s_mov_b32 m0, s51
	s_nop 0
	global_load_lds_dwordx4 v136, s[52:53]
	s_add_i32 m0, s51, 0x2000
	s_nop 0
	global_load_lds_dwordx4 v132, s[52:53]
	s_waitcnt vmcnt(6)
	s_barrier
	v_mfma_f32_16x16x32_bf16 v[52:55], v[212:215], v[164:167], v[52:55]
	v_mfma_f32_16x16x32_bf16 v[48:51], v[220:223], v[164:167], v[48:51]
	v_mfma_f32_16x16x32_bf16 v[36:39], v[212:215], v[172:175], v[36:39]
	v_mfma_f32_16x16x32_bf16 v[32:35], v[220:223], v[172:175], v[32:35]
	v_mfma_f32_16x16x32_bf16 v[20:23], v[212:215], v[196:199], v[20:23]
	v_mfma_f32_16x16x32_bf16 v[16:19], v[220:223], v[196:199], v[16:19]
	v_mfma_f32_16x16x32_bf16 v[4:7], v[212:215], v[204:207], v[4:7]
	v_mfma_f32_16x16x32_bf16 v[0:3], v[220:223], v[204:207], v[0:3]
	v_mfma_f32_16x16x32_bf16 v[52:55], v[216:219], v[168:171], v[52:55]
	v_mfma_f32_16x16x32_bf16 v[48:51], v[224:227], v[168:171], v[48:51]
	v_mfma_f32_16x16x32_bf16 v[36:39], v[216:219], v[176:179], v[36:39]
	v_mfma_f32_16x16x32_bf16 v[32:35], v[224:227], v[176:179], v[32:35]
	v_mfma_f32_16x16x32_bf16 v[20:23], v[216:219], v[200:203], v[20:23]
	v_mfma_f32_16x16x32_bf16 v[16:19], v[224:227], v[200:203], v[16:19]
	v_mfma_f32_16x16x32_bf16 v[4:7], v[216:219], v[208:211], v[4:7]
	v_mfma_f32_16x16x32_bf16 v[0:3], v[224:227], v[208:211], v[0:3]
	s_add_i32 s51, 0, 0x18000
	s_barrier
	ds_read_b128 v[128:131], v230
	ds_read_b128 v[146:149], v230 offset:1024
	ds_read_b128 v[150:153], v230 offset:2048
	ds_read_b128 v[160:163], v230 offset:3072
	s_add_u32 s20, s20, 0x40000
	s_addc_u32 s21, s21, 0
	s_mov_b32 m0, s42
	ds_read_b128 v[164:167], v158 offset:32768
	ds_read_b128 v[168:171], v158 offset:33792
	ds_read_b128 v[172:175], v158 offset:34816
	ds_read_b128 v[176:179], v158 offset:35840
	ds_read_b128 v[196:199], v158 offset:36864
	ds_read_b128 v[200:203], v158 offset:37888
	ds_read_b128 v[204:207], v158 offset:38912
	ds_read_b128 v[208:211], v158 offset:39936
	global_load_lds_dwordx4 v138, s[20:21]
	s_mov_b32 m0, s43
	s_nop 0
	global_load_lds_dwordx4 v134, s[20:21]
	s_waitcnt lgkmcnt(8)
	s_barrier
	s_waitcnt lgkmcnt(7)
	v_mfma_f32_16x16x32_bf16 v[124:127], v[128:131], v[164:167], v[124:127]
	v_mfma_f32_16x16x32_bf16 v[120:123], v[150:153], v[164:167], v[120:123]
	s_waitcnt lgkmcnt(5)
	v_mfma_f32_16x16x32_bf16 v[108:111], v[128:131], v[172:175], v[108:111]
	v_mfma_f32_16x16x32_bf16 v[104:107], v[150:153], v[172:175], v[104:107]
	s_waitcnt lgkmcnt(3)
	v_mfma_f32_16x16x32_bf16 v[92:95], v[128:131], v[196:199], v[92:95]
	v_mfma_f32_16x16x32_bf16 v[88:91], v[150:153], v[196:199], v[88:91]
	s_waitcnt lgkmcnt(1)
	v_mfma_f32_16x16x32_bf16 v[76:79], v[128:131], v[204:207], v[76:79]
	v_mfma_f32_16x16x32_bf16 v[72:75], v[150:153], v[204:207], v[72:75]
	v_mfma_f32_16x16x32_bf16 v[124:127], v[146:149], v[168:171], v[124:127]
	v_mfma_f32_16x16x32_bf16 v[120:123], v[160:163], v[168:171], v[120:123]
	v_mfma_f32_16x16x32_bf16 v[108:111], v[146:149], v[176:179], v[108:111]
	v_mfma_f32_16x16x32_bf16 v[104:107], v[160:163], v[176:179], v[104:107]
	v_mfma_f32_16x16x32_bf16 v[92:95], v[146:149], v[200:203], v[92:95]
	v_mfma_f32_16x16x32_bf16 v[88:91], v[160:163], v[200:203], v[88:91]
	s_waitcnt lgkmcnt(0)
	v_mfma_f32_16x16x32_bf16 v[76:79], v[146:149], v[208:211], v[76:79]
	v_mfma_f32_16x16x32_bf16 v[72:75], v[160:163], v[208:211], v[72:75]
	s_barrier
	s_add_i32 s20, 0, 0x1c000
	s_add_i32 s21, s51, s34
	s_mov_b32 m0, s21
	ds_read_b128 v[212:215], v231
	ds_read_b128 v[216:219], v231 offset:1024
	ds_read_b128 v[220:223], v231 offset:2048
	ds_read_b128 v[224:227], v231 offset:3072
	global_load_lds_dwordx4 v136, vcc
	s_add_i32 m0, s21, 0x2000
	s_nop 0
	global_load_lds_dwordx4 v132, vcc
	s_barrier
	s_waitcnt lgkmcnt(3)
	v_mfma_f32_16x16x32_bf16 v[116:119], v[212:215], v[164:167], v[116:119]
	s_waitcnt lgkmcnt(1)
	v_mfma_f32_16x16x32_bf16 v[112:115], v[220:223], v[164:167], v[112:115]
	v_mfma_f32_16x16x32_bf16 v[100:103], v[212:215], v[172:175], v[100:103]
	v_mfma_f32_16x16x32_bf16 v[96:99], v[220:223], v[172:175], v[96:99]
	v_mfma_f32_16x16x32_bf16 v[84:87], v[212:215], v[196:199], v[84:87]
	v_mfma_f32_16x16x32_bf16 v[80:83], v[220:223], v[196:199], v[80:83]
	v_mfma_f32_16x16x32_bf16 v[68:71], v[212:215], v[204:207], v[68:71]
	v_mfma_f32_16x16x32_bf16 v[64:67], v[220:223], v[204:207], v[64:67]
	v_mfma_f32_16x16x32_bf16 v[116:119], v[216:219], v[168:171], v[116:119]
	s_waitcnt lgkmcnt(0)
	v_mfma_f32_16x16x32_bf16 v[112:115], v[224:227], v[168:171], v[112:115]
	v_mfma_f32_16x16x32_bf16 v[100:103], v[216:219], v[176:179], v[100:103]
	v_mfma_f32_16x16x32_bf16 v[96:99], v[224:227], v[176:179], v[96:99]
	v_mfma_f32_16x16x32_bf16 v[84:87], v[216:219], v[200:203], v[84:87]
	v_mfma_f32_16x16x32_bf16 v[80:83], v[224:227], v[200:203], v[80:83]
	v_mfma_f32_16x16x32_bf16 v[68:71], v[216:219], v[208:211], v[68:71]
	v_mfma_f32_16x16x32_bf16 v[64:67], v[224:227], v[208:211], v[64:67]
	s_mov_b32 m0, s46
	s_barrier
; #define PG8_STAGE(bufoff, gbase, voff) do { _Pragma("unroll") for (int _i = 0; _i < 2; ++_i) \
;     __builtin_amdgcn_global_load_lds((const unsigned*)((const char*)(gbase) + (voff)[_i]), (LAS unsigned*)(lds + (bufoff) + ldsw + _i * 8192), 16, 0, 0); } while (0)
; #define PG8_LDA(dst, b, h) do { _Pragma("unroll") for (int m = 0; m < 4; ++m) _Pragma("unroll") for (int k = 0; k < 2; ++k) dst[m][k] = *(const LAS bf16x8*)(lds + PG8_SA(b, h) + aoff + m * 2048 + k * 1024); } while (0)
; #define PG8_MMA(ai, bj, At, Bt) do { __builtin_amdgcn_s_setprio(1); _Pragma("unroll") for (int m = 0; m < 4; ++m) _Pragma("unroll") for (int n = 0; n < 2; ++n) _Pragma("unroll") for (int k = 0; k < 2; ++k) \
;     acc[ai][bj][m][n] = __builtin_amdgcn_mfma_f32_16x16x32_bf16(Bt[n][k], At[m][k], acc[ai][bj][m][n], 0, 0, 0); __builtin_amdgcn_s_setprio(0); } while (0)
; #define PG8_WAIT_V(n) asm volatile("s_waitcnt vmcnt(" #n ")" ::: "memory")
; #define PG8_WAIT_L(n) asm volatile("s_waitcnt lgkmcnt(" #n ")" ::: "memory")
; #define PG8_BAR __builtin_amdgcn_s_barrier()
; #define PG8_SCHED __builtin_amdgcn_sched_barrier(0)
; template <class Epi, class Sched>
; DI void gemm_phase(LAS unsigned char* lds, const Gemm g, const Sched& S, const Epi& E) {
;     ...
;       PG8_LDA(At, 1, 1); PG8_STAGE(PG8_SA(1, 0), a3, voffA);
;       PG8_BAR; PG8_WAIT_L(0); PG8_MMA(1, 0, At, B0); PG8_BAR; PG8_SCHED;
;       PG8_STAGE(PG8_SB(1, 1), b3 + hstep, voffB);
;       PG8_WAIT_V(6); PG8_BAR; PG8_MMA(1, 1, At, B1); PG8_BAR;
;     }
;   DI void operator()(const f32x4 (&acc)[2][2][4][2], const pg8::Unit& u, int wr, int wc, int fr_, int fq_) const {
;     ...
;             } else if (EPI == EPI_CIN) {
;               if (n == 0) {
;                 const int gb = u.pn * 256 + bj * 128 + wc * 32;
;                 const int f8 = gb + 8 * fq;
;                 const f32x4 v1 = acc[ai][bj][m][1];
;                 if (gb < 1024) st_bf8((u16*)(big + O_QD) + (size_t)token * 1024 + f8, v, v1, rinv * (0.125f * LOG2E));
;                 else if (gb < 2048) st_bf8((u16*)(big + O_KD) + (size_t)token * 1024 + (f8 - 1024), v, v1, rinv);
;                 else st_bf8((u16*)(big + O_VDT) + (size_t)token * 1024 + (f8 - 2048), v, v1, rinv);
	ds_read_b128 v[164:167], v158 offset:49152
	ds_read_b128 v[168:171], v158 offset:50176
	ds_read_b128 v[172:175], v158 offset:51200
	ds_read_b128 v[176:179], v158 offset:52224
	ds_read_b128 v[196:199], v158 offset:53248
	ds_read_b128 v[200:203], v158 offset:54272
	ds_read_b128 v[204:207], v158 offset:55296
	ds_read_b128 v[208:211], v158 offset:56320
	global_load_lds_dwordx4 v138, s[100:101]
	s_mov_b32 m0, s47
	s_nop 0
	global_load_lds_dwordx4 v134, s[100:101]
	s_barrier
	s_waitcnt lgkmcnt(7)
	v_mfma_f32_16x16x32_bf16 v[60:63], v[128:131], v[164:167], v[60:63]
	v_mfma_f32_16x16x32_bf16 v[56:59], v[150:153], v[164:167], v[56:59]
	s_waitcnt lgkmcnt(5)
	v_mfma_f32_16x16x32_bf16 v[44:47], v[128:131], v[172:175], v[44:47]
	v_mfma_f32_16x16x32_bf16 v[40:43], v[150:153], v[172:175], v[40:43]
	s_waitcnt lgkmcnt(3)
	v_mfma_f32_16x16x32_bf16 v[28:31], v[128:131], v[196:199], v[28:31]
	v_mfma_f32_16x16x32_bf16 v[24:27], v[150:153], v[196:199], v[24:27]
	s_waitcnt lgkmcnt(1)
	v_mfma_f32_16x16x32_bf16 v[12:15], v[128:131], v[204:207], v[12:15]
	v_mfma_f32_16x16x32_bf16 v[8:11], v[150:153], v[204:207], v[8:11]
	v_mfma_f32_16x16x32_bf16 v[60:63], v[146:149], v[168:171], v[60:63]
	v_mfma_f32_16x16x32_bf16 v[56:59], v[160:163], v[168:171], v[56:59]
	v_mfma_f32_16x16x32_bf16 v[44:47], v[146:149], v[176:179], v[44:47]
	v_mfma_f32_16x16x32_bf16 v[40:43], v[160:163], v[176:179], v[40:43]
	v_mfma_f32_16x16x32_bf16 v[28:31], v[146:149], v[200:203], v[28:31]
	v_mfma_f32_16x16x32_bf16 v[24:27], v[160:163], v[200:203], v[24:27]
	s_waitcnt lgkmcnt(0)
	v_mfma_f32_16x16x32_bf16 v[12:15], v[146:149], v[208:211], v[12:15]
	v_mfma_f32_16x16x32_bf16 v[8:11], v[160:163], v[208:211], v[8:11]
	s_barrier
	s_add_u32 s4, s4, 0x40080
	s_addc_u32 s5, s5, 0
	s_add_i32 s20, s20, s34
	s_mov_b32 m0, s20
	s_nop 0
	global_load_lds_dwordx4 v136, s[4:5]
	s_add_i32 m0, s20, 0x2000
	s_nop 0
	global_load_lds_dwordx4 v132, s[4:5]
	s_waitcnt vmcnt(6)
	s_barrier
	v_mfma_f32_16x16x32_bf16 v[52:55], v[212:215], v[164:167], v[52:55]
	v_mfma_f32_16x16x32_bf16 v[48:51], v[220:223], v[164:167], v[48:51]
	v_mfma_f32_16x16x32_bf16 v[36:39], v[212:215], v[172:175], v[36:39]
	v_mfma_f32_16x16x32_bf16 v[32:35], v[220:223], v[172:175], v[32:35]
	v_mfma_f32_16x16x32_bf16 v[20:23], v[212:215], v[196:199], v[20:23]
	v_mfma_f32_16x16x32_bf16 v[16:19], v[220:223], v[196:199], v[16:19]
	v_mfma_f32_16x16x32_bf16 v[4:7], v[212:215], v[204:207], v[4:7]
	v_mfma_f32_16x16x32_bf16 v[0:3], v[220:223], v[204:207], v[0:3]
	v_mfma_f32_16x16x32_bf16 v[52:55], v[216:219], v[168:171], v[52:55]
	v_mfma_f32_16x16x32_bf16 v[48:51], v[224:227], v[168:171], v[48:51]
	v_mfma_f32_16x16x32_bf16 v[36:39], v[216:219], v[176:179], v[36:39]
	v_mfma_f32_16x16x32_bf16 v[32:35], v[224:227], v[176:179], v[32:35]
	v_mfma_f32_16x16x32_bf16 v[20:23], v[216:219], v[200:203], v[20:23]
	v_mfma_f32_16x16x32_bf16 v[16:19], v[224:227], v[200:203], v[16:19]
	v_mfma_f32_16x16x32_bf16 v[4:7], v[216:219], v[208:211], v[4:7]
	v_mfma_f32_16x16x32_bf16 v[0:3], v[224:227], v[208:211], v[0:3]
	s_add_i32 s50, s50, 2
	s_add_u32 s2, s2, 0x100
	s_addc_u32 s3, s3, 0
	s_add_u32 s37, s37, 0x100
	s_addc_u32 s49, s49, 0
	s_cmp_gt_u32 s50, 13
	s_barrier
	s_cbranch_scc0 .LBB0_370
	v_mov_b32_e32 v128, v182
	s_lshl_b32 s2, s22, 10
	v_and_or_b32 v160, v128, 15, s44
	v_lshrrev_b32_e32 v128, 1, v128
	s_add_i32 s2, s2, 0
	v_and_b32_e32 v146, 24, v128
	v_lshl_add_u32 v128, v160, 2, s2
	v_add_u32_e32 v159, 0x20000, v128
	s_lshl_b32 s13, s28, 8
	s_lshl_b32 s3, s23, 8
	ds_read_b32 v154, v159
	v_add_u32_e32 v150, s13, v160
	s_or_b32 s20, s3, s45
	v_ashrrev_i32_e32 v151, 31, v150
	s_cmpk_gt_i32 s20, 0x3ff
	v_lshlrev_b64 v[128:129], 11, v[150:151]
	v_or_b32_e32 v148, s20, v146
	s_cselect_b64 s[4:5], -1, 0
	s_cmpk_gt_u32 s3, 0x7ff
	s_cselect_b64 s[2:3], -1, 0
	v_mov_b32_e32 v144, v148
	v_lshl_add_u64 v[152:153], s[10:11], 0, v[128:129]
	s_mov_b64 s[22:23], -1
	s_and_b64 vcc, exec, s[4:5]
	s_cbranch_vccz .LBB0_377
	s_waitcnt lgkmcnt(0)
	v_pk_mul_f32 v[128:129], v[124:125], v[154:155] op_sel_hi:[1,0]
	v_pk_mul_f32 v[130:131], v[126:127], v[154:155] op_sel_hi:[1,0]
	v_cvt_pk_bf16_f32 v128, v128, v129
	v_cvt_pk_bf16_f32 v129, v130, v131
	v_pk_mul_f32 v[130:131], v[120:121], v[154:155] op_sel_hi:[1,0]
	v_pk_mul_f32 v[162:163], v[122:123], v[154:155] op_sel_hi:[1,0]
	v_lshl_add_u64 v[156:157], v[144:145], 1, v[152:153]
	v_cvt_pk_bf16_f32 v130, v130, v131
	v_cvt_pk_bf16_f32 v131, v162, v163
	s_and_b64 vcc, exec, s[2:3]
	s_cbranch_vccz .LBB0_374
	v_add_co_u32_e32 v162, vcc, 0x7fff000, v156
	s_mov_b64 s[22:23], 0
	s_nop 0
	v_addc_co_u32_e32 v163, vcc, 0, v157, vcc
	global_store_dwordx4 v[162:163], v[128:131], off

; #define PG8_STAGE(bufoff, gbase, voff) do { _Pragma("unroll") for (int _i = 0; _i < 2; ++_i) \
;     __builtin_amdgcn_global_load_lds((const unsigned*)((const char*)(gbase) + (voff)[_i]), (LAS unsigned*)(lds + (bufoff) + ldsw + _i * 8192), 16, 0, 0); } while (0)
; #define PG8_LDA(dst, b, h) do { _Pragma("unroll") for (int m = 0; m < 4; ++m) _Pragma("unroll") for (int k = 0; k < 2; ++k) dst[m][k] = *(const LAS bf16x8*)(lds + PG8_SA(b, h) + aoff + m * 2048 + k * 1024); } while (0)
; #define PG8_LDB(dst, b, h) do { _Pragma("unroll") for (int n = 0; n < 2; ++n) _Pragma("unroll") for (int k = 0; k < 2; ++k) dst[n][k] = *(const LAS bf16x8*)(lds + PG8_SB(b, h) + boff + n * 2048 + k * 1024); } while (0)
; #define PG8_MMA(ai, bj, At, Bt) do { __builtin_amdgcn_s_setprio(1); _Pragma("unroll") for (int m = 0; m < 4; ++m) _Pragma("unroll") for (int n = 0; n < 2; ++n) _Pragma("unroll") for (int k = 0; k < 2; ++k) \
;     acc[ai][bj][m][n] = __builtin_amdgcn_mfma_f32_16x16x32_bf16(Bt[n][k], At[m][k], acc[ai][bj][m][n], 0, 0, 0); __builtin_amdgcn_s_setprio(0); } while (0)
; #define PG8_WAIT_L(n) asm volatile("s_waitcnt lgkmcnt(" #n ")" ::: "memory")
; #define PG8_BAR __builtin_amdgcn_s_barrier()
; #define PG8_SCHED __builtin_amdgcn_sched_barrier(0)
; template <class Epi, class Sched>
; DI void gemm_phase(LAS unsigned char* lds, const Gemm g, const Sched& S, const Epi& E) {
;     ...
;       const bool last = (t == nt - 2);
;       const char* a1 = cA + (size_t)(t + 1) * kstep;
;       const char* a2 = last ? nA : cA + (size_t)(t + 2) * kstep; const char* b2 = last ? nB : cB + (size_t)(t + 2) * kstep;
;       const char* a3 = a2 + kstep; const char* b3 = b2 + kstep;
;       PG8_LDB(B0, 0, 0); PG8_SCHED; PG8_LDA(At, 0, 0); PG8_STAGE(PG8_SA(1, 1), a1 + hstep, voffA);
;       PG8_WAIT_L(8); PG8_BAR; PG8_WAIT_L(0); PG8_MMA(0, 0, At, B0); PG8_BAR; PG8_SCHED;
;       PG8_LDB(B1, 0, 1); PG8_STAGE(PG8_SB(0, 0), b2, voffB);
;       PG8_BAR; PG8_WAIT_L(0); PG8_MMA(0, 1, At, B1); PG8_BAR;
;       PG8_LDA(At, 0, 1); PG8_STAGE(PG8_SA(0, 0), a2, voffA);
;       PG8_BAR; PG8_WAIT_L(0); PG8_MMA(1, 0, At, B0); PG8_BAR; PG8_SCHED;
.LBB0_689:
	s_add_u32 s22, s20, 0xfffc0080
	s_addc_u32 s23, s21, -1
	s_add_i32 s42, 0, 0x10000
	ds_read_b128 v[128:131], v222
	ds_read_b128 v[132:135], v222 offset:1024
	ds_read_b128 v[150:153], v222 offset:2048
	ds_read_b128 v[154:157], v222 offset:3072
	s_cmp_eq_u32 s41, 12
	s_cselect_b32 s29, s13, s23
	s_cselect_b32 s28, s37, s22
	s_cselect_b32 s23, s15, s40
	s_cselect_b32 s22, s38, s39
	s_add_i32 m0, s56, 0xc000
	ds_read_b128 v[158:161], v197
	ds_read_b128 v[162:165], v197 offset:1024
	ds_read_b128 v[166:169], v197 offset:2048
	ds_read_b128 v[170:173], v197 offset:3072
	ds_read_b128 v[174:177], v197 offset:4096
	ds_read_b128 v[178:181], v197 offset:5120
	ds_read_b128 v[198:201], v197 offset:6144
	ds_read_b128 v[202:205], v197 offset:7168
	global_load_lds_dwordx4 v146, s[20:21]
	s_add_i32 m0, s56, 0xe000
	s_nop 0
	global_load_lds_dwordx4 v148, s[20:21]
	s_waitcnt lgkmcnt(8)
	s_barrier
	s_waitcnt lgkmcnt(7)
	v_mfma_f32_16x16x32_bf16 v[124:127], v[128:131], v[158:161], v[124:127]
	v_mfma_f32_16x16x32_bf16 v[120:123], v[150:153], v[158:161], v[120:123]
	s_waitcnt lgkmcnt(5)
	v_mfma_f32_16x16x32_bf16 v[108:111], v[128:131], v[166:169], v[108:111]
	v_mfma_f32_16x16x32_bf16 v[104:107], v[150:153], v[166:169], v[104:107]
	s_waitcnt lgkmcnt(3)
	v_mfma_f32_16x16x32_bf16 v[92:95], v[128:131], v[174:177], v[92:95]
	v_mfma_f32_16x16x32_bf16 v[88:91], v[150:153], v[174:177], v[88:91]
	s_waitcnt lgkmcnt(1)
	v_mfma_f32_16x16x32_bf16 v[76:79], v[128:131], v[198:201], v[76:79]
	v_mfma_f32_16x16x32_bf16 v[72:75], v[150:153], v[198:201], v[72:75]
	v_mfma_f32_16x16x32_bf16 v[124:127], v[132:135], v[162:165], v[124:127]
	v_mfma_f32_16x16x32_bf16 v[120:123], v[154:157], v[162:165], v[120:123]
	v_mfma_f32_16x16x32_bf16 v[108:111], v[132:135], v[170:173], v[108:111]
	v_mfma_f32_16x16x32_bf16 v[104:107], v[154:157], v[170:173], v[104:107]
	v_mfma_f32_16x16x32_bf16 v[92:95], v[132:135], v[178:181], v[92:95]
	v_mfma_f32_16x16x32_bf16 v[88:91], v[154:157], v[178:181], v[88:91]
	s_waitcnt lgkmcnt(0)
	v_mfma_f32_16x16x32_bf16 v[76:79], v[132:135], v[202:205], v[76:79]
	v_mfma_f32_16x16x32_bf16 v[72:75], v[154:157], v[202:205], v[72:75]
	s_barrier
	s_add_i32 s44, 0, 0x14000
	s_add_i32 s42, s42, s52
	s_add_u32 vcc_lo, s22, s0
	s_addc_u32 vcc_hi, s23, s1
	s_mov_b32 m0, s42
	ds_read_b128 v[206:209], v223
	ds_read_b128 v[210:213], v223 offset:1024
	ds_read_b128 v[214:217], v223 offset:2048
	ds_read_b128 v[218:221], v223 offset:3072
	global_load_lds_dwordx4 v140, s[22:23]
	s_add_i32 m0, s42, 0x2000
	s_nop 0
	global_load_lds_dwordx4 v136, s[22:23]
	s_barrier
	s_waitcnt lgkmcnt(3)
	v_mfma_f32_16x16x32_bf16 v[116:119], v[206:209], v[158:161], v[116:119]
	s_waitcnt lgkmcnt(1)
	v_mfma_f32_16x16x32_bf16 v[112:115], v[214:217], v[158:161], v[112:115]
	v_mfma_f32_16x16x32_bf16 v[100:103], v[206:209], v[166:169], v[100:103]
	v_mfma_f32_16x16x32_bf16 v[96:99], v[214:217], v[166:169], v[96:99]
	v_mfma_f32_16x16x32_bf16 v[84:87], v[206:209], v[174:177], v[84:87]
	v_mfma_f32_16x16x32_bf16 v[80:83], v[214:217], v[174:177], v[80:83]
	v_mfma_f32_16x16x32_bf16 v[68:71], v[206:209], v[198:201], v[68:71]
	v_mfma_f32_16x16x32_bf16 v[64:67], v[214:217], v[198:201], v[64:67]
	v_mfma_f32_16x16x32_bf16 v[116:119], v[210:213], v[162:165], v[116:119]
	s_waitcnt lgkmcnt(0)
	v_mfma_f32_16x16x32_bf16 v[112:115], v[218:221], v[162:165], v[112:115]
	v_mfma_f32_16x16x32_bf16 v[100:103], v[210:213], v[170:173], v[100:103]
	v_mfma_f32_16x16x32_bf16 v[96:99], v[218:221], v[170:173], v[96:99]
	v_mfma_f32_16x16x32_bf16 v[84:87], v[210:213], v[178:181], v[84:87]
	v_mfma_f32_16x16x32_bf16 v[80:83], v[218:221], v[178:181], v[80:83]
	v_mfma_f32_16x16x32_bf16 v[68:71], v[210:213], v[202:205], v[68:71]
	v_mfma_f32_16x16x32_bf16 v[64:67], v[218:221], v[202:205], v[64:67]
	s_mov_b32 m0, s56
	s_add_u32 s100, s28, s0
	s_addc_u32 s101, s29, s1
	s_barrier
	ds_read_b128 v[158:161], v197 offset:16384
	ds_read_b128 v[162:165], v197 offset:17408
	ds_read_b128 v[166:169], v197 offset:18432
	ds_read_b128 v[170:173], v197 offset:19456
	ds_read_b128 v[174:177], v197 offset:20480
	ds_read_b128 v[178:181], v197 offset:21504
	ds_read_b128 v[198:201], v197 offset:22528
	ds_read_b128 v[202:205], v197 offset:23552
	global_load_lds_dwordx4 v142, s[28:29]
	s_mov_b32 m0, s57
	s_nop 0
	global_load_lds_dwordx4 v138, s[28:29]
	s_barrier
	s_waitcnt lgkmcnt(7)
	v_mfma_f32_16x16x32_bf16 v[60:63], v[128:131], v[158:161], v[60:63]
	v_mfma_f32_16x16x32_bf16 v[56:59], v[150:153], v[158:161], v[56:59]
	s_waitcnt lgkmcnt(5)
	v_mfma_f32_16x16x32_bf16 v[44:47], v[128:131], v[166:169], v[44:47]
	v_mfma_f32_16x16x32_bf16 v[40:43], v[150:153], v[166:169], v[40:43]
	s_waitcnt lgkmcnt(3)
	v_mfma_f32_16x16x32_bf16 v[28:31], v[128:131], v[174:177], v[28:31]
	v_mfma_f32_16x16x32_bf16 v[24:27], v[150:153], v[174:177], v[24:27]
	s_waitcnt lgkmcnt(1)
	v_mfma_f32_16x16x32_bf16 v[12:15], v[128:131], v[198:201], v[12:15]
	v_mfma_f32_16x16x32_bf16 v[8:11], v[150:153], v[198:201], v[8:11]
	v_mfma_f32_16x16x32_bf16 v[60:63], v[132:135], v[162:165], v[60:63]
	v_mfma_f32_16x16x32_bf16 v[56:59], v[154:157], v[162:165], v[56:59]
	v_mfma_f32_16x16x32_bf16 v[44:47], v[132:135], v[170:173], v[44:47]
	v_mfma_f32_16x16x32_bf16 v[40:43], v[154:157], v[170:173], v[40:43]
	v_mfma_f32_16x16x32_bf16 v[28:31], v[132:135], v[178:181], v[28:31]
	v_mfma_f32_16x16x32_bf16 v[24:27], v[154:157], v[178:181], v[24:27]
	s_waitcnt lgkmcnt(0)
	v_mfma_f32_16x16x32_bf16 v[12:15], v[132:135], v[202:205], v[12:15]
	v_mfma_f32_16x16x32_bf16 v[8:11], v[154:157], v[202:205], v[8:11]
	s_barrier
; #define PG8_STAGE(bufoff, gbase, voff) do { _Pragma("unroll") for (int _i = 0; _i < 2; ++_i) \
;     __builtin_amdgcn_global_load_lds((const unsigned*)((const char*)(gbase) + (voff)[_i]), (LAS unsigned*)(lds + (bufoff) + ldsw + _i * 8192), 16, 0, 0); } while (0)
; #define PG8_LDA(dst, b, h) do { _Pragma("unroll") for (int m = 0; m < 4; ++m) _Pragma("unroll") for (int k = 0; k < 2; ++k) dst[m][k] = *(const LAS bf16x8*)(lds + PG8_SA(b, h) + aoff + m * 2048 + k * 1024); } while (0)
; #define PG8_LDB(dst, b, h) do { _Pragma("unroll") for (int n = 0; n < 2; ++n) _Pragma("unroll") for (int k = 0; k < 2; ++k) dst[n][k] = *(const LAS bf16x8*)(lds + PG8_SB(b, h) + boff + n * 2048 + k * 1024); } while (0)
; #define PG8_MMA(ai, bj, At, Bt) do { __builtin_amdgcn_s_setprio(1); _Pragma("unroll") for (int m = 0; m < 4; ++m) _Pragma("unroll") for (int n = 0; n < 2; ++n) _Pragma("unroll") for (int k = 0; k < 2; ++k) \
;     acc[ai][bj][m][n] = __builtin_amdgcn_mfma_f32_16x16x32_bf16(Bt[n][k], At[m][k], acc[ai][bj][m][n], 0, 0, 0); __builtin_amdgcn_s_setprio(0); } while (0)
; #define PG8_WAIT_V(n) asm volatile("s_waitcnt vmcnt(" #n ")" ::: "memory")
; #define PG8_WAIT_L(n) asm volatile("s_waitcnt lgkmcnt(" #n ")" ::: "memory")
; #define PG8_BAR __builtin_amdgcn_s_barrier()
; #define PG8_SCHED __builtin_amdgcn_sched_barrier(0)
; template <class Epi, class Sched>
; DI void gemm_phase(LAS unsigned char* lds, const Gemm g, const Sched& S, const Epi& E) {
;     ...
;       PG8_STAGE(PG8_SB(0, 1), b2 + hstep, voffB);
;       PG8_WAIT_V(6); PG8_BAR; PG8_MMA(1, 1, At, B1); PG8_BAR;
;       PG8_LDB(B0, 1, 0); PG8_SCHED; PG8_LDA(At, 1, 0); PG8_STAGE(PG8_SA(0, 1), a2 + hstep, voffA);
;       PG8_WAIT_L(8); PG8_BAR; PG8_WAIT_L(0); PG8_MMA(0, 0, At, B0); PG8_BAR; PG8_SCHED;
;       PG8_LDB(B1, 1, 1); PG8_STAGE(PG8_SB(1, 0), b3, voffB);
;       PG8_BAR; PG8_WAIT_L(0); PG8_MMA(0, 1, At, B1); PG8_BAR;
	s_add_u32 s42, s22, 0x40000
	s_addc_u32 s43, s23, 0
	s_add_i32 s44, s44, s52
	s_mov_b32 m0, s44
	s_nop 0
	global_load_lds_dwordx4 v140, s[42:43]
	s_add_i32 m0, s44, 0x2000
	s_nop 0
	global_load_lds_dwordx4 v136, s[42:43]
	s_waitcnt vmcnt(6)
	s_barrier
	v_mfma_f32_16x16x32_bf16 v[52:55], v[206:209], v[158:161], v[52:55]
	v_mfma_f32_16x16x32_bf16 v[48:51], v[214:217], v[158:161], v[48:51]
	v_mfma_f32_16x16x32_bf16 v[36:39], v[206:209], v[166:169], v[36:39]
	v_mfma_f32_16x16x32_bf16 v[32:35], v[214:217], v[166:169], v[32:35]
	v_mfma_f32_16x16x32_bf16 v[20:23], v[206:209], v[174:177], v[20:23]
	v_mfma_f32_16x16x32_bf16 v[16:19], v[214:217], v[174:177], v[16:19]
	v_mfma_f32_16x16x32_bf16 v[4:7], v[206:209], v[198:201], v[4:7]
	v_mfma_f32_16x16x32_bf16 v[0:3], v[214:217], v[198:201], v[0:3]
	v_mfma_f32_16x16x32_bf16 v[52:55], v[210:213], v[162:165], v[52:55]
	v_mfma_f32_16x16x32_bf16 v[48:51], v[218:221], v[162:165], v[48:51]
	v_mfma_f32_16x16x32_bf16 v[36:39], v[210:213], v[170:173], v[36:39]
	v_mfma_f32_16x16x32_bf16 v[32:35], v[218:221], v[170:173], v[32:35]
	v_mfma_f32_16x16x32_bf16 v[20:23], v[210:213], v[178:181], v[20:23]
	v_mfma_f32_16x16x32_bf16 v[16:19], v[218:221], v[178:181], v[16:19]
	v_mfma_f32_16x16x32_bf16 v[4:7], v[210:213], v[202:205], v[4:7]
	v_mfma_f32_16x16x32_bf16 v[0:3], v[218:221], v[202:205], v[0:3]
	s_add_i32 s42, 0, 0x18000
	s_barrier
	ds_read_b128 v[128:131], v224
	ds_read_b128 v[132:135], v224 offset:1024
	ds_read_b128 v[150:153], v224 offset:2048
	ds_read_b128 v[154:157], v224 offset:3072
	s_add_u32 s28, s28, 0x40000
	s_addc_u32 s29, s29, 0
	s_mov_b32 m0, s58
	ds_read_b128 v[158:161], v197 offset:32768
	ds_read_b128 v[162:165], v197 offset:33792
	ds_read_b128 v[166:169], v197 offset:34816
	ds_read_b128 v[170:173], v197 offset:35840
	ds_read_b128 v[174:177], v197 offset:36864
	ds_read_b128 v[178:181], v197 offset:37888
	ds_read_b128 v[198:201], v197 offset:38912
	ds_read_b128 v[202:205], v197 offset:39936
	global_load_lds_dwordx4 v142, s[28:29]
	s_mov_b32 m0, s59
	s_nop 0
	global_load_lds_dwordx4 v138, s[28:29]
	s_waitcnt lgkmcnt(8)
	s_barrier
	s_waitcnt lgkmcnt(7)
	v_mfma_f32_16x16x32_bf16 v[124:127], v[128:131], v[158:161], v[124:127]
	v_mfma_f32_16x16x32_bf16 v[120:123], v[150:153], v[158:161], v[120:123]
	s_waitcnt lgkmcnt(5)
	v_mfma_f32_16x16x32_bf16 v[108:111], v[128:131], v[166:169], v[108:111]
	v_mfma_f32_16x16x32_bf16 v[104:107], v[150:153], v[166:169], v[104:107]
	s_waitcnt lgkmcnt(3)
	v_mfma_f32_16x16x32_bf16 v[92:95], v[128:131], v[174:177], v[92:95]
	v_mfma_f32_16x16x32_bf16 v[88:91], v[150:153], v[174:177], v[88:91]
	s_waitcnt lgkmcnt(1)
	v_mfma_f32_16x16x32_bf16 v[76:79], v[128:131], v[198:201], v[76:79]
	v_mfma_f32_16x16x32_bf16 v[72:75], v[150:153], v[198:201], v[72:75]
	v_mfma_f32_16x16x32_bf16 v[124:127], v[132:135], v[162:165], v[124:127]
	v_mfma_f32_16x16x32_bf16 v[120:123], v[154:157], v[162:165], v[120:123]
	v_mfma_f32_16x16x32_bf16 v[108:111], v[132:135], v[170:173], v[108:111]
	v_mfma_f32_16x16x32_bf16 v[104:107], v[154:157], v[170:173], v[104:107]
	v_mfma_f32_16x16x32_bf16 v[92:95], v[132:135], v[178:181], v[92:95]
	v_mfma_f32_16x16x32_bf16 v[88:91], v[154:157], v[178:181], v[88:91]
	s_waitcnt lgkmcnt(0)
	v_mfma_f32_16x16x32_bf16 v[76:79], v[132:135], v[202:205], v[76:79]
	v_mfma_f32_16x16x32_bf16 v[72:75], v[154:157], v[202:205], v[72:75]
	s_barrier
	s_add_i32 s28, 0, 0x1c000
	s_add_i32 s29, s42, s52
	s_mov_b32 m0, s29
	ds_read_b128 v[206:209], v225
	ds_read_b128 v[210:213], v225 offset:1024
	ds_read_b128 v[214:217], v225 offset:2048
	ds_read_b128 v[218:221], v225 offset:3072
	global_load_lds_dwordx4 v140, vcc
	s_add_i32 m0, s29, 0x2000
	s_nop 0
	global_load_lds_dwordx4 v136, vcc
	s_barrier
	s_waitcnt lgkmcnt(3)
	v_mfma_f32_16x16x32_bf16 v[116:119], v[206:209], v[158:161], v[116:119]
	s_waitcnt lgkmcnt(1)
	v_mfma_f32_16x16x32_bf16 v[112:115], v[214:217], v[158:161], v[112:115]
	v_mfma_f32_16x16x32_bf16 v[100:103], v[206:209], v[166:169], v[100:103]
	v_mfma_f32_16x16x32_bf16 v[96:99], v[214:217], v[166:169], v[96:99]
	v_mfma_f32_16x16x32_bf16 v[84:87], v[206:209], v[174:177], v[84:87]
	v_mfma_f32_16x16x32_bf16 v[80:83], v[214:217], v[174:177], v[80:83]
	v_mfma_f32_16x16x32_bf16 v[68:71], v[206:209], v[198:201], v[68:71]
	v_mfma_f32_16x16x32_bf16 v[64:67], v[214:217], v[198:201], v[64:67]
	v_mfma_f32_16x16x32_bf16 v[116:119], v[210:213], v[162:165], v[116:119]
	s_waitcnt lgkmcnt(0)
	v_mfma_f32_16x16x32_bf16 v[112:115], v[218:221], v[162:165], v[112:115]
	v_mfma_f32_16x16x32_bf16 v[100:103], v[210:213], v[170:173], v[100:103]
	v_mfma_f32_16x16x32_bf16 v[96:99], v[218:221], v[170:173], v[96:99]
	v_mfma_f32_16x16x32_bf16 v[84:87], v[210:213], v[178:181], v[84:87]
	v_mfma_f32_16x16x32_bf16 v[80:83], v[218:221], v[178:181], v[80:83]
	v_mfma_f32_16x16x32_bf16 v[68:71], v[210:213], v[202:205], v[68:71]
	v_mfma_f32_16x16x32_bf16 v[64:67], v[218:221], v[202:205], v[64:67]
	s_mov_b32 m0, s62
	s_barrier
	ds_read_b128 v[158:161], v197 offset:49152
	ds_read_b128 v[162:165], v197 offset:50176
	ds_read_b128 v[166:169], v197 offset:51200
	ds_read_b128 v[170:173], v197 offset:52224
	ds_read_b128 v[174:177], v197 offset:53248
	ds_read_b128 v[178:181], v197 offset:54272
	ds_read_b128 v[198:201], v197 offset:55296
	ds_read_b128 v[202:205], v197 offset:56320
	global_load_lds_dwordx4 v142, s[100:101]
	s_mov_b32 m0, s63
	s_nop 0
	global_load_lds_dwordx4 v138, s[100:101]
	s_barrier
; #define PG8_STAGE(bufoff, gbase, voff) do { _Pragma("unroll") for (int _i = 0; _i < 2; ++_i) \
;     __builtin_amdgcn_global_load_lds((const unsigned*)((const char*)(gbase) + (voff)[_i]), (LAS unsigned*)(lds + (bufoff) + ldsw + _i * 8192), 16, 0, 0); } while (0)
; #define PG8_LDA(dst, b, h) do { _Pragma("unroll") for (int m = 0; m < 4; ++m) _Pragma("unroll") for (int k = 0; k < 2; ++k) dst[m][k] = *(const LAS bf16x8*)(lds + PG8_SA(b, h) + aoff + m * 2048 + k * 1024); } while (0)
; #define PG8_WAIT_V(n) asm volatile("s_waitcnt vmcnt(" #n ")" ::: "memory")
; #define PG8_WAIT_L(n) asm volatile("s_waitcnt lgkmcnt(" #n ")" ::: "memory")
; #define PG8_BAR __builtin_amdgcn_s_barrier()
; #define PG8_SCHED __builtin_amdgcn_sched_barrier(0)
; template <class Epi, class Sched>
; DI void gemm_phase(LAS unsigned char* lds, const Gemm g, const Sched& S, const Epi& E) {
;     ...
;       PG8_LDA(At, 1, 1); PG8_STAGE(PG8_SA(1, 0), a3, voffA);
;       PG8_BAR; PG8_WAIT_L(0); PG8_MMA(1, 0, At, B0); PG8_BAR; PG8_SCHED;
;       PG8_STAGE(PG8_SB(1, 1), b3 + hstep, voffB);
;       PG8_WAIT_V(6); PG8_BAR; PG8_MMA(1, 1, At, B1); PG8_BAR;
;     }
;   DI void operator()(const f32x4 (&acc)[2][2][4][2], const pg8::Unit& u, int wr, int wc, int fr_, int fq_) const {
;     ...
;             if (EPI == EPI_ABIN) {
;               if (n == 0) {
;                 const int gb = u.pn * 256 + bj * 128 + wc * 32; const int f8 = gb + 8 * fq;
;                 const f32x4 v1 = acc[ai][bj][m][1];
;                 if (gb < 384) st_bf8((u16*)(big + E_CQ) + (size_t)token * 384 + f8, v, v1, rinv);
;                 else if (gb < 640) st_bf8((u16*)(big + E_CKV) + (size_t)token * 256 + (f8 - 384), v, v1, rinv);
;                 else if (gb < 672) {
;                   f32x4 a0 = v, a1 = v1;
;                   rope_perm(a0, a1, fq, t_ & 63, tcos, tsin, token & (S_ - 1));
;                   st_bf8((u16*)(big + E_KPE) + (size_t)token * 32 + 8 * fq, a0, a1, rinv);
;                 }
;                 else if (gb < 1184) st_bf8((u16*)(big + E_QNA) + (size_t)token * 512 + (f8 - 672), v, v1, rinv * (0.125f * LOG2E));
;                 else if (gb < 1696) st_bf8((u16*)(big + E_KNA) + (size_t)token * 512 + (f8 - 1184), v, v1, rinv);
;                 else if (gb < 2208) st_bf8((u16*)(big + E_VNAT) + (size_t)token * 512 + (f8 - 1696), v, v1, rinv);
	s_waitcnt lgkmcnt(7)
	v_mfma_f32_16x16x32_bf16 v[60:63], v[128:131], v[158:161], v[60:63]
	v_mfma_f32_16x16x32_bf16 v[56:59], v[150:153], v[158:161], v[56:59]
	s_waitcnt lgkmcnt(5)
	v_mfma_f32_16x16x32_bf16 v[44:47], v[128:131], v[166:169], v[44:47]
	v_mfma_f32_16x16x32_bf16 v[40:43], v[150:153], v[166:169], v[40:43]
	s_waitcnt lgkmcnt(3)
	v_mfma_f32_16x16x32_bf16 v[28:31], v[128:131], v[174:177], v[28:31]
	v_mfma_f32_16x16x32_bf16 v[24:27], v[150:153], v[174:177], v[24:27]
	s_waitcnt lgkmcnt(1)
	v_mfma_f32_16x16x32_bf16 v[12:15], v[128:131], v[198:201], v[12:15]
	v_mfma_f32_16x16x32_bf16 v[8:11], v[150:153], v[198:201], v[8:11]
	v_mfma_f32_16x16x32_bf16 v[60:63], v[132:135], v[162:165], v[60:63]
	v_mfma_f32_16x16x32_bf16 v[56:59], v[154:157], v[162:165], v[56:59]
	v_mfma_f32_16x16x32_bf16 v[44:47], v[132:135], v[170:173], v[44:47]
	v_mfma_f32_16x16x32_bf16 v[40:43], v[154:157], v[170:173], v[40:43]
	v_mfma_f32_16x16x32_bf16 v[28:31], v[132:135], v[178:181], v[28:31]
	v_mfma_f32_16x16x32_bf16 v[24:27], v[154:157], v[178:181], v[24:27]
	s_waitcnt lgkmcnt(0)
	v_mfma_f32_16x16x32_bf16 v[12:15], v[132:135], v[202:205], v[12:15]
	v_mfma_f32_16x16x32_bf16 v[8:11], v[154:157], v[202:205], v[8:11]
	s_barrier
	s_add_u32 s22, s22, 0x40080
	s_addc_u32 s23, s23, 0
	s_add_i32 s28, s28, s52
	s_mov_b32 m0, s28
	s_nop 0
	global_load_lds_dwordx4 v140, s[22:23]
	s_add_i32 m0, s28, 0x2000
	s_nop 0
	global_load_lds_dwordx4 v136, s[22:23]
	s_waitcnt vmcnt(6)
	s_barrier
	v_mfma_f32_16x16x32_bf16 v[52:55], v[206:209], v[158:161], v[52:55]
	v_mfma_f32_16x16x32_bf16 v[48:51], v[214:217], v[158:161], v[48:51]
	v_mfma_f32_16x16x32_bf16 v[36:39], v[206:209], v[166:169], v[36:39]
	v_mfma_f32_16x16x32_bf16 v[32:35], v[214:217], v[166:169], v[32:35]
	v_mfma_f32_16x16x32_bf16 v[20:23], v[206:209], v[174:177], v[20:23]
	v_mfma_f32_16x16x32_bf16 v[16:19], v[214:217], v[174:177], v[16:19]
	v_mfma_f32_16x16x32_bf16 v[4:7], v[206:209], v[198:201], v[4:7]
	v_mfma_f32_16x16x32_bf16 v[0:3], v[214:217], v[198:201], v[0:3]
	v_mfma_f32_16x16x32_bf16 v[52:55], v[210:213], v[162:165], v[52:55]
	v_mfma_f32_16x16x32_bf16 v[48:51], v[218:221], v[162:165], v[48:51]
	v_mfma_f32_16x16x32_bf16 v[36:39], v[210:213], v[170:173], v[36:39]
	v_mfma_f32_16x16x32_bf16 v[32:35], v[218:221], v[170:173], v[32:35]
	v_mfma_f32_16x16x32_bf16 v[20:23], v[210:213], v[178:181], v[20:23]
	v_mfma_f32_16x16x32_bf16 v[16:19], v[218:221], v[178:181], v[16:19]
	v_mfma_f32_16x16x32_bf16 v[4:7], v[210:213], v[202:205], v[4:7]
	v_mfma_f32_16x16x32_bf16 v[0:3], v[218:221], v[202:205], v[0:3]
	s_add_i32 s41, s41, 2
	s_add_u32 s20, s20, 0x100
	s_addc_u32 s21, s21, 0
	s_add_u32 s39, s39, 0x100
	s_addc_u32 s40, s40, 0
	s_cmp_gt_u32 s41, 13
	s_barrier
	s_cbranch_scc0 .LBB0_689
	v_mov_b32_e32 v128, v182
	s_lshl_b32 s20, s34, 10
	v_bfe_u32 v129, v128, 4, 2
	v_and_or_b32 v201, v128, 15, s60
	s_lshl_b32 s13, s35, 8
	v_lshlrev_b32_e32 v128, 2, v128
	s_movk_i32 s21, 0x80
	s_add_i32 s20, s20, 0
	s_lshl_b32 s15, s36, 8
	v_bitop3_b32 v198, v128, s21, v190 bitop3:0x6c
	v_lshl_add_u32 v128, v201, 2, s20
	s_or_b32 s20, s13, s61
	v_add_u32_e32 v200, 0x20000, v128
	s_cmpk_gt_i32 s20, 0x17f
	ds_read_b32 v156, v200
	s_cselect_b64 s[28:29], -1, 0
	s_cmpk_gt_u32 s13, 0x27f
	s_cselect_b64 s[46:47], -1, 0
	s_cmpk_gt_u32 s20, 0x29f
	s_cselect_b64 s[40:41], -1, 0
	s_cmpk_gt_u32 s20, 0x49f
	v_lshlrev_b32_e32 v144, 3, v129
	v_add_u32_e32 v154, s15, v201
	s_cselect_b64 s[34:35], -1, 0
	s_cmpk_gt_u32 s20, 0x69f
	v_ashrrev_i32_e32 v155, 31, v154
	v_lshlrev_b32_e32 v128, 4, v154
	v_or_b32_e32 v150, s20, v144
	s_cselect_b64 s[22:23], -1, 0
	s_cmpk_lt_u32 s20, 0x8a0
	v_and_b32_e32 v199, 8, v144
	v_cmp_lt_u32_e64 s[92:93], 1, v129
	v_lshlrev_b64 v[164:165], 10, v[154:155]
	s_waitcnt lgkmcnt(0)
	v_mul_f32_e32 v162, 0x3e38aa3b, v156
	v_and_b32_e32 v157, 0xfcf0, v128
	v_lshlrev_b64 v[160:161], 6, v[154:155]
	v_lshlrev_b64 v[158:159], 9, v[154:155]
	s_cselect_b64 s[20:21], -1, 0
	v_mov_b32_e32 v152, v150
	v_mov_b32_e32 v153, v145
	s_mov_b64 s[36:37], -1
	s_and_b64 vcc, exec, s[28:29]
	s_cbranch_vccz .LBB0_714
	s_and_b64 vcc, exec, s[46:47]
	s_cbranch_vccz .LBB0_711
	s_and_b64 vcc, exec, s[40:41]
	s_cbranch_vccz .LBB0_704
	s_and_b64 vcc, exec, s[34:35]
	s_cbranch_vccz .LBB0_701
	s_and_b64 vcc, exec, s[22:23]
	s_cbranch_vccz .LBB0_698
	s_andn2_b64 vcc, exec, s[20:21]
	s_cbranch_vccnz .LBB0_697
	v_lshl_add_u64 v[128:129], s[2:3], 0, v[164:165]
	v_lshl_add_u64 v[132:133], v[152:153], 1, v[128:129]
	v_pk_mul_f32 v[128:129], v[124:125], v[156:157] op_sel_hi:[1,0]
	v_pk_mul_f32 v[130:131], v[126:127], v[156:157] op_sel_hi:[1,0]
	v_cvt_pk_bf16_f32 v128, v128, v129
	v_cvt_pk_bf16_f32 v129, v130, v131
	v_pk_mul_f32 v[130:131], v[120:121], v[156:157] op_sel_hi:[1,0]
	v_pk_mul_f32 v[134:135], v[122:123], v[156:157] op_sel_hi:[1,0]
	v_add_co_u32_e32 v132, vcc, 0x69ff000, v132
	v_cvt_pk_bf16_f32 v130, v130, v131
	v_cvt_pk_bf16_f32 v131, v134, v135
	v_addc_co_u32_e32 v133, vcc, 0, v133, vcc
	global_store_dwordx4 v[132:133], v[128:131], off offset:704

; #define PG8_STAGE(bufoff, gbase, voff) do { _Pragma("unroll") for (int _i = 0; _i < 2; ++_i) \
;     __builtin_amdgcn_global_load_lds((const unsigned*)((const char*)(gbase) + (voff)[_i]), (LAS unsigned*)(lds + (bufoff) + ldsw + _i * 8192), 16, 0, 0); } while (0)
; #define PG8_LDA(dst, b, h) do { _Pragma("unroll") for (int m = 0; m < 4; ++m) _Pragma("unroll") for (int k = 0; k < 2; ++k) dst[m][k] = *(const LAS bf16x8*)(lds + PG8_SA(b, h) + aoff + m * 2048 + k * 1024); } while (0)
; #define PG8_LDB(dst, b, h) do { _Pragma("unroll") for (int n = 0; n < 2; ++n) _Pragma("unroll") for (int k = 0; k < 2; ++k) dst[n][k] = *(const LAS bf16x8*)(lds + PG8_SB(b, h) + boff + n * 2048 + k * 1024); } while (0)
; #define PG8_MMA(ai, bj, At, Bt) do { __builtin_amdgcn_s_setprio(1); _Pragma("unroll") for (int m = 0; m < 4; ++m) _Pragma("unroll") for (int n = 0; n < 2; ++n) _Pragma("unroll") for (int k = 0; k < 2; ++k) \
;     acc[ai][bj][m][n] = __builtin_amdgcn_mfma_f32_16x16x32_bf16(Bt[n][k], At[m][k], acc[ai][bj][m][n], 0, 0, 0); __builtin_amdgcn_s_setprio(0); } while (0)
; #define PG8_WAIT_L(n) asm volatile("s_waitcnt lgkmcnt(" #n ")" ::: "memory")
; #define PG8_BAR __builtin_amdgcn_s_barrier()
; #define PG8_SCHED __builtin_amdgcn_sched_barrier(0)
; template <class Epi, class Sched>
; DI void gemm_phase(LAS unsigned char* lds, const Gemm g, const Sched& S, const Epi& E) {
;     ...
;       const bool last = (t == nt - 2);
;       const char* a1 = cA + (size_t)(t + 1) * kstep;
;       const char* a2 = last ? nA : cA + (size_t)(t + 2) * kstep; const char* b2 = last ? nB : cB + (size_t)(t + 2) * kstep;
;       const char* a3 = a2 + kstep; const char* b3 = b2 + kstep;
;       PG8_LDB(B0, 0, 0); PG8_SCHED; PG8_LDA(At, 0, 0); PG8_STAGE(PG8_SA(1, 1), a1 + hstep, voffA);
;       PG8_WAIT_L(8); PG8_BAR; PG8_WAIT_L(0); PG8_MMA(0, 0, At, B0); PG8_BAR; PG8_SCHED;
;       PG8_LDB(B1, 0, 1); PG8_STAGE(PG8_SB(0, 0), b2, voffB);
;       PG8_BAR; PG8_WAIT_L(0); PG8_MMA(0, 1, At, B1); PG8_BAR;
;       PG8_LDA(At, 0, 1); PG8_STAGE(PG8_SA(0, 0), a2, voffA);
;       PG8_BAR; PG8_WAIT_L(0); PG8_MMA(1, 0, At, B0); PG8_BAR; PG8_SCHED;
.LBB0_1202:
	s_add_u32 s20, s18, 0x100
	s_addc_u32 s21, s19, 0
	s_add_i32 s55, 0, 0x10000
	ds_read_b128 v[140:143], v224
	ds_read_b128 v[146:149], v224 offset:1024
	ds_read_b128 v[150:153], v224 offset:2048
	ds_read_b128 v[154:157], v224 offset:3072
	s_cmp_eq_u32 s54, 2
	s_cselect_b32 s29, s3, s21
	s_cselect_b32 s28, s2, s20
	s_cselect_b32 s23, s5, s53
	s_cselect_b32 s22, s4, s52
	s_add_i32 m0, s38, 0xc000
	ds_read_b128 v[158:161], v163
	ds_read_b128 v[164:167], v163 offset:1024
	ds_read_b128 v[168:171], v163 offset:2048
	ds_read_b128 v[172:175], v163 offset:3072
	ds_read_b128 v[176:179], v163 offset:4096
	ds_read_b128 v[196:199], v163 offset:5120
	ds_read_b128 v[200:203], v163 offset:6144
	ds_read_b128 v[204:207], v163 offset:7168
	global_load_lds_dwordx4 v136, s[18:19]
	s_add_i32 m0, s38, 0xe000
	s_nop 0
	global_load_lds_dwordx4 v138, s[18:19]
	s_waitcnt lgkmcnt(8)
	s_barrier
	s_waitcnt lgkmcnt(7)
	v_mfma_f32_16x16x32_bf16 v[124:127], v[140:143], v[158:161], v[124:127]
	v_mfma_f32_16x16x32_bf16 v[120:123], v[150:153], v[158:161], v[120:123]
	s_waitcnt lgkmcnt(5)
	v_mfma_f32_16x16x32_bf16 v[108:111], v[140:143], v[168:171], v[108:111]
	v_mfma_f32_16x16x32_bf16 v[104:107], v[150:153], v[168:171], v[104:107]
	s_waitcnt lgkmcnt(3)
	v_mfma_f32_16x16x32_bf16 v[92:95], v[140:143], v[176:179], v[92:95]
	v_mfma_f32_16x16x32_bf16 v[88:91], v[150:153], v[176:179], v[88:91]
	s_waitcnt lgkmcnt(1)
	v_mfma_f32_16x16x32_bf16 v[76:79], v[140:143], v[200:203], v[76:79]
	v_mfma_f32_16x16x32_bf16 v[72:75], v[150:153], v[200:203], v[72:75]
	v_mfma_f32_16x16x32_bf16 v[124:127], v[146:149], v[164:167], v[124:127]
	v_mfma_f32_16x16x32_bf16 v[120:123], v[154:157], v[164:167], v[120:123]
	v_mfma_f32_16x16x32_bf16 v[108:111], v[146:149], v[172:175], v[108:111]
	v_mfma_f32_16x16x32_bf16 v[104:107], v[154:157], v[172:175], v[104:107]
	v_mfma_f32_16x16x32_bf16 v[92:95], v[146:149], v[196:199], v[92:95]
	v_mfma_f32_16x16x32_bf16 v[88:91], v[154:157], v[196:199], v[88:91]
	s_waitcnt lgkmcnt(0)
	v_mfma_f32_16x16x32_bf16 v[76:79], v[146:149], v[204:207], v[76:79]
	v_mfma_f32_16x16x32_bf16 v[72:75], v[154:157], v[204:207], v[72:75]
	s_barrier
	s_add_i32 s56, 0, 0x14000
	s_add_i32 s18, s55, s35
	s_add_u32 vcc_lo, s22, s0
	s_addc_u32 vcc_hi, s23, s1
	s_mov_b32 m0, s18
	ds_read_b128 v[208:211], v225
	ds_read_b128 v[212:215], v225 offset:1024
	ds_read_b128 v[216:219], v225 offset:2048
	ds_read_b128 v[220:223], v225 offset:3072
	global_load_lds_dwordx4 v130, s[22:23]
	s_add_i32 m0, s18, 0x2000
	s_nop 0
	global_load_lds_dwordx4 v134, s[22:23]
	s_barrier
	s_waitcnt lgkmcnt(3)
	v_mfma_f32_16x16x32_bf16 v[116:119], v[208:211], v[158:161], v[116:119]
	s_waitcnt lgkmcnt(1)
	v_mfma_f32_16x16x32_bf16 v[112:115], v[216:219], v[158:161], v[112:115]
	v_mfma_f32_16x16x32_bf16 v[100:103], v[208:211], v[168:171], v[100:103]
	v_mfma_f32_16x16x32_bf16 v[96:99], v[216:219], v[168:171], v[96:99]
	v_mfma_f32_16x16x32_bf16 v[84:87], v[208:211], v[176:179], v[84:87]
	v_mfma_f32_16x16x32_bf16 v[80:83], v[216:219], v[176:179], v[80:83]
	v_mfma_f32_16x16x32_bf16 v[68:71], v[208:211], v[200:203], v[68:71]
	v_mfma_f32_16x16x32_bf16 v[64:67], v[216:219], v[200:203], v[64:67]
	v_mfma_f32_16x16x32_bf16 v[116:119], v[212:215], v[164:167], v[116:119]
	s_waitcnt lgkmcnt(0)
	v_mfma_f32_16x16x32_bf16 v[112:115], v[220:223], v[164:167], v[112:115]
	v_mfma_f32_16x16x32_bf16 v[100:103], v[212:215], v[172:175], v[100:103]
	v_mfma_f32_16x16x32_bf16 v[96:99], v[220:223], v[172:175], v[96:99]
	v_mfma_f32_16x16x32_bf16 v[84:87], v[212:215], v[196:199], v[84:87]
	v_mfma_f32_16x16x32_bf16 v[80:83], v[220:223], v[196:199], v[80:83]
	v_mfma_f32_16x16x32_bf16 v[68:71], v[212:215], v[204:207], v[68:71]
	v_mfma_f32_16x16x32_bf16 v[64:67], v[220:223], v[204:207], v[64:67]
	s_mov_b32 m0, s38
	s_add_u32 s100, s28, s0
	s_addc_u32 s101, s29, s1
	s_barrier
	ds_read_b128 v[158:161], v163 offset:16384
	ds_read_b128 v[164:167], v163 offset:17408
	ds_read_b128 v[168:171], v163 offset:18432
	ds_read_b128 v[172:175], v163 offset:19456
	ds_read_b128 v[176:179], v163 offset:20480
	ds_read_b128 v[196:199], v163 offset:21504
	ds_read_b128 v[200:203], v163 offset:22528
	ds_read_b128 v[204:207], v163 offset:23552
	global_load_lds_dwordx4 v128, s[28:29]
	s_mov_b32 m0, s39
	s_nop 0
	global_load_lds_dwordx4 v132, s[28:29]
	s_barrier
	s_waitcnt lgkmcnt(7)
	v_mfma_f32_16x16x32_bf16 v[60:63], v[140:143], v[158:161], v[60:63]
	v_mfma_f32_16x16x32_bf16 v[56:59], v[150:153], v[158:161], v[56:59]
	s_waitcnt lgkmcnt(5)
	v_mfma_f32_16x16x32_bf16 v[44:47], v[140:143], v[168:171], v[44:47]
	v_mfma_f32_16x16x32_bf16 v[40:43], v[150:153], v[168:171], v[40:43]
	s_waitcnt lgkmcnt(3)
	v_mfma_f32_16x16x32_bf16 v[28:31], v[140:143], v[176:179], v[28:31]
	v_mfma_f32_16x16x32_bf16 v[24:27], v[150:153], v[176:179], v[24:27]
	s_waitcnt lgkmcnt(1)
	v_mfma_f32_16x16x32_bf16 v[12:15], v[140:143], v[200:203], v[12:15]
	v_mfma_f32_16x16x32_bf16 v[8:11], v[150:153], v[200:203], v[8:11]
	v_mfma_f32_16x16x32_bf16 v[60:63], v[146:149], v[164:167], v[60:63]
	v_mfma_f32_16x16x32_bf16 v[56:59], v[154:157], v[164:167], v[56:59]
	v_mfma_f32_16x16x32_bf16 v[44:47], v[146:149], v[172:175], v[44:47]
	v_mfma_f32_16x16x32_bf16 v[40:43], v[154:157], v[172:175], v[40:43]
	v_mfma_f32_16x16x32_bf16 v[28:31], v[146:149], v[196:199], v[28:31]
	v_mfma_f32_16x16x32_bf16 v[24:27], v[154:157], v[196:199], v[24:27]
	s_waitcnt lgkmcnt(0)
	v_mfma_f32_16x16x32_bf16 v[12:15], v[146:149], v[204:207], v[12:15]
	v_mfma_f32_16x16x32_bf16 v[8:11], v[154:157], v[204:207], v[8:11]
	s_barrier
; #define PG8_STAGE(bufoff, gbase, voff) do { _Pragma("unroll") for (int _i = 0; _i < 2; ++_i) \
;     __builtin_amdgcn_global_load_lds((const unsigned*)((const char*)(gbase) + (voff)[_i]), (LAS unsigned*)(lds + (bufoff) + ldsw + _i * 8192), 16, 0, 0); } while (0)
; #define PG8_LDA(dst, b, h) do { _Pragma("unroll") for (int m = 0; m < 4; ++m) _Pragma("unroll") for (int k = 0; k < 2; ++k) dst[m][k] = *(const LAS bf16x8*)(lds + PG8_SA(b, h) + aoff + m * 2048 + k * 1024); } while (0)
; #define PG8_LDB(dst, b, h) do { _Pragma("unroll") for (int n = 0; n < 2; ++n) _Pragma("unroll") for (int k = 0; k < 2; ++k) dst[n][k] = *(const LAS bf16x8*)(lds + PG8_SB(b, h) + boff + n * 2048 + k * 1024); } while (0)
; #define PG8_MMA(ai, bj, At, Bt) do { __builtin_amdgcn_s_setprio(1); _Pragma("unroll") for (int m = 0; m < 4; ++m) _Pragma("unroll") for (int n = 0; n < 2; ++n) _Pragma("unroll") for (int k = 0; k < 2; ++k) \
;     acc[ai][bj][m][n] = __builtin_amdgcn_mfma_f32_16x16x32_bf16(Bt[n][k], At[m][k], acc[ai][bj][m][n], 0, 0, 0); __builtin_amdgcn_s_setprio(0); } while (0)
; #define PG8_WAIT_V(n) asm volatile("s_waitcnt vmcnt(" #n ")" ::: "memory")
; #define PG8_WAIT_L(n) asm volatile("s_waitcnt lgkmcnt(" #n ")" ::: "memory")
; #define PG8_BAR __builtin_amdgcn_s_barrier()
; #define PG8_SCHED __builtin_amdgcn_sched_barrier(0)
; template <class Epi, class Sched>
; DI void gemm_phase(LAS unsigned char* lds, const Gemm g, const Sched& S, const Epi& E) {
;     ...
;       PG8_STAGE(PG8_SB(0, 1), b2 + hstep, voffB);
;       PG8_WAIT_V(6); PG8_BAR; PG8_MMA(1, 1, At, B1); PG8_BAR;
;       PG8_LDB(B0, 1, 0); PG8_SCHED; PG8_LDA(At, 1, 0); PG8_STAGE(PG8_SA(0, 1), a2 + hstep, voffA);
;       PG8_WAIT_L(8); PG8_BAR; PG8_WAIT_L(0); PG8_MMA(0, 0, At, B0); PG8_BAR; PG8_SCHED;
;       PG8_LDB(B1, 1, 1); PG8_STAGE(PG8_SB(1, 0), b3, voffB);
;       PG8_BAR; PG8_WAIT_L(0); PG8_MMA(0, 1, At, B1); PG8_BAR;
	s_add_u32 s18, s22, 0x18000
	s_addc_u32 s19, s23, 0
	s_add_i32 s55, s56, s35
	s_mov_b32 m0, s55
	s_nop 0
	global_load_lds_dwordx4 v130, s[18:19]
	s_add_i32 m0, s55, 0x2000
	s_nop 0
	global_load_lds_dwordx4 v134, s[18:19]
	s_waitcnt vmcnt(6)
	s_barrier
	v_mfma_f32_16x16x32_bf16 v[52:55], v[208:211], v[158:161], v[52:55]
	v_mfma_f32_16x16x32_bf16 v[48:51], v[216:219], v[158:161], v[48:51]
	v_mfma_f32_16x16x32_bf16 v[36:39], v[208:211], v[168:171], v[36:39]
	v_mfma_f32_16x16x32_bf16 v[32:35], v[216:219], v[168:171], v[32:35]
	v_mfma_f32_16x16x32_bf16 v[20:23], v[208:211], v[176:179], v[20:23]
	v_mfma_f32_16x16x32_bf16 v[16:19], v[216:219], v[176:179], v[16:19]
	v_mfma_f32_16x16x32_bf16 v[4:7], v[208:211], v[200:203], v[4:7]
	v_mfma_f32_16x16x32_bf16 v[0:3], v[216:219], v[200:203], v[0:3]
	v_mfma_f32_16x16x32_bf16 v[52:55], v[212:215], v[164:167], v[52:55]
	v_mfma_f32_16x16x32_bf16 v[48:51], v[220:223], v[164:167], v[48:51]
	v_mfma_f32_16x16x32_bf16 v[36:39], v[212:215], v[172:175], v[36:39]
	v_mfma_f32_16x16x32_bf16 v[32:35], v[220:223], v[172:175], v[32:35]
	v_mfma_f32_16x16x32_bf16 v[20:23], v[212:215], v[196:199], v[20:23]
	v_mfma_f32_16x16x32_bf16 v[16:19], v[220:223], v[196:199], v[16:19]
	v_mfma_f32_16x16x32_bf16 v[4:7], v[212:215], v[204:207], v[4:7]
	v_mfma_f32_16x16x32_bf16 v[0:3], v[220:223], v[204:207], v[0:3]
	s_add_i32 s55, 0, 0x18000
	s_barrier
	ds_read_b128 v[140:143], v226
	ds_read_b128 v[146:149], v226 offset:1024
	ds_read_b128 v[150:153], v226 offset:2048
	ds_read_b128 v[154:157], v226 offset:3072
	s_add_u32 s18, s28, 0x18000
	s_addc_u32 s19, s29, 0
	s_mov_b32 m0, s40
	ds_read_b128 v[158:161], v163 offset:32768
	ds_read_b128 v[164:167], v163 offset:33792
	ds_read_b128 v[168:171], v163 offset:34816
	ds_read_b128 v[172:175], v163 offset:35840
	ds_read_b128 v[176:179], v163 offset:36864
	ds_read_b128 v[196:199], v163 offset:37888
	ds_read_b128 v[200:203], v163 offset:38912
	ds_read_b128 v[204:207], v163 offset:39936
	global_load_lds_dwordx4 v128, s[18:19]
	s_mov_b32 m0, s41
	s_nop 0
	global_load_lds_dwordx4 v132, s[18:19]
	s_waitcnt lgkmcnt(8)
	s_barrier
	s_waitcnt lgkmcnt(7)
	v_mfma_f32_16x16x32_bf16 v[124:127], v[140:143], v[158:161], v[124:127]
	v_mfma_f32_16x16x32_bf16 v[120:123], v[150:153], v[158:161], v[120:123]
	s_waitcnt lgkmcnt(5)
	v_mfma_f32_16x16x32_bf16 v[108:111], v[140:143], v[168:171], v[108:111]
	v_mfma_f32_16x16x32_bf16 v[104:107], v[150:153], v[168:171], v[104:107]
	s_waitcnt lgkmcnt(3)
	v_mfma_f32_16x16x32_bf16 v[92:95], v[140:143], v[176:179], v[92:95]
	v_mfma_f32_16x16x32_bf16 v[88:91], v[150:153], v[176:179], v[88:91]
	s_waitcnt lgkmcnt(1)
	v_mfma_f32_16x16x32_bf16 v[76:79], v[140:143], v[200:203], v[76:79]
	v_mfma_f32_16x16x32_bf16 v[72:75], v[150:153], v[200:203], v[72:75]
	v_mfma_f32_16x16x32_bf16 v[124:127], v[146:149], v[164:167], v[124:127]
	v_mfma_f32_16x16x32_bf16 v[120:123], v[154:157], v[164:167], v[120:123]
	v_mfma_f32_16x16x32_bf16 v[108:111], v[146:149], v[172:175], v[108:111]
	v_mfma_f32_16x16x32_bf16 v[104:107], v[154:157], v[172:175], v[104:107]
	v_mfma_f32_16x16x32_bf16 v[92:95], v[146:149], v[196:199], v[92:95]
	v_mfma_f32_16x16x32_bf16 v[88:91], v[154:157], v[196:199], v[88:91]
	s_waitcnt lgkmcnt(0)
	v_mfma_f32_16x16x32_bf16 v[76:79], v[146:149], v[204:207], v[76:79]
	v_mfma_f32_16x16x32_bf16 v[72:75], v[154:157], v[204:207], v[72:75]
	s_barrier
	s_add_i32 s28, 0, 0x1c000
	s_add_i32 s18, s55, s35
	s_mov_b32 m0, s18
	ds_read_b128 v[208:211], v227
	ds_read_b128 v[212:215], v227 offset:1024
	ds_read_b128 v[216:219], v227 offset:2048
	ds_read_b128 v[220:223], v227 offset:3072
	global_load_lds_dwordx4 v130, vcc
	s_add_i32 m0, s18, 0x2000
	s_nop 0
	global_load_lds_dwordx4 v134, vcc
	s_barrier
	s_waitcnt lgkmcnt(3)
	v_mfma_f32_16x16x32_bf16 v[116:119], v[208:211], v[158:161], v[116:119]
	s_waitcnt lgkmcnt(1)
	v_mfma_f32_16x16x32_bf16 v[112:115], v[216:219], v[158:161], v[112:115]
	v_mfma_f32_16x16x32_bf16 v[100:103], v[208:211], v[168:171], v[100:103]
	v_mfma_f32_16x16x32_bf16 v[96:99], v[216:219], v[168:171], v[96:99]
	v_mfma_f32_16x16x32_bf16 v[84:87], v[208:211], v[176:179], v[84:87]
	v_mfma_f32_16x16x32_bf16 v[80:83], v[216:219], v[176:179], v[80:83]
	v_mfma_f32_16x16x32_bf16 v[68:71], v[208:211], v[200:203], v[68:71]
	v_mfma_f32_16x16x32_bf16 v[64:67], v[216:219], v[200:203], v[64:67]
	v_mfma_f32_16x16x32_bf16 v[116:119], v[212:215], v[164:167], v[116:119]
	s_waitcnt lgkmcnt(0)
	v_mfma_f32_16x16x32_bf16 v[112:115], v[220:223], v[164:167], v[112:115]
	v_mfma_f32_16x16x32_bf16 v[100:103], v[212:215], v[172:175], v[100:103]
	v_mfma_f32_16x16x32_bf16 v[96:99], v[220:223], v[172:175], v[96:99]
	v_mfma_f32_16x16x32_bf16 v[84:87], v[212:215], v[196:199], v[84:87]
	v_mfma_f32_16x16x32_bf16 v[80:83], v[220:223], v[196:199], v[80:83]
	v_mfma_f32_16x16x32_bf16 v[68:71], v[212:215], v[204:207], v[68:71]
	v_mfma_f32_16x16x32_bf16 v[64:67], v[220:223], v[204:207], v[64:67]
	s_mov_b32 m0, s44
	s_barrier
	ds_read_b128 v[158:161], v163 offset:49152
	ds_read_b128 v[164:167], v163 offset:50176
	ds_read_b128 v[168:171], v163 offset:51200
	ds_read_b128 v[172:175], v163 offset:52224
	ds_read_b128 v[176:179], v163 offset:53248
	ds_read_b128 v[196:199], v163 offset:54272
	ds_read_b128 v[200:203], v163 offset:55296
	ds_read_b128 v[204:207], v163 offset:56320
	global_load_lds_dwordx4 v128, s[100:101]
	s_mov_b32 m0, s45
	s_nop 0
	global_load_lds_dwordx4 v132, s[100:101]
	s_barrier
; #define PG8_STAGE(bufoff, gbase, voff) do { _Pragma("unroll") for (int _i = 0; _i < 2; ++_i) \
;     __builtin_amdgcn_global_load_lds((const unsigned*)((const char*)(gbase) + (voff)[_i]), (LAS unsigned*)(lds + (bufoff) + ldsw + _i * 8192), 16, 0, 0); } while (0)
; #define PG8_LDA(dst, b, h) do { _Pragma("unroll") for (int m = 0; m < 4; ++m) _Pragma("unroll") for (int k = 0; k < 2; ++k) dst[m][k] = *(const LAS bf16x8*)(lds + PG8_SA(b, h) + aoff + m * 2048 + k * 1024); } while (0)
; #define PG8_MMA(ai, bj, At, Bt) do { __builtin_amdgcn_s_setprio(1); _Pragma("unroll") for (int m = 0; m < 4; ++m) _Pragma("unroll") for (int n = 0; n < 2; ++n) _Pragma("unroll") for (int k = 0; k < 2; ++k) \
;     acc[ai][bj][m][n] = __builtin_amdgcn_mfma_f32_16x16x32_bf16(Bt[n][k], At[m][k], acc[ai][bj][m][n], 0, 0, 0); __builtin_amdgcn_s_setprio(0); } while (0)
; #define PG8_WAIT_V(n) asm volatile("s_waitcnt vmcnt(" #n ")" ::: "memory")
; #define PG8_WAIT_L(n) asm volatile("s_waitcnt lgkmcnt(" #n ")" ::: "memory")
; #define PG8_BAR __builtin_amdgcn_s_barrier()
; #define PG8_SCHED __builtin_amdgcn_sched_barrier(0)
; template <class Epi, class Sched>
; DI void gemm_phase(LAS unsigned char* lds, const Gemm g, const Sched& S, const Epi& E) {
;     ...
;       PG8_LDA(At, 1, 1); PG8_STAGE(PG8_SA(1, 0), a3, voffA);
;       PG8_BAR; PG8_WAIT_L(0); PG8_MMA(1, 0, At, B0); PG8_BAR; PG8_SCHED;
;       PG8_STAGE(PG8_SB(1, 1), b3 + hstep, voffB);
;       PG8_WAIT_V(6); PG8_BAR; PG8_MMA(1, 1, At, B1); PG8_BAR;
;     }
; DI void rope_perm(f32x4& a0, f32x4& a1, int fq, int lane, const float* tcos, const float* tsin, int pos) {
;   f32x4 p0, p1;
; #pragma unroll
;   for (int e = 0; e < 4; ++e) { p0[e] = shx(a0[e], 32, lane); p1[e] = shx(a1[e], 32, lane); }
;   const int jb = 8 * (fq & 1);
;   const f32x4 c0 = *(const f32x4*)(tcos + pos * 16 + jb), c1 = *(const f32x4*)(tcos + pos * 16 + jb + 4);
;   const f32x4 s0 = *(const f32x4*)(tsin + pos * 16 + jb), s1 = *(const f32x4*)(tsin + pos * 16 + jb + 4);
;   if (fq < 2) { a0 = a0 * c0 - p0 * s0; a1 = a1 * c1 - p1 * s1; }
;   else        { a0 = a0 * c0 + p0 * s0; a1 = a1 * c1 + p1 * s1; }
; }
	s_waitcnt lgkmcnt(7)
	v_mfma_f32_16x16x32_bf16 v[60:63], v[140:143], v[158:161], v[60:63]
	v_mfma_f32_16x16x32_bf16 v[56:59], v[150:153], v[158:161], v[56:59]
	s_waitcnt lgkmcnt(5)
	v_mfma_f32_16x16x32_bf16 v[44:47], v[140:143], v[168:171], v[44:47]
	v_mfma_f32_16x16x32_bf16 v[40:43], v[150:153], v[168:171], v[40:43]
	s_waitcnt lgkmcnt(3)
	v_mfma_f32_16x16x32_bf16 v[28:31], v[140:143], v[176:179], v[28:31]
	v_mfma_f32_16x16x32_bf16 v[24:27], v[150:153], v[176:179], v[24:27]
	s_waitcnt lgkmcnt(1)
	v_mfma_f32_16x16x32_bf16 v[12:15], v[140:143], v[200:203], v[12:15]
	v_mfma_f32_16x16x32_bf16 v[8:11], v[150:153], v[200:203], v[8:11]
	v_mfma_f32_16x16x32_bf16 v[60:63], v[146:149], v[164:167], v[60:63]
	v_mfma_f32_16x16x32_bf16 v[56:59], v[154:157], v[164:167], v[56:59]
	v_mfma_f32_16x16x32_bf16 v[44:47], v[146:149], v[172:175], v[44:47]
	v_mfma_f32_16x16x32_bf16 v[40:43], v[154:157], v[172:175], v[40:43]
	v_mfma_f32_16x16x32_bf16 v[28:31], v[146:149], v[196:199], v[28:31]
	v_mfma_f32_16x16x32_bf16 v[24:27], v[154:157], v[196:199], v[24:27]
	s_waitcnt lgkmcnt(0)
	v_mfma_f32_16x16x32_bf16 v[12:15], v[146:149], v[204:207], v[12:15]
	v_mfma_f32_16x16x32_bf16 v[8:11], v[154:157], v[204:207], v[8:11]
	s_barrier
	s_add_u32 s18, s22, 0x18080
	s_addc_u32 s19, s23, 0
	s_add_i32 s22, s28, s35
	s_mov_b32 m0, s22
	s_nop 0
	global_load_lds_dwordx4 v130, s[18:19]
	s_add_i32 m0, s22, 0x2000
	s_nop 0
	global_load_lds_dwordx4 v134, s[18:19]
	s_waitcnt vmcnt(6)
	s_barrier
	v_mfma_f32_16x16x32_bf16 v[52:55], v[208:211], v[158:161], v[52:55]
	v_mfma_f32_16x16x32_bf16 v[48:51], v[216:219], v[158:161], v[48:51]
	v_mfma_f32_16x16x32_bf16 v[36:39], v[208:211], v[168:171], v[36:39]
	v_mfma_f32_16x16x32_bf16 v[32:35], v[216:219], v[168:171], v[32:35]
	v_mfma_f32_16x16x32_bf16 v[20:23], v[208:211], v[176:179], v[20:23]
	v_mfma_f32_16x16x32_bf16 v[16:19], v[216:219], v[176:179], v[16:19]
	v_mfma_f32_16x16x32_bf16 v[4:7], v[208:211], v[200:203], v[4:7]
	v_mfma_f32_16x16x32_bf16 v[0:3], v[216:219], v[200:203], v[0:3]
	v_mfma_f32_16x16x32_bf16 v[52:55], v[212:215], v[164:167], v[52:55]
	v_mfma_f32_16x16x32_bf16 v[48:51], v[220:223], v[164:167], v[48:51]
	v_mfma_f32_16x16x32_bf16 v[36:39], v[212:215], v[172:175], v[36:39]
	v_mfma_f32_16x16x32_bf16 v[32:35], v[220:223], v[172:175], v[32:35]
	v_mfma_f32_16x16x32_bf16 v[20:23], v[212:215], v[196:199], v[20:23]
	v_mfma_f32_16x16x32_bf16 v[16:19], v[220:223], v[196:199], v[16:19]
	v_mfma_f32_16x16x32_bf16 v[4:7], v[212:215], v[204:207], v[4:7]
	v_mfma_f32_16x16x32_bf16 v[0:3], v[220:223], v[204:207], v[0:3]
	s_add_i32 s54, s54, 2
	s_add_u32 s52, s52, 0x100
	s_addc_u32 s53, s53, 0
	s_cmp_gt_u32 s54, 3
	s_mov_b64 s[18:19], s[20:21]
	s_barrier
	s_cbranch_scc0 .LBB0_1202
	v_mov_b32_e32 v140, v182
	s_lshl_b32 s19, s51, 10
	s_lshl_b32 s18, s49, 8
	s_or_b32 s18, s18, s43
	v_and_or_b32 v167, v140, 15, s42
	v_lshlrev_b32_e32 v141, 2, v140
	s_movk_i32 s20, 0x80
	s_add_i32 s19, s19, 0
	v_bitop3_b32 v164, v141, s20, v190 bitop3:0x6c
	v_lshl_add_u32 v141, v167, 2, s19
	s_mul_hi_i32 s19, s18, 0x2aaaaaab
	v_add_u32_e32 v166, 0x20000, v141
	s_lshr_b32 s20, s19, 31
	s_lshr_b32 s19, s19, 4
	s_lshl_b32 s50, s50, 8
	ds_read_b32 v144, v166
	s_add_i32 s19, s19, s20
	v_add_u32_e32 v165, s50, v167
	s_mulk_i32 s19, 0x60
	v_bfe_u32 v168, v140, 4, 2
	v_lshrrev_b32_e32 v140, 1, v140
	v_lshlrev_b32_e32 v141, 4, v165
	s_sub_i32 s19, s18, s19
	v_and_b32_e32 v140, 8, v140
	v_and_b32_e32 v141, 0xfcf0, v141
	s_cmp_eq_u32 s19, 64
	v_cmp_lt_u32_e64 s[78:79], 1, v168
	s_cselect_b64 s[20:21], -1, 0
	s_cmp_lg_u32 s19, 64
	v_lshlrev_b32_e32 v142, 2, v141
	v_lshlrev_b32_e32 v140, 2, v140
	s_cbranch_scc1 .LBB0_1209
	v_mov_b32_e32 v143, v145
	v_lshl_add_u64 v[146:147], s[12:13], 0, v[142:143]
	v_mov_b32_e32 v141, v145
	v_lshl_add_u64 v[152:153], s[14:15], 0, v[142:143]
	v_lshl_add_u64 v[146:147], v[146:147], 0, v[140:141]
	v_lshl_add_u64 v[152:153], v[152:153], 0, v[140:141]
	global_load_dwordx4 v[148:151], v[146:147], off
	global_load_dwordx4 v[154:157], v[152:153], off
	global_load_dwordx4 v[170:173], v[152:153], off offset:16
	global_load_dwordx4 v[174:177], v[146:147], off offset:16
	ds_bpermute_b32 v152, v164, v124
	ds_bpermute_b32 v160, v164, v120
	ds_bpermute_b32 v153, v164, v125
	ds_bpermute_b32 v161, v164, v121
	ds_bpermute_b32 v158, v164, v126
	ds_bpermute_b32 v178, v164, v122
	ds_bpermute_b32 v159, v164, v127
	ds_bpermute_b32 v179, v164, v123
	s_waitcnt vmcnt(0) lgkmcnt(0)
	v_pk_mul_f32 v[154:155], v[154:155], v[152:153]
	v_pk_mul_f32 v[146:147], v[126:127], v[150:151]
	v_pk_mul_f32 v[150:151], v[124:125], v[148:149]
	v_pk_mul_f32 v[158:159], v[156:157], v[158:159]
	v_pk_mul_f32 v[148:149], v[170:171], v[160:161]
	v_pk_mul_f32 v[152:153], v[172:173], v[178:179]
	v_pk_mul_f32 v[156:157], v[122:123], v[176:177]
	v_pk_mul_f32 v[160:161], v[120:121], v[174:175]
	s_and_saveexec_b64 s[22:23], s[78:79]
	s_xor_b64 s[22:23], exec, s[22:23]
	v_pk_add_f32 v[126:127], v[146:147], v[158:159]
	v_pk_add_f32 v[124:125], v[150:151], v[154:155]
	v_pk_add_f32 v[122:123], v[156:157], v[152:153]
	v_pk_add_f32 v[120:121], v[160:161], v[148:149]
	s_andn2_saveexec_b64 s[22:23], s[22:23]
	v_sub_f32_e32 v127, v147, v159
	v_sub_f32_e32 v126, v146, v158
	v_sub_f32_e32 v125, v151, v155
	v_sub_f32_e32 v124, v150, v154
	v_sub_f32_e32 v123, v157, v153
	v_sub_f32_e32 v122, v156, v152
	v_sub_f32_e32 v121, v161, v149
	v_sub_f32_e32 v120, v160, v148
	s_or_b64 exec, exec, s[22:23]

; #define PG8_STAGE(bufoff, gbase, voff) do { _Pragma("unroll") for (int _i = 0; _i < 2; ++_i) \
;     __builtin_amdgcn_global_load_lds((const unsigned*)((const char*)(gbase) + (voff)[_i]), (LAS unsigned*)(lds + (bufoff) + ldsw + _i * 8192), 16, 0, 0); } while (0)
; #define PG8_LDA(dst, b, h) do { _Pragma("unroll") for (int m = 0; m < 4; ++m) _Pragma("unroll") for (int k = 0; k < 2; ++k) dst[m][k] = *(const LAS bf16x8*)(lds + PG8_SA(b, h) + aoff + m * 2048 + k * 1024); } while (0)
; #define PG8_LDB(dst, b, h) do { _Pragma("unroll") for (int n = 0; n < 2; ++n) _Pragma("unroll") for (int k = 0; k < 2; ++k) dst[n][k] = *(const LAS bf16x8*)(lds + PG8_SB(b, h) + boff + n * 2048 + k * 1024); } while (0)
; #define PG8_MMA(ai, bj, At, Bt) do { __builtin_amdgcn_s_setprio(1); _Pragma("unroll") for (int m = 0; m < 4; ++m) _Pragma("unroll") for (int n = 0; n < 2; ++n) _Pragma("unroll") for (int k = 0; k < 2; ++k) \
;     acc[ai][bj][m][n] = __builtin_amdgcn_mfma_f32_16x16x32_bf16(Bt[n][k], At[m][k], acc[ai][bj][m][n], 0, 0, 0); __builtin_amdgcn_s_setprio(0); } while (0)
; #define PG8_WAIT_L(n) asm volatile("s_waitcnt lgkmcnt(" #n ")" ::: "memory")
; #define PG8_BAR __builtin_amdgcn_s_barrier()
; #define PG8_SCHED __builtin_amdgcn_sched_barrier(0)
; template <class Epi, class Sched>
; DI void gemm_phase(LAS unsigned char* lds, const Gemm g, const Sched& S, const Epi& E) {
;     ...
;       const bool last = (t == nt - 2);
;       const char* a1 = cA + (size_t)(t + 1) * kstep;
;       const char* a2 = last ? nA : cA + (size_t)(t + 2) * kstep; const char* b2 = last ? nB : cB + (size_t)(t + 2) * kstep;
;       const char* a3 = a2 + kstep; const char* b3 = b2 + kstep;
;       PG8_LDB(B0, 0, 0); PG8_SCHED; PG8_LDA(At, 0, 0); PG8_STAGE(PG8_SA(1, 1), a1 + hstep, voffA);
;       PG8_WAIT_L(8); PG8_BAR; PG8_WAIT_L(0); PG8_MMA(0, 0, At, B0); PG8_BAR; PG8_SCHED;
;       PG8_LDB(B1, 0, 1); PG8_STAGE(PG8_SB(0, 0), b2, voffB);
;       PG8_BAR; PG8_WAIT_L(0); PG8_MMA(0, 1, At, B1); PG8_BAR;
;       PG8_LDA(At, 0, 1); PG8_STAGE(PG8_SA(0, 0), a2, voffA);
;       PG8_BAR; PG8_WAIT_L(0); PG8_MMA(1, 0, At, B0); PG8_BAR; PG8_SCHED;
.LBB0_1346:
	s_add_u32 s48, s28, s40
	s_addc_u32 s49, s29, s41
	s_add_u32 s44, s48, 0x100
	s_addc_u32 s45, s49, 0
	s_and_b64 s[42:43], s[36:37], exec
	s_cselect_b32 s45, s15, s45
	s_cselect_b32 s44, s21, s44
	s_add_u32 s40, s22, s40
	s_addc_u32 s41, s23, s41
	s_add_u32 s40, s40, 0x100
	s_addc_u32 s41, s41, 0
	s_add_i32 s70, 0, 0x10000
	s_and_b64 s[36:37], s[36:37], exec
	s_cselect_b32 s47, s13, s41
	s_cselect_b32 s46, s24, s40
	s_add_u32 s48, s48, 0x10080
	s_addc_u32 s49, s49, 0
	s_add_i32 s74, s70, s51
	s_add_i32 m0, s56, 0xc000
	s_add_i32 s75, s56, 0xe000
	s_add_i32 s73, 0, 0x14000
	s_add_i32 s72, s74, 0x2000
	s_add_u32 s42, s46, 0x10000
	s_addc_u32 s43, s47, 0
	s_add_i32 s69, s73, s51
	ds_read_b128 v[136:139], v220
	ds_read_b128 v[146:149], v220 offset:1024
	ds_read_b128 v[150:153], v220 offset:2048
	ds_read_b128 v[154:157], v220 offset:3072
	s_add_i32 s68, s69, 0x2000
	s_add_i32 s67, 0, 0x18000
	s_add_u32 s40, s44, 0x10000
	s_addc_u32 s41, s45, 0
	s_add_i32 s66, s67, s51
	s_add_i32 s65, 0, 0x1c000
	s_add_i32 s64, s66, 0x2000
	s_add_u32 s36, s46, 0x10080
	s_addc_u32 s37, s47, 0
	s_add_i32 s71, s65, s51
	s_add_i32 s70, s71, 0x2000
	ds_read_b128 v[158:161], v143
	ds_read_b128 v[162:165], v143 offset:1024
	ds_read_b128 v[166:169], v143 offset:2048
	ds_read_b128 v[170:173], v143 offset:3072
	ds_read_b128 v[174:177], v143 offset:4096
	ds_read_b128 v[178:181], v143 offset:5120
	ds_read_b128 v[196:199], v143 offset:6144
	ds_read_b128 v[200:203], v143 offset:7168
	global_load_lds_dwordx4 v128, s[48:49]
	s_mov_b32 m0, s75
	s_nop 0
	global_load_lds_dwordx4 v132, s[48:49]
	s_waitcnt lgkmcnt(8)
	s_barrier
	s_waitcnt lgkmcnt(7)
	v_mfma_f32_16x16x32_bf16 v[124:127], v[136:139], v[158:161], v[124:127]
	v_mfma_f32_16x16x32_bf16 v[120:123], v[150:153], v[158:161], v[120:123]
	s_waitcnt lgkmcnt(5)
	v_mfma_f32_16x16x32_bf16 v[108:111], v[136:139], v[166:169], v[108:111]
	v_mfma_f32_16x16x32_bf16 v[104:107], v[150:153], v[166:169], v[104:107]
	s_waitcnt lgkmcnt(3)
	v_mfma_f32_16x16x32_bf16 v[92:95], v[136:139], v[174:177], v[92:95]
	v_mfma_f32_16x16x32_bf16 v[88:91], v[150:153], v[174:177], v[88:91]
	s_waitcnt lgkmcnt(1)
	v_mfma_f32_16x16x32_bf16 v[76:79], v[136:139], v[196:199], v[76:79]
	v_mfma_f32_16x16x32_bf16 v[72:75], v[150:153], v[196:199], v[72:75]
	v_mfma_f32_16x16x32_bf16 v[124:127], v[146:149], v[162:165], v[124:127]
	v_mfma_f32_16x16x32_bf16 v[120:123], v[154:157], v[162:165], v[120:123]
	v_mfma_f32_16x16x32_bf16 v[108:111], v[146:149], v[170:173], v[108:111]
	v_mfma_f32_16x16x32_bf16 v[104:107], v[154:157], v[170:173], v[104:107]
	v_mfma_f32_16x16x32_bf16 v[92:95], v[146:149], v[178:181], v[92:95]
	v_mfma_f32_16x16x32_bf16 v[88:91], v[154:157], v[178:181], v[88:91]
	s_waitcnt lgkmcnt(0)
	v_mfma_f32_16x16x32_bf16 v[76:79], v[146:149], v[200:203], v[76:79]
	v_mfma_f32_16x16x32_bf16 v[72:75], v[154:157], v[200:203], v[72:75]
	s_barrier
	s_mov_b32 m0, s74
	ds_read_b128 v[204:207], v221
	ds_read_b128 v[208:211], v221 offset:1024
	ds_read_b128 v[212:215], v221 offset:2048
	ds_read_b128 v[216:219], v221 offset:3072
	s_add_u32 vcc_lo, s46, s0
	s_addc_u32 vcc_hi, s47, s1
	global_load_lds_dwordx4 v130, s[46:47]
	s_mov_b32 m0, s72
	s_nop 0
	global_load_lds_dwordx4 v134, s[46:47]
	s_barrier
	s_waitcnt lgkmcnt(3)
	v_mfma_f32_16x16x32_bf16 v[116:119], v[204:207], v[158:161], v[116:119]
	s_waitcnt lgkmcnt(1)
	v_mfma_f32_16x16x32_bf16 v[112:115], v[212:215], v[158:161], v[112:115]
	v_mfma_f32_16x16x32_bf16 v[100:103], v[204:207], v[166:169], v[100:103]
	v_mfma_f32_16x16x32_bf16 v[96:99], v[212:215], v[166:169], v[96:99]
	v_mfma_f32_16x16x32_bf16 v[84:87], v[204:207], v[174:177], v[84:87]
	v_mfma_f32_16x16x32_bf16 v[80:83], v[212:215], v[174:177], v[80:83]
	v_mfma_f32_16x16x32_bf16 v[68:71], v[204:207], v[196:199], v[68:71]
	v_mfma_f32_16x16x32_bf16 v[64:67], v[212:215], v[196:199], v[64:67]
	v_mfma_f32_16x16x32_bf16 v[116:119], v[208:211], v[162:165], v[116:119]
	s_waitcnt lgkmcnt(0)
	v_mfma_f32_16x16x32_bf16 v[112:115], v[216:219], v[162:165], v[112:115]
	v_mfma_f32_16x16x32_bf16 v[100:103], v[208:211], v[170:173], v[100:103]
	v_mfma_f32_16x16x32_bf16 v[96:99], v[216:219], v[170:173], v[96:99]
	v_mfma_f32_16x16x32_bf16 v[84:87], v[208:211], v[178:181], v[84:87]
	v_mfma_f32_16x16x32_bf16 v[80:83], v[216:219], v[178:181], v[80:83]
	v_mfma_f32_16x16x32_bf16 v[68:71], v[208:211], v[200:203], v[68:71]
	v_mfma_f32_16x16x32_bf16 v[64:67], v[216:219], v[200:203], v[64:67]
	s_mov_b32 m0, s56
	s_add_u32 s100, s44, s0
	s_addc_u32 s101, s45, s1
	s_barrier
	ds_read_b128 v[158:161], v143 offset:16384
	ds_read_b128 v[162:165], v143 offset:17408
	ds_read_b128 v[166:169], v143 offset:18432
	ds_read_b128 v[170:173], v143 offset:19456
	ds_read_b128 v[174:177], v143 offset:20480
	ds_read_b128 v[178:181], v143 offset:21504
	ds_read_b128 v[196:199], v143 offset:22528
	ds_read_b128 v[200:203], v143 offset:23552
	global_load_lds_dwordx4 v128, s[44:45]
	s_mov_b32 m0, s57
	s_nop 0
	global_load_lds_dwordx4 v132, s[44:45]
	s_barrier
	s_waitcnt lgkmcnt(7)
	v_mfma_f32_16x16x32_bf16 v[60:63], v[136:139], v[158:161], v[60:63]
	v_mfma_f32_16x16x32_bf16 v[56:59], v[150:153], v[158:161], v[56:59]
	s_waitcnt lgkmcnt(5)
	v_mfma_f32_16x16x32_bf16 v[44:47], v[136:139], v[166:169], v[44:47]
	v_mfma_f32_16x16x32_bf16 v[40:43], v[150:153], v[166:169], v[40:43]
	s_waitcnt lgkmcnt(3)
	v_mfma_f32_16x16x32_bf16 v[28:31], v[136:139], v[174:177], v[28:31]
	v_mfma_f32_16x16x32_bf16 v[24:27], v[150:153], v[174:177], v[24:27]
	s_waitcnt lgkmcnt(1)
	v_mfma_f32_16x16x32_bf16 v[12:15], v[136:139], v[196:199], v[12:15]
	v_mfma_f32_16x16x32_bf16 v[8:11], v[150:153], v[196:199], v[8:11]
	v_mfma_f32_16x16x32_bf16 v[60:63], v[146:149], v[162:165], v[60:63]
	v_mfma_f32_16x16x32_bf16 v[56:59], v[154:157], v[162:165], v[56:59]
	v_mfma_f32_16x16x32_bf16 v[44:47], v[146:149], v[170:173], v[44:47]
	v_mfma_f32_16x16x32_bf16 v[40:43], v[154:157], v[170:173], v[40:43]
	v_mfma_f32_16x16x32_bf16 v[28:31], v[146:149], v[178:181], v[28:31]
	v_mfma_f32_16x16x32_bf16 v[24:27], v[154:157], v[178:181], v[24:27]
	s_waitcnt lgkmcnt(0)
	v_mfma_f32_16x16x32_bf16 v[12:15], v[146:149], v[200:203], v[12:15]
	v_mfma_f32_16x16x32_bf16 v[8:11], v[154:157], v[200:203], v[8:11]
	s_barrier
; #define PG8_STAGE(bufoff, gbase, voff) do { _Pragma("unroll") for (int _i = 0; _i < 2; ++_i) \
;     __builtin_amdgcn_global_load_lds((const unsigned*)((const char*)(gbase) + (voff)[_i]), (LAS unsigned*)(lds + (bufoff) + ldsw + _i * 8192), 16, 0, 0); } while (0)
; #define PG8_LDA(dst, b, h) do { _Pragma("unroll") for (int m = 0; m < 4; ++m) _Pragma("unroll") for (int k = 0; k < 2; ++k) dst[m][k] = *(const LAS bf16x8*)(lds + PG8_SA(b, h) + aoff + m * 2048 + k * 1024); } while (0)
; #define PG8_LDB(dst, b, h) do { _Pragma("unroll") for (int n = 0; n < 2; ++n) _Pragma("unroll") for (int k = 0; k < 2; ++k) dst[n][k] = *(const LAS bf16x8*)(lds + PG8_SB(b, h) + boff + n * 2048 + k * 1024); } while (0)
; #define PG8_MMA(ai, bj, At, Bt) do { __builtin_amdgcn_s_setprio(1); _Pragma("unroll") for (int m = 0; m < 4; ++m) _Pragma("unroll") for (int n = 0; n < 2; ++n) _Pragma("unroll") for (int k = 0; k < 2; ++k) \
;     acc[ai][bj][m][n] = __builtin_amdgcn_mfma_f32_16x16x32_bf16(Bt[n][k], At[m][k], acc[ai][bj][m][n], 0, 0, 0); __builtin_amdgcn_s_setprio(0); } while (0)
; #define PG8_WAIT_V(n) asm volatile("s_waitcnt vmcnt(" #n ")" ::: "memory")
; #define PG8_WAIT_L(n) asm volatile("s_waitcnt lgkmcnt(" #n ")" ::: "memory")
; #define PG8_BAR __builtin_amdgcn_s_barrier()
; #define PG8_SCHED __builtin_amdgcn_sched_barrier(0)
; template <class Epi, class Sched>
; DI void gemm_phase(LAS unsigned char* lds, const Gemm g, const Sched& S, const Epi& E) {
;     ...
;       PG8_STAGE(PG8_SB(0, 1), b2 + hstep, voffB);
;       PG8_WAIT_V(6); PG8_BAR; PG8_MMA(1, 1, At, B1); PG8_BAR;
;       PG8_LDB(B0, 1, 0); PG8_SCHED; PG8_LDA(At, 1, 0); PG8_STAGE(PG8_SA(0, 1), a2 + hstep, voffA);
;       PG8_WAIT_L(8); PG8_BAR; PG8_WAIT_L(0); PG8_MMA(0, 0, At, B0); PG8_BAR; PG8_SCHED;
;       PG8_LDB(B1, 1, 1); PG8_STAGE(PG8_SB(1, 0), b3, voffB);
;       PG8_BAR; PG8_WAIT_L(0); PG8_MMA(0, 1, At, B1); PG8_BAR;
	s_mov_b32 m0, s69
	s_nop 0
	global_load_lds_dwordx4 v130, s[42:43]
	s_mov_b32 m0, s68
	s_nop 0
	global_load_lds_dwordx4 v134, s[42:43]
	s_waitcnt vmcnt(6)
	s_barrier
	v_mfma_f32_16x16x32_bf16 v[52:55], v[204:207], v[158:161], v[52:55]
	v_mfma_f32_16x16x32_bf16 v[48:51], v[212:215], v[158:161], v[48:51]
	v_mfma_f32_16x16x32_bf16 v[36:39], v[204:207], v[166:169], v[36:39]
	v_mfma_f32_16x16x32_bf16 v[32:35], v[212:215], v[166:169], v[32:35]
	v_mfma_f32_16x16x32_bf16 v[20:23], v[204:207], v[174:177], v[20:23]
	v_mfma_f32_16x16x32_bf16 v[16:19], v[212:215], v[174:177], v[16:19]
	v_mfma_f32_16x16x32_bf16 v[4:7], v[204:207], v[196:199], v[4:7]
	v_mfma_f32_16x16x32_bf16 v[0:3], v[212:215], v[196:199], v[0:3]
	v_mfma_f32_16x16x32_bf16 v[52:55], v[208:211], v[162:165], v[52:55]
	v_mfma_f32_16x16x32_bf16 v[48:51], v[216:219], v[162:165], v[48:51]
	v_mfma_f32_16x16x32_bf16 v[36:39], v[208:211], v[170:173], v[36:39]
	v_mfma_f32_16x16x32_bf16 v[32:35], v[216:219], v[170:173], v[32:35]
	v_mfma_f32_16x16x32_bf16 v[20:23], v[208:211], v[178:181], v[20:23]
	v_mfma_f32_16x16x32_bf16 v[16:19], v[216:219], v[178:181], v[16:19]
	v_mfma_f32_16x16x32_bf16 v[4:7], v[208:211], v[200:203], v[4:7]
	v_mfma_f32_16x16x32_bf16 v[0:3], v[216:219], v[200:203], v[0:3]
	s_barrier
	ds_read_b128 v[136:139], v222
	ds_read_b128 v[146:149], v222 offset:1024
	ds_read_b128 v[150:153], v222 offset:2048
	ds_read_b128 v[154:157], v222 offset:3072
	s_mov_b32 m0, s58
	ds_read_b128 v[158:161], v143 offset:32768
	ds_read_b128 v[162:165], v143 offset:33792
	ds_read_b128 v[166:169], v143 offset:34816
	ds_read_b128 v[170:173], v143 offset:35840
	ds_read_b128 v[174:177], v143 offset:36864
	ds_read_b128 v[178:181], v143 offset:37888
	ds_read_b128 v[196:199], v143 offset:38912
	ds_read_b128 v[200:203], v143 offset:39936
	global_load_lds_dwordx4 v128, s[40:41]
	s_mov_b32 m0, s59
	s_nop 0
	global_load_lds_dwordx4 v132, s[40:41]
	s_waitcnt lgkmcnt(8)
	s_barrier
	s_waitcnt lgkmcnt(7)
	v_mfma_f32_16x16x32_bf16 v[124:127], v[136:139], v[158:161], v[124:127]
	v_mfma_f32_16x16x32_bf16 v[120:123], v[150:153], v[158:161], v[120:123]
	s_waitcnt lgkmcnt(5)
	v_mfma_f32_16x16x32_bf16 v[108:111], v[136:139], v[166:169], v[108:111]
	v_mfma_f32_16x16x32_bf16 v[104:107], v[150:153], v[166:169], v[104:107]
	s_waitcnt lgkmcnt(3)
	v_mfma_f32_16x16x32_bf16 v[92:95], v[136:139], v[174:177], v[92:95]
	v_mfma_f32_16x16x32_bf16 v[88:91], v[150:153], v[174:177], v[88:91]
	s_waitcnt lgkmcnt(1)
	v_mfma_f32_16x16x32_bf16 v[76:79], v[136:139], v[196:199], v[76:79]
	v_mfma_f32_16x16x32_bf16 v[72:75], v[150:153], v[196:199], v[72:75]
	v_mfma_f32_16x16x32_bf16 v[124:127], v[146:149], v[162:165], v[124:127]
	v_mfma_f32_16x16x32_bf16 v[120:123], v[154:157], v[162:165], v[120:123]
	v_mfma_f32_16x16x32_bf16 v[108:111], v[146:149], v[170:173], v[108:111]
	v_mfma_f32_16x16x32_bf16 v[104:107], v[154:157], v[170:173], v[104:107]
	v_mfma_f32_16x16x32_bf16 v[92:95], v[146:149], v[178:181], v[92:95]
	v_mfma_f32_16x16x32_bf16 v[88:91], v[154:157], v[178:181], v[88:91]
	s_waitcnt lgkmcnt(0)
	v_mfma_f32_16x16x32_bf16 v[76:79], v[146:149], v[200:203], v[76:79]
	v_mfma_f32_16x16x32_bf16 v[72:75], v[154:157], v[200:203], v[72:75]
	s_barrier
	s_mov_b32 m0, s66
	ds_read_b128 v[204:207], v223
	ds_read_b128 v[208:211], v223 offset:1024
	ds_read_b128 v[212:215], v223 offset:2048
	ds_read_b128 v[216:219], v223 offset:3072
	global_load_lds_dwordx4 v130, vcc
	s_mov_b32 m0, s64
	s_nop 0
	global_load_lds_dwordx4 v134, vcc
	s_barrier
	s_waitcnt lgkmcnt(3)
	v_mfma_f32_16x16x32_bf16 v[116:119], v[204:207], v[158:161], v[116:119]
	s_waitcnt lgkmcnt(1)
	v_mfma_f32_16x16x32_bf16 v[112:115], v[212:215], v[158:161], v[112:115]
	v_mfma_f32_16x16x32_bf16 v[100:103], v[204:207], v[166:169], v[100:103]
	v_mfma_f32_16x16x32_bf16 v[96:99], v[212:215], v[166:169], v[96:99]
	v_mfma_f32_16x16x32_bf16 v[84:87], v[204:207], v[174:177], v[84:87]
	v_mfma_f32_16x16x32_bf16 v[80:83], v[212:215], v[174:177], v[80:83]
	v_mfma_f32_16x16x32_bf16 v[68:71], v[204:207], v[196:199], v[68:71]
	v_mfma_f32_16x16x32_bf16 v[64:67], v[212:215], v[196:199], v[64:67]
	v_mfma_f32_16x16x32_bf16 v[116:119], v[208:211], v[162:165], v[116:119]
	s_waitcnt lgkmcnt(0)
	v_mfma_f32_16x16x32_bf16 v[112:115], v[216:219], v[162:165], v[112:115]
	v_mfma_f32_16x16x32_bf16 v[100:103], v[208:211], v[170:173], v[100:103]
	v_mfma_f32_16x16x32_bf16 v[96:99], v[216:219], v[170:173], v[96:99]
	v_mfma_f32_16x16x32_bf16 v[84:87], v[208:211], v[178:181], v[84:87]
	v_mfma_f32_16x16x32_bf16 v[80:83], v[216:219], v[178:181], v[80:83]
	v_mfma_f32_16x16x32_bf16 v[68:71], v[208:211], v[200:203], v[68:71]
	v_mfma_f32_16x16x32_bf16 v[64:67], v[216:219], v[200:203], v[64:67]
	s_mov_b32 m0, s62
	s_barrier
; #define PG8_STAGE(bufoff, gbase, voff) do { _Pragma("unroll") for (int _i = 0; _i < 2; ++_i) \
;     __builtin_amdgcn_global_load_lds((const unsigned*)((const char*)(gbase) + (voff)[_i]), (LAS unsigned*)(lds + (bufoff) + ldsw + _i * 8192), 16, 0, 0); } while (0)
; #define PG8_LDA(dst, b, h) do { _Pragma("unroll") for (int m = 0; m < 4; ++m) _Pragma("unroll") for (int k = 0; k < 2; ++k) dst[m][k] = *(const LAS bf16x8*)(lds + PG8_SA(b, h) + aoff + m * 2048 + k * 1024); } while (0)
; #define PG8_MMA(ai, bj, At, Bt) do { __builtin_amdgcn_s_setprio(1); _Pragma("unroll") for (int m = 0; m < 4; ++m) _Pragma("unroll") for (int n = 0; n < 2; ++n) _Pragma("unroll") for (int k = 0; k < 2; ++k) \
;     acc[ai][bj][m][n] = __builtin_amdgcn_mfma_f32_16x16x32_bf16(Bt[n][k], At[m][k], acc[ai][bj][m][n], 0, 0, 0); __builtin_amdgcn_s_setprio(0); } while (0)
; #define PG8_WAIT_V(n) asm volatile("s_waitcnt vmcnt(" #n ")" ::: "memory")
; #define PG8_WAIT_L(n) asm volatile("s_waitcnt lgkmcnt(" #n ")" ::: "memory")
; #define PG8_BAR __builtin_amdgcn_s_barrier()
; #define PG8_SCHED __builtin_amdgcn_sched_barrier(0)
; template <class Epi, class Sched>
; DI void gemm_phase(LAS unsigned char* lds, const Gemm g, const Sched& S, const Epi& E) {
;     ...
;       PG8_LDA(At, 1, 1); PG8_STAGE(PG8_SA(1, 0), a3, voffA);
;       PG8_BAR; PG8_WAIT_L(0); PG8_MMA(1, 0, At, B0); PG8_BAR; PG8_SCHED;
;       PG8_STAGE(PG8_SB(1, 1), b3 + hstep, voffB);
;       PG8_WAIT_V(6); PG8_BAR; PG8_MMA(1, 1, At, B1); PG8_BAR;
;     }
;   DI void operator()(const f32x4 (&acc)[2][2][4][2], const pg8::Unit& u, int wr, int wc, int fr_, int fq_) const {
;     ...
;             } else if (EPI == EPI_UKV) {
;               if (n == 0) {
;                 const int gb = u.pn * 256 + bj * 128 + wc * 32;
;                 const int hd = gb >> 7, within = (gb & 127) + 8 * fq;
;                 const f32x4 v1 = acc[ai][bj][m][1];
;                 if (within < 64) st_bf8((u16*)(big + E_KNOPE) + (size_t)token * 512 + hd * 64 + within, v, v1, rinv);
;                 else st_bf8((u16*)(big + E_VMLAT) + (size_t)token * 512 + hd * 64 + (within - 64), v, v1, rinv);
;               }
	ds_read_b128 v[158:161], v143 offset:49152
	ds_read_b128 v[162:165], v143 offset:50176
	ds_read_b128 v[166:169], v143 offset:51200
	ds_read_b128 v[170:173], v143 offset:52224
	ds_read_b128 v[174:177], v143 offset:53248
	ds_read_b128 v[178:181], v143 offset:54272
	ds_read_b128 v[196:199], v143 offset:55296
	ds_read_b128 v[200:203], v143 offset:56320
	global_load_lds_dwordx4 v128, s[100:101]
	s_mov_b32 m0, s63
	s_nop 0
	global_load_lds_dwordx4 v132, s[100:101]
	s_barrier
	s_waitcnt lgkmcnt(7)
	v_mfma_f32_16x16x32_bf16 v[60:63], v[136:139], v[158:161], v[60:63]
	v_mfma_f32_16x16x32_bf16 v[56:59], v[150:153], v[158:161], v[56:59]
	s_waitcnt lgkmcnt(5)
	v_mfma_f32_16x16x32_bf16 v[44:47], v[136:139], v[166:169], v[44:47]
	v_mfma_f32_16x16x32_bf16 v[40:43], v[150:153], v[166:169], v[40:43]
	s_waitcnt lgkmcnt(3)
	v_mfma_f32_16x16x32_bf16 v[28:31], v[136:139], v[174:177], v[28:31]
	v_mfma_f32_16x16x32_bf16 v[24:27], v[150:153], v[174:177], v[24:27]
	s_waitcnt lgkmcnt(1)
	v_mfma_f32_16x16x32_bf16 v[12:15], v[136:139], v[196:199], v[12:15]
	v_mfma_f32_16x16x32_bf16 v[8:11], v[150:153], v[196:199], v[8:11]
	v_mfma_f32_16x16x32_bf16 v[60:63], v[146:149], v[162:165], v[60:63]
	v_mfma_f32_16x16x32_bf16 v[56:59], v[154:157], v[162:165], v[56:59]
	v_mfma_f32_16x16x32_bf16 v[44:47], v[146:149], v[170:173], v[44:47]
	v_mfma_f32_16x16x32_bf16 v[40:43], v[154:157], v[170:173], v[40:43]
	v_mfma_f32_16x16x32_bf16 v[28:31], v[146:149], v[178:181], v[28:31]
	v_mfma_f32_16x16x32_bf16 v[24:27], v[154:157], v[178:181], v[24:27]
	s_waitcnt lgkmcnt(0)
	v_mfma_f32_16x16x32_bf16 v[12:15], v[146:149], v[200:203], v[12:15]
	v_mfma_f32_16x16x32_bf16 v[8:11], v[154:157], v[200:203], v[8:11]
	s_barrier
	s_mov_b32 m0, s71
	s_nop 0
	global_load_lds_dwordx4 v130, s[36:37]
	s_mov_b32 m0, s70
	s_nop 0
	global_load_lds_dwordx4 v134, s[36:37]
	s_waitcnt vmcnt(6)
	s_barrier
	v_mfma_f32_16x16x32_bf16 v[52:55], v[204:207], v[158:161], v[52:55]
	v_mfma_f32_16x16x32_bf16 v[48:51], v[212:215], v[158:161], v[48:51]
	v_mfma_f32_16x16x32_bf16 v[36:39], v[204:207], v[166:169], v[36:39]
	v_mfma_f32_16x16x32_bf16 v[32:35], v[212:215], v[166:169], v[32:35]
	v_mfma_f32_16x16x32_bf16 v[20:23], v[204:207], v[174:177], v[20:23]
	v_mfma_f32_16x16x32_bf16 v[16:19], v[212:215], v[174:177], v[16:19]
	v_mfma_f32_16x16x32_bf16 v[4:7], v[204:207], v[196:199], v[4:7]
	v_mfma_f32_16x16x32_bf16 v[0:3], v[212:215], v[196:199], v[0:3]
	v_mfma_f32_16x16x32_bf16 v[52:55], v[208:211], v[162:165], v[52:55]
	v_mfma_f32_16x16x32_bf16 v[48:51], v[216:219], v[162:165], v[48:51]
	v_mfma_f32_16x16x32_bf16 v[36:39], v[208:211], v[170:173], v[36:39]
	v_mfma_f32_16x16x32_bf16 v[32:35], v[216:219], v[170:173], v[32:35]
	v_mfma_f32_16x16x32_bf16 v[20:23], v[208:211], v[178:181], v[20:23]
	v_mfma_f32_16x16x32_bf16 v[16:19], v[216:219], v[178:181], v[16:19]
	v_mfma_f32_16x16x32_bf16 v[4:7], v[208:211], v[200:203], v[4:7]
	v_mfma_f32_16x16x32_bf16 v[0:3], v[216:219], v[200:203], v[0:3]
	s_andn2_b64 vcc, exec, s[34:35]
	s_mov_b64 s[36:37], -1
	s_mov_b64 s[34:35], 0
	s_mov_b64 s[40:41], 0x100
	s_barrier
	s_cbranch_vccz .LBB0_1346
	v_mov_b32_e32 v136, v182
	s_lshl_b32 s3, s3, 10
	s_add_i32 s3, s3, 0
	v_and_or_b32 v147, v136, 15, s60
	v_lshl_add_u32 v137, v147, 2, s3
	v_add_u32_e32 v146, 0x20000, v137
	ds_read_b32 v138, v146
	s_lshl_b32 s13, s20, 8
	v_lshrrev_b32_e32 v136, 1, v136
	v_and_or_b32 v139, v136, 24, s61
	v_add_u32_e32 v136, s13, v147
	v_ashrrev_i32_e32 v137, 31, v136
	s_waitcnt lgkmcnt(0)
	v_pk_mul_f32 v[124:125], v[124:125], v[138:139] op_sel_hi:[1,0]
	v_pk_mul_f32 v[126:127], v[126:127], v[138:139] op_sel_hi:[1,0]
	v_pk_mul_f32 v[120:121], v[120:121], v[138:139] op_sel_hi:[1,0]
	v_lshlrev_b64 v[140:141], 10, v[136:137]
	s_lshl_b32 s20, s2, 7
	v_cvt_pk_bf16_f32 v124, v124, v125
	v_cvt_pk_bf16_f32 v125, v126, v127
	v_cvt_pk_bf16_f32 v126, v120, v121
	v_pk_mul_f32 v[120:121], v[122:123], v[138:139] op_sel_hi:[1,0]
	s_ashr_i32 s21, s20, 31
	v_cvt_pk_bf16_f32 v127, v120, v121
	v_lshl_add_u64 v[120:121], s[6:7], 0, v[140:141]
	s_mov_b64 s[2:3], -1
	s_and_b64 vcc, exec, s[4:5]
	v_lshl_add_u64 v[120:121], s[20:21], 1, v[120:121]
	v_lshlrev_b32_e32 v144, 1, v139
	s_cbranch_vccz .LBB0_1349
	v_lshl_add_u64 v[122:123], v[120:121], 0, v[144:145]
	v_add_co_u32_e32 v122, vcc, 0xd9ff000, v122
	s_mov_b64 s[2:3], 0
	s_nop 0
	v_addc_co_u32_e32 v123, vcc, 0, v123, vcc
	global_store_dwordx4 v[122:123], v[124:127], off offset:3968

; #define PG8_STAGE(bufoff, gbase, voff) do { _Pragma("unroll") for (int _i = 0; _i < 2; ++_i) \
;     __builtin_amdgcn_global_load_lds((const unsigned*)((const char*)(gbase) + (voff)[_i]), (LAS unsigned*)(lds + (bufoff) + ldsw + _i * 8192), 16, 0, 0); } while (0)
; #define PG8_LDA(dst, b, h) do { _Pragma("unroll") for (int m = 0; m < 4; ++m) _Pragma("unroll") for (int k = 0; k < 2; ++k) dst[m][k] = *(const LAS bf16x8*)(lds + PG8_SA(b, h) + aoff + m * 2048 + k * 1024); } while (0)
; #define PG8_LDB(dst, b, h) do { _Pragma("unroll") for (int n = 0; n < 2; ++n) _Pragma("unroll") for (int k = 0; k < 2; ++k) dst[n][k] = *(const LAS bf16x8*)(lds + PG8_SB(b, h) + boff + n * 2048 + k * 1024); } while (0)
; #define PG8_MMA(ai, bj, At, Bt) do { __builtin_amdgcn_s_setprio(1); _Pragma("unroll") for (int m = 0; m < 4; ++m) _Pragma("unroll") for (int n = 0; n < 2; ++n) _Pragma("unroll") for (int k = 0; k < 2; ++k) \
;     acc[ai][bj][m][n] = __builtin_amdgcn_mfma_f32_16x16x32_bf16(Bt[n][k], At[m][k], acc[ai][bj][m][n], 0, 0, 0); __builtin_amdgcn_s_setprio(0); } while (0)
; #define PG8_WAIT_L(n) asm volatile("s_waitcnt lgkmcnt(" #n ")" ::: "memory")
; #define PG8_BAR __builtin_amdgcn_s_barrier()
; #define PG8_SCHED __builtin_amdgcn_sched_barrier(0)
; template <class Epi, class Sched>
; DI void gemm_phase(LAS unsigned char* lds, const Gemm g, const Sched& S, const Epi& E) {
;     ...
;       const bool last = (t == nt - 2);
;       const char* a1 = cA + (size_t)(t + 1) * kstep;
;       const char* a2 = last ? nA : cA + (size_t)(t + 2) * kstep; const char* b2 = last ? nB : cB + (size_t)(t + 2) * kstep;
;       const char* a3 = a2 + kstep; const char* b3 = b2 + kstep;
;       PG8_LDB(B0, 0, 0); PG8_SCHED; PG8_LDA(At, 0, 0); PG8_STAGE(PG8_SA(1, 1), a1 + hstep, voffA);
;       PG8_WAIT_L(8); PG8_BAR; PG8_WAIT_L(0); PG8_MMA(0, 0, At, B0); PG8_BAR; PG8_SCHED;
;       PG8_LDB(B1, 0, 1); PG8_STAGE(PG8_SB(0, 0), b2, voffB);
;       PG8_BAR; PG8_WAIT_L(0); PG8_MMA(0, 1, At, B1); PG8_BAR;
;       PG8_LDA(At, 0, 1); PG8_STAGE(PG8_SA(0, 0), a2, voffA);
;       PG8_BAR; PG8_WAIT_L(0); PG8_MMA(1, 0, At, B0); PG8_BAR; PG8_SCHED;
.LBB0_1644:
	s_add_u32 s4, s2, 0xfffc0080
	s_addc_u32 s5, s3, -1
	s_add_i32 s55, 0, 0x10000
	ds_read_b128 v[128:131], v224
	ds_read_b128 v[132:135], v224 offset:1024
	ds_read_b128 v[148:151], v224 offset:2048
	ds_read_b128 v[152:155], v224 offset:3072
	s_cmp_eq_u32 s54, 12
	s_cselect_b32 s29, s19, s5
	s_cselect_b32 s28, s35, s4
	s_cselect_b32 s5, s17, s53
	s_cselect_b32 s4, s51, s52
	s_add_i32 m0, s41, 0xc000
	ds_read_b128 v[160:163], v159
	ds_read_b128 v[164:167], v159 offset:1024
	ds_read_b128 v[168:171], v159 offset:2048
	ds_read_b128 v[172:175], v159 offset:3072
	ds_read_b128 v[176:179], v159 offset:4096
	ds_read_b128 v[196:199], v159 offset:5120
	ds_read_b128 v[200:203], v159 offset:6144
	ds_read_b128 v[204:207], v159 offset:7168
	global_load_lds_dwordx4 v142, s[2:3]
	s_add_i32 m0, s41, 0xe000
	s_nop 0
	global_load_lds_dwordx4 v146, s[2:3]
	s_waitcnt lgkmcnt(8)
	s_barrier
	s_waitcnt lgkmcnt(7)
	v_mfma_f32_16x16x32_bf16 v[124:127], v[128:131], v[160:163], v[124:127]
	v_mfma_f32_16x16x32_bf16 v[120:123], v[148:151], v[160:163], v[120:123]
	s_waitcnt lgkmcnt(5)
	v_mfma_f32_16x16x32_bf16 v[108:111], v[128:131], v[168:171], v[108:111]
	v_mfma_f32_16x16x32_bf16 v[104:107], v[148:151], v[168:171], v[104:107]
	s_waitcnt lgkmcnt(3)
	v_mfma_f32_16x16x32_bf16 v[92:95], v[128:131], v[176:179], v[92:95]
	v_mfma_f32_16x16x32_bf16 v[88:91], v[148:151], v[176:179], v[88:91]
	s_waitcnt lgkmcnt(1)
	v_mfma_f32_16x16x32_bf16 v[76:79], v[128:131], v[200:203], v[76:79]
	v_mfma_f32_16x16x32_bf16 v[72:75], v[148:151], v[200:203], v[72:75]
	v_mfma_f32_16x16x32_bf16 v[124:127], v[132:135], v[164:167], v[124:127]
	v_mfma_f32_16x16x32_bf16 v[120:123], v[152:155], v[164:167], v[120:123]
	v_mfma_f32_16x16x32_bf16 v[108:111], v[132:135], v[172:175], v[108:111]
	v_mfma_f32_16x16x32_bf16 v[104:107], v[152:155], v[172:175], v[104:107]
	v_mfma_f32_16x16x32_bf16 v[92:95], v[132:135], v[196:199], v[92:95]
	v_mfma_f32_16x16x32_bf16 v[88:91], v[152:155], v[196:199], v[88:91]
	s_waitcnt lgkmcnt(0)
	v_mfma_f32_16x16x32_bf16 v[76:79], v[132:135], v[204:207], v[76:79]
	v_mfma_f32_16x16x32_bf16 v[72:75], v[152:155], v[204:207], v[72:75]
	s_barrier
	s_add_i32 s58, 0, 0x14000
	s_add_i32 s55, s55, s40
	ds_read_b128 v[208:211], v225
	ds_read_b128 v[212:215], v225 offset:1024
	ds_read_b128 v[216:219], v225 offset:2048
	ds_read_b128 v[220:223], v225 offset:3072
	s_add_u32 vcc_lo, s4, s0
	s_addc_u32 vcc_hi, s5, s1
	s_mov_b32 m0, s55
	s_nop 0
	global_load_lds_dwordx4 v144, s[4:5]
	s_add_i32 m0, s55, 0x2000
	s_nop 0
	global_load_lds_dwordx4 v136, s[4:5]
	s_barrier
	s_waitcnt lgkmcnt(3)
	v_mfma_f32_16x16x32_bf16 v[116:119], v[208:211], v[160:163], v[116:119]
	s_waitcnt lgkmcnt(1)
	v_mfma_f32_16x16x32_bf16 v[112:115], v[216:219], v[160:163], v[112:115]
	v_mfma_f32_16x16x32_bf16 v[100:103], v[208:211], v[168:171], v[100:103]
	v_mfma_f32_16x16x32_bf16 v[96:99], v[216:219], v[168:171], v[96:99]
	v_mfma_f32_16x16x32_bf16 v[84:87], v[208:211], v[176:179], v[84:87]
	v_mfma_f32_16x16x32_bf16 v[80:83], v[216:219], v[176:179], v[80:83]
	v_mfma_f32_16x16x32_bf16 v[68:71], v[208:211], v[200:203], v[68:71]
	v_mfma_f32_16x16x32_bf16 v[64:67], v[216:219], v[200:203], v[64:67]
	v_mfma_f32_16x16x32_bf16 v[116:119], v[212:215], v[164:167], v[116:119]
	s_waitcnt lgkmcnt(0)
	v_mfma_f32_16x16x32_bf16 v[112:115], v[220:223], v[164:167], v[112:115]
	v_mfma_f32_16x16x32_bf16 v[100:103], v[212:215], v[172:175], v[100:103]
	v_mfma_f32_16x16x32_bf16 v[96:99], v[220:223], v[172:175], v[96:99]
	v_mfma_f32_16x16x32_bf16 v[84:87], v[212:215], v[196:199], v[84:87]
	v_mfma_f32_16x16x32_bf16 v[80:83], v[220:223], v[196:199], v[80:83]
	v_mfma_f32_16x16x32_bf16 v[68:71], v[212:215], v[204:207], v[68:71]
	v_mfma_f32_16x16x32_bf16 v[64:67], v[220:223], v[204:207], v[64:67]
	s_mov_b32 m0, s41
	s_add_u32 s100, s28, s0
	s_addc_u32 s101, s29, s1
	s_barrier
	ds_read_b128 v[160:163], v159 offset:16384
	ds_read_b128 v[164:167], v159 offset:17408
	ds_read_b128 v[168:171], v159 offset:18432
	ds_read_b128 v[172:175], v159 offset:19456
	ds_read_b128 v[176:179], v159 offset:20480
	ds_read_b128 v[196:199], v159 offset:21504
	ds_read_b128 v[200:203], v159 offset:22528
	ds_read_b128 v[204:207], v159 offset:23552
	global_load_lds_dwordx4 v140, s[28:29]
	s_mov_b32 m0, s42
	s_nop 0
	global_load_lds_dwordx4 v138, s[28:29]
	s_barrier
	s_waitcnt lgkmcnt(7)
	v_mfma_f32_16x16x32_bf16 v[60:63], v[128:131], v[160:163], v[60:63]
	v_mfma_f32_16x16x32_bf16 v[56:59], v[148:151], v[160:163], v[56:59]
	s_waitcnt lgkmcnt(5)
	v_mfma_f32_16x16x32_bf16 v[44:47], v[128:131], v[168:171], v[44:47]
	v_mfma_f32_16x16x32_bf16 v[40:43], v[148:151], v[168:171], v[40:43]
	s_waitcnt lgkmcnt(3)
	v_mfma_f32_16x16x32_bf16 v[28:31], v[128:131], v[176:179], v[28:31]
	v_mfma_f32_16x16x32_bf16 v[24:27], v[148:151], v[176:179], v[24:27]
	s_waitcnt lgkmcnt(1)
	v_mfma_f32_16x16x32_bf16 v[12:15], v[128:131], v[200:203], v[12:15]
	v_mfma_f32_16x16x32_bf16 v[8:11], v[148:151], v[200:203], v[8:11]
	v_mfma_f32_16x16x32_bf16 v[60:63], v[132:135], v[164:167], v[60:63]
	v_mfma_f32_16x16x32_bf16 v[56:59], v[152:155], v[164:167], v[56:59]
	v_mfma_f32_16x16x32_bf16 v[44:47], v[132:135], v[172:175], v[44:47]
	v_mfma_f32_16x16x32_bf16 v[40:43], v[152:155], v[172:175], v[40:43]
	v_mfma_f32_16x16x32_bf16 v[28:31], v[132:135], v[196:199], v[28:31]
	v_mfma_f32_16x16x32_bf16 v[24:27], v[152:155], v[196:199], v[24:27]
	s_waitcnt lgkmcnt(0)
	v_mfma_f32_16x16x32_bf16 v[12:15], v[132:135], v[204:207], v[12:15]
	v_mfma_f32_16x16x32_bf16 v[8:11], v[152:155], v[204:207], v[8:11]
	s_barrier
; #define PG8_STAGE(bufoff, gbase, voff) do { _Pragma("unroll") for (int _i = 0; _i < 2; ++_i) \
;     __builtin_amdgcn_global_load_lds((const unsigned*)((const char*)(gbase) + (voff)[_i]), (LAS unsigned*)(lds + (bufoff) + ldsw + _i * 8192), 16, 0, 0); } while (0)
; #define PG8_LDA(dst, b, h) do { _Pragma("unroll") for (int m = 0; m < 4; ++m) _Pragma("unroll") for (int k = 0; k < 2; ++k) dst[m][k] = *(const LAS bf16x8*)(lds + PG8_SA(b, h) + aoff + m * 2048 + k * 1024); } while (0)
; #define PG8_LDB(dst, b, h) do { _Pragma("unroll") for (int n = 0; n < 2; ++n) _Pragma("unroll") for (int k = 0; k < 2; ++k) dst[n][k] = *(const LAS bf16x8*)(lds + PG8_SB(b, h) + boff + n * 2048 + k * 1024); } while (0)
; #define PG8_MMA(ai, bj, At, Bt) do { __builtin_amdgcn_s_setprio(1); _Pragma("unroll") for (int m = 0; m < 4; ++m) _Pragma("unroll") for (int n = 0; n < 2; ++n) _Pragma("unroll") for (int k = 0; k < 2; ++k) \
;     acc[ai][bj][m][n] = __builtin_amdgcn_mfma_f32_16x16x32_bf16(Bt[n][k], At[m][k], acc[ai][bj][m][n], 0, 0, 0); __builtin_amdgcn_s_setprio(0); } while (0)
; #define PG8_WAIT_V(n) asm volatile("s_waitcnt vmcnt(" #n ")" ::: "memory")
; #define PG8_WAIT_L(n) asm volatile("s_waitcnt lgkmcnt(" #n ")" ::: "memory")
; #define PG8_BAR __builtin_amdgcn_s_barrier()
; #define PG8_SCHED __builtin_amdgcn_sched_barrier(0)
; template <class Epi, class Sched>
; DI void gemm_phase(LAS unsigned char* lds, const Gemm g, const Sched& S, const Epi& E) {
;     ...
;       PG8_STAGE(PG8_SB(0, 1), b2 + hstep, voffB);
;       PG8_WAIT_V(6); PG8_BAR; PG8_MMA(1, 1, At, B1); PG8_BAR;
;       PG8_LDB(B0, 1, 0); PG8_SCHED; PG8_LDA(At, 1, 0); PG8_STAGE(PG8_SA(0, 1), a2 + hstep, voffA);
;       PG8_WAIT_L(8); PG8_BAR; PG8_WAIT_L(0); PG8_MMA(0, 0, At, B0); PG8_BAR; PG8_SCHED;
;       PG8_LDB(B1, 1, 1); PG8_STAGE(PG8_SB(1, 0), b3, voffB);
;       PG8_BAR; PG8_WAIT_L(0); PG8_MMA(0, 1, At, B1); PG8_BAR;
	s_add_u32 s56, s4, 0x40000
	s_addc_u32 s57, s5, 0
	s_add_i32 s55, s58, s40
	s_mov_b32 m0, s55
	s_nop 0
	global_load_lds_dwordx4 v144, s[56:57]
	s_add_i32 m0, s55, 0x2000
	s_nop 0
	global_load_lds_dwordx4 v136, s[56:57]
	s_waitcnt vmcnt(6)
	s_barrier
	v_mfma_f32_16x16x32_bf16 v[52:55], v[208:211], v[160:163], v[52:55]
	v_mfma_f32_16x16x32_bf16 v[48:51], v[216:219], v[160:163], v[48:51]
	v_mfma_f32_16x16x32_bf16 v[36:39], v[208:211], v[168:171], v[36:39]
	v_mfma_f32_16x16x32_bf16 v[32:35], v[216:219], v[168:171], v[32:35]
	v_mfma_f32_16x16x32_bf16 v[20:23], v[208:211], v[176:179], v[20:23]
	v_mfma_f32_16x16x32_bf16 v[16:19], v[216:219], v[176:179], v[16:19]
	v_mfma_f32_16x16x32_bf16 v[4:7], v[208:211], v[200:203], v[4:7]
	v_mfma_f32_16x16x32_bf16 v[0:3], v[216:219], v[200:203], v[0:3]
	v_mfma_f32_16x16x32_bf16 v[52:55], v[212:215], v[164:167], v[52:55]
	v_mfma_f32_16x16x32_bf16 v[48:51], v[220:223], v[164:167], v[48:51]
	v_mfma_f32_16x16x32_bf16 v[36:39], v[212:215], v[172:175], v[36:39]
	v_mfma_f32_16x16x32_bf16 v[32:35], v[220:223], v[172:175], v[32:35]
	v_mfma_f32_16x16x32_bf16 v[20:23], v[212:215], v[196:199], v[20:23]
	v_mfma_f32_16x16x32_bf16 v[16:19], v[220:223], v[196:199], v[16:19]
	v_mfma_f32_16x16x32_bf16 v[4:7], v[212:215], v[204:207], v[4:7]
	v_mfma_f32_16x16x32_bf16 v[0:3], v[220:223], v[204:207], v[0:3]
	s_add_i32 s55, 0, 0x18000
	s_barrier
	ds_read_b128 v[128:131], v226
	ds_read_b128 v[132:135], v226 offset:1024
	ds_read_b128 v[148:151], v226 offset:2048
	ds_read_b128 v[152:155], v226 offset:3072
	s_add_u32 s28, s28, 0x40000
	s_addc_u32 s29, s29, 0
	s_mov_b32 m0, s43
	ds_read_b128 v[160:163], v159 offset:32768
	ds_read_b128 v[164:167], v159 offset:33792
	ds_read_b128 v[168:171], v159 offset:34816
	ds_read_b128 v[172:175], v159 offset:35840
	ds_read_b128 v[176:179], v159 offset:36864
	ds_read_b128 v[196:199], v159 offset:37888
	ds_read_b128 v[200:203], v159 offset:38912
	ds_read_b128 v[204:207], v159 offset:39936
	global_load_lds_dwordx4 v140, s[28:29]
	s_mov_b32 m0, s44
	s_nop 0
	global_load_lds_dwordx4 v138, s[28:29]
	s_waitcnt lgkmcnt(8)
	s_barrier
	s_waitcnt lgkmcnt(7)
	v_mfma_f32_16x16x32_bf16 v[124:127], v[128:131], v[160:163], v[124:127]
	v_mfma_f32_16x16x32_bf16 v[120:123], v[148:151], v[160:163], v[120:123]
	s_waitcnt lgkmcnt(5)
	v_mfma_f32_16x16x32_bf16 v[108:111], v[128:131], v[168:171], v[108:111]
	v_mfma_f32_16x16x32_bf16 v[104:107], v[148:151], v[168:171], v[104:107]
	s_waitcnt lgkmcnt(3)
	v_mfma_f32_16x16x32_bf16 v[92:95], v[128:131], v[176:179], v[92:95]
	v_mfma_f32_16x16x32_bf16 v[88:91], v[148:151], v[176:179], v[88:91]
	s_waitcnt lgkmcnt(1)
	v_mfma_f32_16x16x32_bf16 v[76:79], v[128:131], v[200:203], v[76:79]
	v_mfma_f32_16x16x32_bf16 v[72:75], v[148:151], v[200:203], v[72:75]
	v_mfma_f32_16x16x32_bf16 v[124:127], v[132:135], v[164:167], v[124:127]
	v_mfma_f32_16x16x32_bf16 v[120:123], v[152:155], v[164:167], v[120:123]
	v_mfma_f32_16x16x32_bf16 v[108:111], v[132:135], v[172:175], v[108:111]
	v_mfma_f32_16x16x32_bf16 v[104:107], v[152:155], v[172:175], v[104:107]
	v_mfma_f32_16x16x32_bf16 v[92:95], v[132:135], v[196:199], v[92:95]
	v_mfma_f32_16x16x32_bf16 v[88:91], v[152:155], v[196:199], v[88:91]
	s_waitcnt lgkmcnt(0)
	v_mfma_f32_16x16x32_bf16 v[76:79], v[132:135], v[204:207], v[76:79]
	v_mfma_f32_16x16x32_bf16 v[72:75], v[152:155], v[204:207], v[72:75]
	s_barrier
	s_add_i32 s28, 0, 0x1c000
	s_add_i32 s29, s55, s40
	s_mov_b32 m0, s29
	ds_read_b128 v[208:211], v227
	ds_read_b128 v[212:215], v227 offset:1024
	ds_read_b128 v[216:219], v227 offset:2048
	ds_read_b128 v[220:223], v227 offset:3072
	global_load_lds_dwordx4 v144, vcc
	s_add_i32 m0, s29, 0x2000
	s_nop 0
	global_load_lds_dwordx4 v136, vcc
	s_barrier
	s_waitcnt lgkmcnt(3)
	v_mfma_f32_16x16x32_bf16 v[116:119], v[208:211], v[160:163], v[116:119]
	s_waitcnt lgkmcnt(1)
	v_mfma_f32_16x16x32_bf16 v[112:115], v[216:219], v[160:163], v[112:115]
	v_mfma_f32_16x16x32_bf16 v[100:103], v[208:211], v[168:171], v[100:103]
	v_mfma_f32_16x16x32_bf16 v[96:99], v[216:219], v[168:171], v[96:99]
	v_mfma_f32_16x16x32_bf16 v[84:87], v[208:211], v[176:179], v[84:87]
	v_mfma_f32_16x16x32_bf16 v[80:83], v[216:219], v[176:179], v[80:83]
	v_mfma_f32_16x16x32_bf16 v[68:71], v[208:211], v[200:203], v[68:71]
	v_mfma_f32_16x16x32_bf16 v[64:67], v[216:219], v[200:203], v[64:67]
	v_mfma_f32_16x16x32_bf16 v[116:119], v[212:215], v[164:167], v[116:119]
	s_waitcnt lgkmcnt(0)
	v_mfma_f32_16x16x32_bf16 v[112:115], v[220:223], v[164:167], v[112:115]
	v_mfma_f32_16x16x32_bf16 v[100:103], v[212:215], v[172:175], v[100:103]
	v_mfma_f32_16x16x32_bf16 v[96:99], v[220:223], v[172:175], v[96:99]
	v_mfma_f32_16x16x32_bf16 v[84:87], v[212:215], v[196:199], v[84:87]
	v_mfma_f32_16x16x32_bf16 v[80:83], v[220:223], v[196:199], v[80:83]
	v_mfma_f32_16x16x32_bf16 v[68:71], v[212:215], v[204:207], v[68:71]
	v_mfma_f32_16x16x32_bf16 v[64:67], v[220:223], v[204:207], v[64:67]
	s_mov_b32 m0, s49
	s_barrier
; DI float bf2f(unsigned v) { return __uint_as_float(v << 16); }
; #define PG8_STAGE(bufoff, gbase, voff) do { _Pragma("unroll") for (int _i = 0; _i < 2; ++_i) \
;     __builtin_amdgcn_global_load_lds((const unsigned*)((const char*)(gbase) + (voff)[_i]), (LAS unsigned*)(lds + (bufoff) + ldsw + _i * 8192), 16, 0, 0); } while (0)
; #define PG8_LDA(dst, b, h) do { _Pragma("unroll") for (int m = 0; m < 4; ++m) _Pragma("unroll") for (int k = 0; k < 2; ++k) dst[m][k] = *(const LAS bf16x8*)(lds + PG8_SA(b, h) + aoff + m * 2048 + k * 1024); } while (0)
; #define PG8_MMA(ai, bj, At, Bt) do { __builtin_amdgcn_s_setprio(1); _Pragma("unroll") for (int m = 0; m < 4; ++m) _Pragma("unroll") for (int n = 0; n < 2; ++n) _Pragma("unroll") for (int k = 0; k < 2; ++k) \
;     acc[ai][bj][m][n] = __builtin_amdgcn_mfma_f32_16x16x32_bf16(Bt[n][k], At[m][k], acc[ai][bj][m][n], 0, 0, 0); __builtin_amdgcn_s_setprio(0); } while (0)
; #define PG8_WAIT_V(n) asm volatile("s_waitcnt vmcnt(" #n ")" ::: "memory")
; #define PG8_WAIT_L(n) asm volatile("s_waitcnt lgkmcnt(" #n ")" ::: "memory")
; #define PG8_BAR __builtin_amdgcn_s_barrier()
; #define PG8_SCHED __builtin_amdgcn_sched_barrier(0)
; template <class Epi, class Sched>
; DI void gemm_phase(LAS unsigned char* lds, const Gemm g, const Sched& S, const Epi& E) {
;     ...
;       PG8_LDA(At, 1, 1); PG8_STAGE(PG8_SA(1, 0), a3, voffA);
;       PG8_BAR; PG8_WAIT_L(0); PG8_MMA(1, 0, At, B0); PG8_BAR; PG8_SCHED;
;       PG8_STAGE(PG8_SB(1, 1), b3 + hstep, voffB);
;       PG8_WAIT_V(6); PG8_BAR; PG8_MMA(1, 1, At, B1); PG8_BAR;
;     }
;   DI void operator()(const f32x4 (&acc)[2][2][4][2], const pg8::Unit& u, int wr, int wc, int fr_, int fq_) const {
;     ...
;               if (n == 0) {
;                 const int f8 = u.pn * 256 + bj * 128 + wc * 32 + 8 * fq;
;                 const f32x4 v1 = acc[ai][bj][m][1];
;                 f32x4 r0, r1;
;                 if (rsrc) {
;                   r0 = *(const f32x4*)(rsrc + (size_t)token * 1024 + f8); r1 = *(const f32x4*)(rsrc + (size_t)token * 1024 + f8 + 4);
;                 } else {
;                   const u32x4 xu = *(const u32x4*)(xr + (size_t)token * 1024 + f8);
;                   r0 = (f32x4){bf2f(xu.x & 0xffffu), bf2f(xu.x >> 16), bf2f(xu.y & 0xffffu), bf2f(xu.y >> 16)};
;                   r1 = (f32x4){bf2f(xu.z & 0xffffu), bf2f(xu.z >> 16), bf2f(xu.w & 0xffffu), bf2f(xu.w >> 16)};
;                 }
	ds_read_b128 v[160:163], v159 offset:49152
	ds_read_b128 v[164:167], v159 offset:50176
	ds_read_b128 v[168:171], v159 offset:51200
	ds_read_b128 v[172:175], v159 offset:52224
	ds_read_b128 v[176:179], v159 offset:53248
	ds_read_b128 v[196:199], v159 offset:54272
	ds_read_b128 v[200:203], v159 offset:55296
	ds_read_b128 v[204:207], v159 offset:56320
	global_load_lds_dwordx4 v140, s[100:101]
	s_mov_b32 m0, s50
	s_nop 0
	global_load_lds_dwordx4 v138, s[100:101]
	s_barrier
	s_waitcnt lgkmcnt(7)
	v_mfma_f32_16x16x32_bf16 v[60:63], v[128:131], v[160:163], v[60:63]
	v_mfma_f32_16x16x32_bf16 v[56:59], v[148:151], v[160:163], v[56:59]
	s_waitcnt lgkmcnt(5)
	v_mfma_f32_16x16x32_bf16 v[44:47], v[128:131], v[168:171], v[44:47]
	v_mfma_f32_16x16x32_bf16 v[40:43], v[148:151], v[168:171], v[40:43]
	s_waitcnt lgkmcnt(3)
	v_mfma_f32_16x16x32_bf16 v[28:31], v[128:131], v[176:179], v[28:31]
	v_mfma_f32_16x16x32_bf16 v[24:27], v[148:151], v[176:179], v[24:27]
	s_waitcnt lgkmcnt(1)
	v_mfma_f32_16x16x32_bf16 v[12:15], v[128:131], v[200:203], v[12:15]
	v_mfma_f32_16x16x32_bf16 v[8:11], v[148:151], v[200:203], v[8:11]
	v_mfma_f32_16x16x32_bf16 v[60:63], v[132:135], v[164:167], v[60:63]
	v_mfma_f32_16x16x32_bf16 v[56:59], v[152:155], v[164:167], v[56:59]
	v_mfma_f32_16x16x32_bf16 v[44:47], v[132:135], v[172:175], v[44:47]
	v_mfma_f32_16x16x32_bf16 v[40:43], v[152:155], v[172:175], v[40:43]
	v_mfma_f32_16x16x32_bf16 v[28:31], v[132:135], v[196:199], v[28:31]
	v_mfma_f32_16x16x32_bf16 v[24:27], v[152:155], v[196:199], v[24:27]
	s_waitcnt lgkmcnt(0)
	v_mfma_f32_16x16x32_bf16 v[12:15], v[132:135], v[204:207], v[12:15]
	v_mfma_f32_16x16x32_bf16 v[8:11], v[152:155], v[204:207], v[8:11]
	s_barrier
	s_add_u32 s4, s4, 0x40080
	s_addc_u32 s5, s5, 0
	s_add_i32 s28, s28, s40
	s_mov_b32 m0, s28
	s_nop 0
	global_load_lds_dwordx4 v144, s[4:5]
	s_add_i32 m0, s28, 0x2000
	s_nop 0
	global_load_lds_dwordx4 v136, s[4:5]
	s_waitcnt vmcnt(6)
	s_barrier
	v_mfma_f32_16x16x32_bf16 v[52:55], v[208:211], v[160:163], v[52:55]
	v_mfma_f32_16x16x32_bf16 v[48:51], v[216:219], v[160:163], v[48:51]
	v_mfma_f32_16x16x32_bf16 v[36:39], v[208:211], v[168:171], v[36:39]
	v_mfma_f32_16x16x32_bf16 v[32:35], v[216:219], v[168:171], v[32:35]
	v_mfma_f32_16x16x32_bf16 v[20:23], v[208:211], v[176:179], v[20:23]
	v_mfma_f32_16x16x32_bf16 v[16:19], v[216:219], v[176:179], v[16:19]
	v_mfma_f32_16x16x32_bf16 v[4:7], v[208:211], v[200:203], v[4:7]
	v_mfma_f32_16x16x32_bf16 v[0:3], v[216:219], v[200:203], v[0:3]
	v_mfma_f32_16x16x32_bf16 v[52:55], v[212:215], v[164:167], v[52:55]
	v_mfma_f32_16x16x32_bf16 v[48:51], v[220:223], v[164:167], v[48:51]
	v_mfma_f32_16x16x32_bf16 v[36:39], v[212:215], v[172:175], v[36:39]
	v_mfma_f32_16x16x32_bf16 v[32:35], v[220:223], v[172:175], v[32:35]
	v_mfma_f32_16x16x32_bf16 v[20:23], v[212:215], v[196:199], v[20:23]
	v_mfma_f32_16x16x32_bf16 v[16:19], v[220:223], v[196:199], v[16:19]
	v_mfma_f32_16x16x32_bf16 v[4:7], v[212:215], v[204:207], v[4:7]
	v_mfma_f32_16x16x32_bf16 v[0:3], v[220:223], v[204:207], v[0:3]
	s_add_i32 s54, s54, 2
	s_add_u32 s2, s2, 0x100
	s_addc_u32 s3, s3, 0
	s_add_u32 s52, s52, 0x100
	s_addc_u32 s53, s53, 0
	s_cmp_gt_u32 s54, 13
	s_barrier
	s_cbranch_scc0 .LBB0_1644
	s_lshl_b32 s2, s34, 8
	v_mov_b32_e32 v161, v182
	s_add_i32 s2, s2, s47
	v_cndmask_b32_e64 v130, 0, 1, s[14:15]
	v_and_or_b32 v150, v161, 15, s2
	s_lshl_b32 s2, s24, 8
	v_bfe_u32 v160, v161, 4, 2
	s_or_b32 s2, s2, s48
	v_ashrrev_i32_e32 v151, 31, v150
	v_lshl_or_b32 v148, v160, 3, s2
	v_lshlrev_b64 v[128:129], 12, v[150:151]
	v_ashrrev_i32_e32 v149, 31, v148
	v_lshl_add_u64 v[128:129], s[6:7], 0, v[128:129]
	v_cmp_ne_u32_e64 s[2:3], 1, v130
	s_andn2_b64 vcc, exec, s[14:15]
	v_lshl_add_u64 v[154:155], v[148:149], 2, v[128:129]
	s_cbranch_vccnz .LBB0_1647
	global_load_dwordx4 v[132:135], v[154:155], off offset:16
	global_load_dwordx4 v[128:131], v[154:155], off
	s_mov_b64 s[4:5], 0
	s_branch .LBB0_1648

; #define PG8_STAGE(bufoff, gbase, voff) do { _Pragma("unroll") for (int _i = 0; _i < 2; ++_i) \
;     __builtin_amdgcn_global_load_lds((const unsigned*)((const char*)(gbase) + (voff)[_i]), (LAS unsigned*)(lds + (bufoff) + ldsw + _i * 8192), 16, 0, 0); } while (0)
; #define PG8_LDA(dst, b, h) do { _Pragma("unroll") for (int m = 0; m < 4; ++m) _Pragma("unroll") for (int k = 0; k < 2; ++k) dst[m][k] = *(const LAS bf16x8*)(lds + PG8_SA(b, h) + aoff + m * 2048 + k * 1024); } while (0)
; #define PG8_LDB(dst, b, h) do { _Pragma("unroll") for (int n = 0; n < 2; ++n) _Pragma("unroll") for (int k = 0; k < 2; ++k) dst[n][k] = *(const LAS bf16x8*)(lds + PG8_SB(b, h) + boff + n * 2048 + k * 1024); } while (0)
; #define PG8_MMA(ai, bj, At, Bt) do { __builtin_amdgcn_s_setprio(1); _Pragma("unroll") for (int m = 0; m < 4; ++m) _Pragma("unroll") for (int n = 0; n < 2; ++n) _Pragma("unroll") for (int k = 0; k < 2; ++k) \
;     acc[ai][bj][m][n] = __builtin_amdgcn_mfma_f32_16x16x32_bf16(Bt[n][k], At[m][k], acc[ai][bj][m][n], 0, 0, 0); __builtin_amdgcn_s_setprio(0); } while (0)
; #define PG8_WAIT_L(n) asm volatile("s_waitcnt lgkmcnt(" #n ")" ::: "memory")
; #define PG8_BAR __builtin_amdgcn_s_barrier()
; #define PG8_SCHED __builtin_amdgcn_sched_barrier(0)
; template <class Epi, class Sched>
; DI void gemm_phase(LAS unsigned char* lds, const Gemm g, const Sched& S, const Epi& E) {
;     ...
;       const bool last = (t == nt - 2);
;       const char* a1 = cA + (size_t)(t + 1) * kstep;
;       const char* a2 = last ? nA : cA + (size_t)(t + 2) * kstep; const char* b2 = last ? nB : cB + (size_t)(t + 2) * kstep;
;       const char* a3 = a2 + kstep; const char* b3 = b2 + kstep;
;       PG8_LDB(B0, 0, 0); PG8_SCHED; PG8_LDA(At, 0, 0); PG8_STAGE(PG8_SA(1, 1), a1 + hstep, voffA);
;       PG8_WAIT_L(8); PG8_BAR; PG8_WAIT_L(0); PG8_MMA(0, 0, At, B0); PG8_BAR; PG8_SCHED;
;       PG8_LDB(B1, 0, 1); PG8_STAGE(PG8_SB(0, 0), b2, voffB);
;       PG8_BAR; PG8_WAIT_L(0); PG8_MMA(0, 1, At, B1); PG8_BAR;
;       PG8_LDA(At, 0, 1); PG8_STAGE(PG8_SA(0, 0), a2, voffA);
;       PG8_BAR; PG8_WAIT_L(0); PG8_MMA(1, 0, At, B0); PG8_BAR; PG8_SCHED;
.LBB0_1829:
	s_add_u32 s16, s14, 0xfffc0080
	s_addc_u32 s17, s15, -1
	s_add_i32 s51, 0, 0x10000
	ds_read_b128 v[146:149], v224
	ds_read_b128 v[150:153], v224 offset:1024
	ds_read_b128 v[154:157], v224 offset:2048
	ds_read_b128 v[158:161], v224 offset:3072
	s_cmp_eq_u32 s50, 12
	s_cselect_b32 s19, s7, s17
	s_cselect_b32 s18, s46, s16
	s_cselect_b32 s17, s5, s49
	s_cselect_b32 s16, s47, s48
	s_add_i32 m0, s29, 0xc000
	ds_read_b128 v[162:165], v143
	ds_read_b128 v[166:169], v143 offset:1024
	ds_read_b128 v[170:173], v143 offset:2048
	ds_read_b128 v[174:177], v143 offset:3072
	ds_read_b128 v[178:181], v143 offset:4096
	ds_read_b128 v[196:199], v143 offset:5120
	ds_read_b128 v[200:203], v143 offset:6144
	ds_read_b128 v[204:207], v143 offset:7168
	global_load_lds_dwordx4 v136, s[14:15]
	s_add_i32 m0, s29, 0xe000
	s_nop 0
	global_load_lds_dwordx4 v138, s[14:15]
	s_waitcnt lgkmcnt(8)
	s_barrier
	s_waitcnt lgkmcnt(7)
	v_mfma_f32_16x16x32_bf16 v[124:127], v[146:149], v[162:165], v[124:127]
	v_mfma_f32_16x16x32_bf16 v[120:123], v[154:157], v[162:165], v[120:123]
	s_waitcnt lgkmcnt(5)
	v_mfma_f32_16x16x32_bf16 v[112:115], v[146:149], v[170:173], v[112:115]
	v_mfma_f32_16x16x32_bf16 v[104:107], v[154:157], v[170:173], v[104:107]
	s_waitcnt lgkmcnt(3)
	v_mfma_f32_16x16x32_bf16 v[92:95], v[146:149], v[178:181], v[92:95]
	v_mfma_f32_16x16x32_bf16 v[88:91], v[154:157], v[178:181], v[88:91]
	s_waitcnt lgkmcnt(1)
	v_mfma_f32_16x16x32_bf16 v[80:83], v[146:149], v[200:203], v[80:83]
	v_mfma_f32_16x16x32_bf16 v[72:75], v[154:157], v[200:203], v[72:75]
	v_mfma_f32_16x16x32_bf16 v[124:127], v[150:153], v[166:169], v[124:127]
	v_mfma_f32_16x16x32_bf16 v[120:123], v[158:161], v[166:169], v[120:123]
	v_mfma_f32_16x16x32_bf16 v[112:115], v[150:153], v[174:177], v[112:115]
	v_mfma_f32_16x16x32_bf16 v[104:107], v[158:161], v[174:177], v[104:107]
	v_mfma_f32_16x16x32_bf16 v[92:95], v[150:153], v[196:199], v[92:95]
	v_mfma_f32_16x16x32_bf16 v[88:91], v[158:161], v[196:199], v[88:91]
	s_waitcnt lgkmcnt(0)
	v_mfma_f32_16x16x32_bf16 v[80:83], v[150:153], v[204:207], v[80:83]
	v_mfma_f32_16x16x32_bf16 v[72:75], v[158:161], v[204:207], v[72:75]
	s_barrier
	s_add_i32 s54, 0, 0x14000
	s_add_i32 s51, s51, s20
	ds_read_b128 v[208:211], v225
	ds_read_b128 v[212:215], v225 offset:1024
	ds_read_b128 v[216:219], v225 offset:2048
	ds_read_b128 v[220:223], v225 offset:3072
	s_add_u32 vcc_lo, s16, s0
	s_addc_u32 vcc_hi, s17, s1
	s_mov_b32 m0, s51
	s_nop 0
	global_load_lds_dwordx4 v132, s[16:17]
	s_add_i32 m0, s51, 0x2000
	s_nop 0
	global_load_lds_dwordx4 v128, s[16:17]
	s_barrier
	s_waitcnt lgkmcnt(3)
	v_mfma_f32_16x16x32_bf16 v[116:119], v[208:211], v[162:165], v[116:119]
	s_waitcnt lgkmcnt(1)
	v_mfma_f32_16x16x32_bf16 v[108:111], v[216:219], v[162:165], v[108:111]
	v_mfma_f32_16x16x32_bf16 v[100:103], v[208:211], v[170:173], v[100:103]
	v_mfma_f32_16x16x32_bf16 v[96:99], v[216:219], v[170:173], v[96:99]
	v_mfma_f32_16x16x32_bf16 v[84:87], v[208:211], v[178:181], v[84:87]
	v_mfma_f32_16x16x32_bf16 v[76:79], v[216:219], v[178:181], v[76:79]
	v_mfma_f32_16x16x32_bf16 v[68:71], v[208:211], v[200:203], v[68:71]
	v_mfma_f32_16x16x32_bf16 v[64:67], v[216:219], v[200:203], v[64:67]
	v_mfma_f32_16x16x32_bf16 v[116:119], v[212:215], v[166:169], v[116:119]
	s_waitcnt lgkmcnt(0)
	v_mfma_f32_16x16x32_bf16 v[108:111], v[220:223], v[166:169], v[108:111]
	v_mfma_f32_16x16x32_bf16 v[100:103], v[212:215], v[174:177], v[100:103]
	v_mfma_f32_16x16x32_bf16 v[96:99], v[220:223], v[174:177], v[96:99]
	v_mfma_f32_16x16x32_bf16 v[84:87], v[212:215], v[196:199], v[84:87]
	v_mfma_f32_16x16x32_bf16 v[76:79], v[220:223], v[196:199], v[76:79]
	v_mfma_f32_16x16x32_bf16 v[68:71], v[212:215], v[204:207], v[68:71]
	v_mfma_f32_16x16x32_bf16 v[64:67], v[220:223], v[204:207], v[64:67]
	s_mov_b32 m0, s29
	s_add_u32 s100, s18, s0
	s_addc_u32 s101, s19, s1
	s_barrier
	ds_read_b128 v[162:165], v143 offset:16384
	ds_read_b128 v[166:169], v143 offset:17408
	ds_read_b128 v[170:173], v143 offset:18432
	ds_read_b128 v[174:177], v143 offset:19456
	ds_read_b128 v[178:181], v143 offset:20480
	ds_read_b128 v[196:199], v143 offset:21504
	ds_read_b128 v[200:203], v143 offset:22528
	ds_read_b128 v[204:207], v143 offset:23552
	global_load_lds_dwordx4 v134, s[18:19]
	s_mov_b32 m0, s34
	s_nop 0
	global_load_lds_dwordx4 v130, s[18:19]
	s_barrier
	s_waitcnt lgkmcnt(7)
	v_mfma_f32_16x16x32_bf16 v[60:63], v[146:149], v[162:165], v[60:63]
	v_mfma_f32_16x16x32_bf16 v[56:59], v[154:157], v[162:165], v[56:59]
	s_waitcnt lgkmcnt(5)
	v_mfma_f32_16x16x32_bf16 v[48:51], v[146:149], v[170:173], v[48:51]
	v_mfma_f32_16x16x32_bf16 v[40:43], v[154:157], v[170:173], v[40:43]
	s_waitcnt lgkmcnt(3)
	v_mfma_f32_16x16x32_bf16 v[28:31], v[146:149], v[178:181], v[28:31]
	v_mfma_f32_16x16x32_bf16 v[24:27], v[154:157], v[178:181], v[24:27]
	s_waitcnt lgkmcnt(1)
	v_mfma_f32_16x16x32_bf16 v[16:19], v[146:149], v[200:203], v[16:19]
	v_mfma_f32_16x16x32_bf16 v[8:11], v[154:157], v[200:203], v[8:11]
	v_mfma_f32_16x16x32_bf16 v[60:63], v[150:153], v[166:169], v[60:63]
	v_mfma_f32_16x16x32_bf16 v[56:59], v[158:161], v[166:169], v[56:59]
	v_mfma_f32_16x16x32_bf16 v[48:51], v[150:153], v[174:177], v[48:51]
	v_mfma_f32_16x16x32_bf16 v[40:43], v[158:161], v[174:177], v[40:43]
	v_mfma_f32_16x16x32_bf16 v[28:31], v[150:153], v[196:199], v[28:31]
	v_mfma_f32_16x16x32_bf16 v[24:27], v[158:161], v[196:199], v[24:27]
	s_waitcnt lgkmcnt(0)
	v_mfma_f32_16x16x32_bf16 v[16:19], v[150:153], v[204:207], v[16:19]
	v_mfma_f32_16x16x32_bf16 v[8:11], v[158:161], v[204:207], v[8:11]
	s_barrier
; #define PG8_STAGE(bufoff, gbase, voff) do { _Pragma("unroll") for (int _i = 0; _i < 2; ++_i) \
;     __builtin_amdgcn_global_load_lds((const unsigned*)((const char*)(gbase) + (voff)[_i]), (LAS unsigned*)(lds + (bufoff) + ldsw + _i * 8192), 16, 0, 0); } while (0)
; #define PG8_LDA(dst, b, h) do { _Pragma("unroll") for (int m = 0; m < 4; ++m) _Pragma("unroll") for (int k = 0; k < 2; ++k) dst[m][k] = *(const LAS bf16x8*)(lds + PG8_SA(b, h) + aoff + m * 2048 + k * 1024); } while (0)
; #define PG8_LDB(dst, b, h) do { _Pragma("unroll") for (int n = 0; n < 2; ++n) _Pragma("unroll") for (int k = 0; k < 2; ++k) dst[n][k] = *(const LAS bf16x8*)(lds + PG8_SB(b, h) + boff + n * 2048 + k * 1024); } while (0)
; #define PG8_MMA(ai, bj, At, Bt) do { __builtin_amdgcn_s_setprio(1); _Pragma("unroll") for (int m = 0; m < 4; ++m) _Pragma("unroll") for (int n = 0; n < 2; ++n) _Pragma("unroll") for (int k = 0; k < 2; ++k) \
;     acc[ai][bj][m][n] = __builtin_amdgcn_mfma_f32_16x16x32_bf16(Bt[n][k], At[m][k], acc[ai][bj][m][n], 0, 0, 0); __builtin_amdgcn_s_setprio(0); } while (0)
; #define PG8_WAIT_V(n) asm volatile("s_waitcnt vmcnt(" #n ")" ::: "memory")
; #define PG8_WAIT_L(n) asm volatile("s_waitcnt lgkmcnt(" #n ")" ::: "memory")
; #define PG8_BAR __builtin_amdgcn_s_barrier()
; #define PG8_SCHED __builtin_amdgcn_sched_barrier(0)
; template <class Epi, class Sched>
; DI void gemm_phase(LAS unsigned char* lds, const Gemm g, const Sched& S, const Epi& E) {
;     ...
;       PG8_STAGE(PG8_SB(0, 1), b2 + hstep, voffB);
;       PG8_WAIT_V(6); PG8_BAR; PG8_MMA(1, 1, At, B1); PG8_BAR;
;       PG8_LDB(B0, 1, 0); PG8_SCHED; PG8_LDA(At, 1, 0); PG8_STAGE(PG8_SA(0, 1), a2 + hstep, voffA);
;       PG8_WAIT_L(8); PG8_BAR; PG8_WAIT_L(0); PG8_MMA(0, 0, At, B0); PG8_BAR; PG8_SCHED;
;       PG8_LDB(B1, 1, 1); PG8_STAGE(PG8_SB(1, 0), b3, voffB);
;       PG8_BAR; PG8_WAIT_L(0); PG8_MMA(0, 1, At, B1); PG8_BAR;
	s_add_u32 s52, s16, 0x40000
	s_addc_u32 s53, s17, 0
	s_add_i32 s51, s54, s20
	s_mov_b32 m0, s51
	s_nop 0
	global_load_lds_dwordx4 v132, s[52:53]
	s_add_i32 m0, s51, 0x2000
	s_nop 0
	global_load_lds_dwordx4 v128, s[52:53]
	s_waitcnt vmcnt(6)
	s_barrier
	v_mfma_f32_16x16x32_bf16 v[52:55], v[208:211], v[162:165], v[52:55]
	v_mfma_f32_16x16x32_bf16 v[44:47], v[216:219], v[162:165], v[44:47]
	v_mfma_f32_16x16x32_bf16 v[36:39], v[208:211], v[170:173], v[36:39]
	v_mfma_f32_16x16x32_bf16 v[32:35], v[216:219], v[170:173], v[32:35]
	v_mfma_f32_16x16x32_bf16 v[20:23], v[208:211], v[178:181], v[20:23]
	v_mfma_f32_16x16x32_bf16 v[12:15], v[216:219], v[178:181], v[12:15]
	v_mfma_f32_16x16x32_bf16 v[4:7], v[208:211], v[200:203], v[4:7]
	v_mfma_f32_16x16x32_bf16 v[0:3], v[216:219], v[200:203], v[0:3]
	v_mfma_f32_16x16x32_bf16 v[52:55], v[212:215], v[166:169], v[52:55]
	v_mfma_f32_16x16x32_bf16 v[44:47], v[220:223], v[166:169], v[44:47]
	v_mfma_f32_16x16x32_bf16 v[36:39], v[212:215], v[174:177], v[36:39]
	v_mfma_f32_16x16x32_bf16 v[32:35], v[220:223], v[174:177], v[32:35]
	v_mfma_f32_16x16x32_bf16 v[20:23], v[212:215], v[196:199], v[20:23]
	v_mfma_f32_16x16x32_bf16 v[12:15], v[220:223], v[196:199], v[12:15]
	v_mfma_f32_16x16x32_bf16 v[4:7], v[212:215], v[204:207], v[4:7]
	v_mfma_f32_16x16x32_bf16 v[0:3], v[220:223], v[204:207], v[0:3]
	s_add_i32 s51, 0, 0x18000
	s_barrier
	ds_read_b128 v[146:149], v226
	ds_read_b128 v[150:153], v226 offset:1024
	ds_read_b128 v[154:157], v226 offset:2048
	ds_read_b128 v[158:161], v226 offset:3072
	s_add_u32 s18, s18, 0x40000
	s_addc_u32 s19, s19, 0
	s_mov_b32 m0, s35
	ds_read_b128 v[162:165], v143 offset:32768
	ds_read_b128 v[166:169], v143 offset:33792
	ds_read_b128 v[170:173], v143 offset:34816
	ds_read_b128 v[174:177], v143 offset:35840
	ds_read_b128 v[178:181], v143 offset:36864
	ds_read_b128 v[196:199], v143 offset:37888
	ds_read_b128 v[200:203], v143 offset:38912
	ds_read_b128 v[204:207], v143 offset:39936
	global_load_lds_dwordx4 v134, s[18:19]
	s_mov_b32 m0, s38
	s_nop 0
	global_load_lds_dwordx4 v130, s[18:19]
	s_waitcnt lgkmcnt(8)
	s_barrier
	s_waitcnt lgkmcnt(7)
	v_mfma_f32_16x16x32_bf16 v[124:127], v[146:149], v[162:165], v[124:127]
	v_mfma_f32_16x16x32_bf16 v[120:123], v[154:157], v[162:165], v[120:123]
	s_waitcnt lgkmcnt(5)
	v_mfma_f32_16x16x32_bf16 v[112:115], v[146:149], v[170:173], v[112:115]
	v_mfma_f32_16x16x32_bf16 v[104:107], v[154:157], v[170:173], v[104:107]
	s_waitcnt lgkmcnt(3)
	v_mfma_f32_16x16x32_bf16 v[92:95], v[146:149], v[178:181], v[92:95]
	v_mfma_f32_16x16x32_bf16 v[88:91], v[154:157], v[178:181], v[88:91]
	s_waitcnt lgkmcnt(1)
	v_mfma_f32_16x16x32_bf16 v[80:83], v[146:149], v[200:203], v[80:83]
	v_mfma_f32_16x16x32_bf16 v[72:75], v[154:157], v[200:203], v[72:75]
	v_mfma_f32_16x16x32_bf16 v[124:127], v[150:153], v[166:169], v[124:127]
	v_mfma_f32_16x16x32_bf16 v[120:123], v[158:161], v[166:169], v[120:123]
	v_mfma_f32_16x16x32_bf16 v[112:115], v[150:153], v[174:177], v[112:115]
	v_mfma_f32_16x16x32_bf16 v[104:107], v[158:161], v[174:177], v[104:107]
	v_mfma_f32_16x16x32_bf16 v[92:95], v[150:153], v[196:199], v[92:95]
	v_mfma_f32_16x16x32_bf16 v[88:91], v[158:161], v[196:199], v[88:91]
	s_waitcnt lgkmcnt(0)
	v_mfma_f32_16x16x32_bf16 v[80:83], v[150:153], v[204:207], v[80:83]
	v_mfma_f32_16x16x32_bf16 v[72:75], v[158:161], v[204:207], v[72:75]
	s_barrier
	s_add_i32 s18, 0, 0x1c000
	s_add_i32 s19, s51, s20
	s_mov_b32 m0, s19
	ds_read_b128 v[208:211], v227
	ds_read_b128 v[212:215], v227 offset:1024
	ds_read_b128 v[216:219], v227 offset:2048
	ds_read_b128 v[220:223], v227 offset:3072
	global_load_lds_dwordx4 v132, vcc
	s_add_i32 m0, s19, 0x2000
	s_nop 0
	global_load_lds_dwordx4 v128, vcc
	s_barrier
	s_waitcnt lgkmcnt(3)
	v_mfma_f32_16x16x32_bf16 v[116:119], v[208:211], v[162:165], v[116:119]
	s_waitcnt lgkmcnt(1)
	v_mfma_f32_16x16x32_bf16 v[108:111], v[216:219], v[162:165], v[108:111]
	v_mfma_f32_16x16x32_bf16 v[100:103], v[208:211], v[170:173], v[100:103]
	v_mfma_f32_16x16x32_bf16 v[96:99], v[216:219], v[170:173], v[96:99]
	v_mfma_f32_16x16x32_bf16 v[84:87], v[208:211], v[178:181], v[84:87]
	v_mfma_f32_16x16x32_bf16 v[76:79], v[216:219], v[178:181], v[76:79]
	v_mfma_f32_16x16x32_bf16 v[68:71], v[208:211], v[200:203], v[68:71]
	v_mfma_f32_16x16x32_bf16 v[64:67], v[216:219], v[200:203], v[64:67]
	v_mfma_f32_16x16x32_bf16 v[116:119], v[212:215], v[166:169], v[116:119]
	s_waitcnt lgkmcnt(0)
	v_mfma_f32_16x16x32_bf16 v[108:111], v[220:223], v[166:169], v[108:111]
	v_mfma_f32_16x16x32_bf16 v[100:103], v[212:215], v[174:177], v[100:103]
	v_mfma_f32_16x16x32_bf16 v[96:99], v[220:223], v[174:177], v[96:99]
	v_mfma_f32_16x16x32_bf16 v[84:87], v[212:215], v[196:199], v[84:87]
	v_mfma_f32_16x16x32_bf16 v[76:79], v[220:223], v[196:199], v[76:79]
	v_mfma_f32_16x16x32_bf16 v[68:71], v[212:215], v[204:207], v[68:71]
	v_mfma_f32_16x16x32_bf16 v[64:67], v[220:223], v[204:207], v[64:67]
	s_mov_b32 m0, s40
	s_barrier
	ds_read_b128 v[162:165], v143 offset:49152
	ds_read_b128 v[166:169], v143 offset:50176
	ds_read_b128 v[170:173], v143 offset:51200
	ds_read_b128 v[174:177], v143 offset:52224
	ds_read_b128 v[178:181], v143 offset:53248
	ds_read_b128 v[196:199], v143 offset:54272
	ds_read_b128 v[200:203], v143 offset:55296
	ds_read_b128 v[204:207], v143 offset:56320
	global_load_lds_dwordx4 v134, s[100:101]
	s_mov_b32 m0, s41
	s_nop 0
	global_load_lds_dwordx4 v130, s[100:101]
	s_barrier
; #define PG8_STAGE(bufoff, gbase, voff) do { _Pragma("unroll") for (int _i = 0; _i < 2; ++_i) \
;     __builtin_amdgcn_global_load_lds((const unsigned*)((const char*)(gbase) + (voff)[_i]), (LAS unsigned*)(lds + (bufoff) + ldsw + _i * 8192), 16, 0, 0); } while (0)
; #define PG8_LDA(dst, b, h) do { _Pragma("unroll") for (int m = 0; m < 4; ++m) _Pragma("unroll") for (int k = 0; k < 2; ++k) dst[m][k] = *(const LAS bf16x8*)(lds + PG8_SA(b, h) + aoff + m * 2048 + k * 1024); } while (0)
; #define PG8_MMA(ai, bj, At, Bt) do { __builtin_amdgcn_s_setprio(1); _Pragma("unroll") for (int m = 0; m < 4; ++m) _Pragma("unroll") for (int n = 0; n < 2; ++n) _Pragma("unroll") for (int k = 0; k < 2; ++k) \
;     acc[ai][bj][m][n] = __builtin_amdgcn_mfma_f32_16x16x32_bf16(Bt[n][k], At[m][k], acc[ai][bj][m][n], 0, 0, 0); __builtin_amdgcn_s_setprio(0); } while (0)
; #define PG8_WAIT_V(n) asm volatile("s_waitcnt vmcnt(" #n ")" ::: "memory")
; #define PG8_WAIT_L(n) asm volatile("s_waitcnt lgkmcnt(" #n ")" ::: "memory")
; #define PG8_BAR __builtin_amdgcn_s_barrier()
; #define PG8_SCHED __builtin_amdgcn_sched_barrier(0)
; template <class Epi, class Sched>
; DI void gemm_phase(LAS unsigned char* lds, const Gemm g, const Sched& S, const Epi& E) {
;     ...
;       PG8_LDA(At, 1, 1); PG8_STAGE(PG8_SA(1, 0), a3, voffA);
;       PG8_BAR; PG8_WAIT_L(0); PG8_MMA(1, 0, At, B0); PG8_BAR; PG8_SCHED;
;       PG8_STAGE(PG8_SB(1, 1), b3 + hstep, voffB);
;       PG8_WAIT_V(6); PG8_BAR; PG8_MMA(1, 1, At, B1); PG8_BAR;
;     }
;   DI void operator()(const f32x4 (&acc)[2][2][4][2], const pg8::Unit& u, int wr, int wc, int fr_, int fq_) const {
;     ...
;             } else {
;               if (n == 0) {
;                 const f32x4 v1 = acc[ai][bj][m][1];
;                 u32x4 o4;
;                 { const float t0 = fmaxf(v[0], 0.f) * rinv, t1 = fmaxf(v[1], 0.f) * rinv, t2 = fmaxf(v[2], 0.f) * rinv, t3 = fmaxf(v[3], 0.f) * rinv;
;                   o4.x = pack2(t0 * t0, t1 * t1); o4.y = pack2(t2 * t2, t3 * t3); }
;                 { const float t0 = fmaxf(v1[0], 0.f) * rinv, t1 = fmaxf(v1[1], 0.f) * rinv, t2 = fmaxf(v1[2], 0.f) * rinv, t3 = fmaxf(v1[3], 0.f) * rinv;
;                   o4.z = pack2(t0 * t0, t1 * t1); o4.w = pack2(t2 * t2, t3 * t3); }
;                 *(u32x4*)((u16*)big + (size_t)token * 4096 + u.pn * 256 + bj * 128 + wc * 32 + 8 * fq) = o4;
;               }
	s_waitcnt lgkmcnt(7)
	v_mfma_f32_16x16x32_bf16 v[60:63], v[146:149], v[162:165], v[60:63]
	v_mfma_f32_16x16x32_bf16 v[56:59], v[154:157], v[162:165], v[56:59]
	s_waitcnt lgkmcnt(5)
	v_mfma_f32_16x16x32_bf16 v[48:51], v[146:149], v[170:173], v[48:51]
	v_mfma_f32_16x16x32_bf16 v[40:43], v[154:157], v[170:173], v[40:43]
	s_waitcnt lgkmcnt(3)
	v_mfma_f32_16x16x32_bf16 v[28:31], v[146:149], v[178:181], v[28:31]
	v_mfma_f32_16x16x32_bf16 v[24:27], v[154:157], v[178:181], v[24:27]
	s_waitcnt lgkmcnt(1)
	v_mfma_f32_16x16x32_bf16 v[16:19], v[146:149], v[200:203], v[16:19]
	v_mfma_f32_16x16x32_bf16 v[8:11], v[154:157], v[200:203], v[8:11]
	v_mfma_f32_16x16x32_bf16 v[60:63], v[150:153], v[166:169], v[60:63]
	v_mfma_f32_16x16x32_bf16 v[56:59], v[158:161], v[166:169], v[56:59]
	v_mfma_f32_16x16x32_bf16 v[48:51], v[150:153], v[174:177], v[48:51]
	v_mfma_f32_16x16x32_bf16 v[40:43], v[158:161], v[174:177], v[40:43]
	v_mfma_f32_16x16x32_bf16 v[28:31], v[150:153], v[196:199], v[28:31]
	v_mfma_f32_16x16x32_bf16 v[24:27], v[158:161], v[196:199], v[24:27]
	s_waitcnt lgkmcnt(0)
	v_mfma_f32_16x16x32_bf16 v[16:19], v[150:153], v[204:207], v[16:19]
	v_mfma_f32_16x16x32_bf16 v[8:11], v[158:161], v[204:207], v[8:11]
	s_barrier
	s_add_u32 s16, s16, 0x40080
	s_addc_u32 s17, s17, 0
	s_add_i32 s18, s18, s20
	s_mov_b32 m0, s18
	s_nop 0
	global_load_lds_dwordx4 v132, s[16:17]
	s_add_i32 m0, s18, 0x2000
	s_nop 0
	global_load_lds_dwordx4 v128, s[16:17]
	s_waitcnt vmcnt(6)
	s_barrier
	v_mfma_f32_16x16x32_bf16 v[52:55], v[208:211], v[162:165], v[52:55]
	v_mfma_f32_16x16x32_bf16 v[44:47], v[216:219], v[162:165], v[44:47]
	v_mfma_f32_16x16x32_bf16 v[36:39], v[208:211], v[170:173], v[36:39]
	v_mfma_f32_16x16x32_bf16 v[32:35], v[216:219], v[170:173], v[32:35]
	v_mfma_f32_16x16x32_bf16 v[20:23], v[208:211], v[178:181], v[20:23]
	v_mfma_f32_16x16x32_bf16 v[12:15], v[216:219], v[178:181], v[12:15]
	v_mfma_f32_16x16x32_bf16 v[4:7], v[208:211], v[200:203], v[4:7]
	v_mfma_f32_16x16x32_bf16 v[0:3], v[216:219], v[200:203], v[0:3]
	v_mfma_f32_16x16x32_bf16 v[52:55], v[212:215], v[166:169], v[52:55]
	v_mfma_f32_16x16x32_bf16 v[44:47], v[220:223], v[166:169], v[44:47]
	v_mfma_f32_16x16x32_bf16 v[36:39], v[212:215], v[174:177], v[36:39]
	v_mfma_f32_16x16x32_bf16 v[32:35], v[220:223], v[174:177], v[32:35]
	v_mfma_f32_16x16x32_bf16 v[20:23], v[212:215], v[196:199], v[20:23]
	v_mfma_f32_16x16x32_bf16 v[12:15], v[220:223], v[196:199], v[12:15]
	v_mfma_f32_16x16x32_bf16 v[4:7], v[212:215], v[204:207], v[4:7]
	v_mfma_f32_16x16x32_bf16 v[0:3], v[220:223], v[204:207], v[0:3]
	s_add_i32 s50, s50, 2
	s_add_u32 s14, s14, 0x100
	s_addc_u32 s15, s15, 0
	s_add_u32 s48, s48, 0x100
	s_addc_u32 s49, s49, 0
	s_cmp_gt_u32 s50, 13
	s_barrier
	s_cbranch_scc0 .LBB0_1829
	v_mov_b32_e32 v144, v182
	s_lshl_b32 s5, s43, 10
	s_add_i32 s5, s5, 0
	v_and_or_b32 v141, v144, 15, s39
	v_lshl_add_u32 v140, s44, 8, v141
	v_lshl_add_u32 v141, v141, 2, s5
	v_add_u32_e32 v146, 0x20000, v141
	ds_read2_b32 v[148:149], v146 offset1:16
	v_max_f32_e32 v124, 0, v124
	v_max_f32_e32 v125, 0, v125
	v_max_f32_e32 v126, 0, v126
	v_max_f32_e32 v127, 0, v127
	v_max_f32_e32 v120, 0, v120
	v_max_f32_e32 v121, 0, v121
	s_waitcnt lgkmcnt(0)
	v_pk_mul_f32 v[124:125], v[124:125], v[148:149] op_sel_hi:[1,0]
	v_pk_mul_f32 v[126:127], v[126:127], v[148:149] op_sel_hi:[1,0]
	v_pk_mul_f32 v[120:121], v[120:121], v[148:149] op_sel_hi:[1,0]
	v_pk_mul_f32 v[124:125], v[124:125], v[124:125]
	v_pk_mul_f32 v[126:127], v[126:127], v[126:127]
	v_max_f32_e32 v122, 0, v122
	v_max_f32_e32 v123, 0, v123
	v_pk_mul_f32 v[120:121], v[120:121], v[120:121]
	v_max_f32_e32 v116, 0, v116
	v_max_f32_e32 v117, 0, v117
	v_max_f32_e32 v118, 0, v118
	v_max_f32_e32 v119, 0, v119
	v_max_f32_e32 v108, 0, v108
	v_max_f32_e32 v109, 0, v109
	s_lshl_b32 s14, s45, 8
	v_ashrrev_i32_e32 v141, 31, v140
	v_cvt_pk_bf16_f32 v124, v124, v125
	v_cvt_pk_bf16_f32 v125, v126, v127
	v_cvt_pk_bf16_f32 v126, v120, v121
	v_pk_mul_f32 v[120:121], v[122:123], v[148:149] op_sel_hi:[1,0]
	v_pk_mul_f32 v[116:117], v[116:117], v[148:149] op_sel_hi:[1,0]
	v_pk_mul_f32 v[118:119], v[118:119], v[148:149] op_sel_hi:[1,0]
	v_pk_mul_f32 v[108:109], v[108:109], v[148:149] op_sel_hi:[1,0]
	s_ashr_i32 s15, s14, 31
	v_lshlrev_b64 v[150:151], 13, v[140:141]
	v_pk_mul_f32 v[120:121], v[120:121], v[120:121]
	v_pk_mul_f32 v[116:117], v[116:117], v[116:117]
	v_pk_mul_f32 v[118:119], v[118:119], v[118:119]
	v_max_f32_e32 v110, 0, v110
	v_max_f32_e32 v111, 0, v111
	v_pk_mul_f32 v[108:109], v[108:109], v[108:109]
	v_cvt_pk_bf16_f32 v127, v120, v121
	v_lshl_add_u64 v[120:121], s[2:3], 0, v[150:151]
	s_lshl_b64 s[14:15], s[14:15], 1
	v_cvt_pk_bf16_f32 v116, v116, v117
	v_cvt_pk_bf16_f32 v117, v118, v119
	v_cvt_pk_bf16_f32 v118, v108, v109
	v_pk_mul_f32 v[108:109], v[110:111], v[148:149] op_sel_hi:[1,0]
	v_lshl_add_u64 v[120:121], v[120:121], 0, s[14:15]
	v_pk_mul_f32 v[108:109], v[108:109], v[108:109]
	v_lshl_add_u64 v[120:121], v[120:121], 0, s[24:25]
	v_and_b32_e32 v144, 48, v144
	v_cvt_pk_bf16_f32 v119, v108, v109
	v_add_u32_e32 v108, 16, v140
	v_lshl_add_u64 v[120:121], v[120:121], 0, v[144:145]
	v_ashrrev_i32_e32 v109, 31, v108
	global_store_dwordx4 v[120:121], v[116:119], off offset:256
	v_max_f32_e32 v100, 0, v100
	v_max_f32_e32 v101, 0, v101
	v_lshlrev_b64 v[116:117], 13, v[108:109]
	v_max_f32_e32 v108, v112, v112
	v_mov_b32_e32 v112, v149
	v_max_f32_e32 v102, 0, v102
	v_max_f32_e32 v103, 0, v103
	v_max_f32_e32 v96, 0, v96
	v_max_f32_e32 v97, 0, v97
	v_pk_mul_f32 v[100:101], v[100:101], v[112:113] op_sel_hi:[1,0]
	v_pk_mul_f32 v[102:103], v[102:103], v[112:113] op_sel_hi:[1,0]
	v_pk_mul_f32 v[96:97], v[96:97], v[112:113] op_sel_hi:[1,0]
	v_pk_mul_f32 v[100:101], v[100:101], v[100:101]
	v_pk_mul_f32 v[102:103], v[102:103], v[102:103]
	v_max_f32_e32 v98, 0, v98
	v_max_f32_e32 v99, 0, v99
	v_pk_mul_f32 v[96:97], v[96:97], v[96:97]
	v_cvt_pk_bf16_f32 v100, v100, v101
	v_cvt_pk_bf16_f32 v101, v102, v103
	v_cvt_pk_bf16_f32 v102, v96, v97
	v_pk_mul_f32 v[96:97], v[98:99], v[112:113] op_sel_hi:[1,0]
	ds_read2_b32 v[98:99], v146 offset0:32 offset1:48
	v_max_f32_e32 v92, 0, v92
	v_max_f32_e32 v93, 0, v93
	v_max_f32_e32 v94, 0, v94
	v_max_f32_e32 v95, 0, v95
	v_max_f32_e32 v88, 0, v88
	v_max_f32_e32 v89, 0, v89
	v_pk_mul_f32 v[96:97], v[96:97], v[96:97]
	s_waitcnt lgkmcnt(0)
;   DI void operator()(const f32x4 (&acc)[2][2][4][2], const pg8::Unit& u, int wr, int wc, int fr_, int fq_) const {
;     ...
;             } else {
;               if (n == 0) {
;                 const f32x4 v1 = acc[ai][bj][m][1];
;                 u32x4 o4;
;                 { const float t0 = fmaxf(v[0], 0.f) * rinv, t1 = fmaxf(v[1], 0.f) * rinv, t2 = fmaxf(v[2], 0.f) * rinv, t3 = fmaxf(v[3], 0.f) * rinv;
;                   o4.x = pack2(t0 * t0, t1 * t1); o4.y = pack2(t2 * t2, t3 * t3); }
;                 { const float t0 = fmaxf(v1[0], 0.f) * rinv, t1 = fmaxf(v1[1], 0.f) * rinv, t2 = fmaxf(v1[2], 0.f) * rinv, t3 = fmaxf(v1[3], 0.f) * rinv;
;                   o4.z = pack2(t0 * t0, t1 * t1); o4.w = pack2(t2 * t2, t3 * t3); }
;                 *(u32x4*)((u16*)big + (size_t)token * 4096 + u.pn * 256 + bj * 128 + wc * 32 + 8 * fq) = o4;
;               }
	v_pk_mul_f32 v[92:93], v[92:93], v[98:99] op_sel_hi:[1,0]
	v_pk_mul_f32 v[94:95], v[94:95], v[98:99] op_sel_hi:[1,0]
	v_pk_mul_f32 v[88:89], v[88:89], v[98:99] op_sel_hi:[1,0]
	v_cvt_pk_bf16_f32 v103, v96, v97
	v_add_u32_e32 v96, 32, v140
	v_pk_mul_f32 v[92:93], v[92:93], v[92:93]
	v_pk_mul_f32 v[94:95], v[94:95], v[94:95]
	v_max_f32_e32 v90, 0, v90
	v_max_f32_e32 v91, 0, v91
	v_pk_mul_f32 v[88:89], v[88:89], v[88:89]
	v_max_f32_e32 v84, 0, v84
	v_max_f32_e32 v85, 0, v85
	v_max_f32_e32 v86, 0, v86
	v_max_f32_e32 v87, 0, v87
	v_max_f32_e32 v76, 0, v76
	v_max_f32_e32 v77, 0, v77
	v_ashrrev_i32_e32 v97, 31, v96
	v_cvt_pk_bf16_f32 v92, v92, v93
	v_cvt_pk_bf16_f32 v93, v94, v95
	v_cvt_pk_bf16_f32 v94, v88, v89
	v_pk_mul_f32 v[88:89], v[90:91], v[98:99] op_sel_hi:[1,0]
	v_pk_mul_f32 v[84:85], v[84:85], v[98:99] op_sel_hi:[1,0]
	v_pk_mul_f32 v[86:87], v[86:87], v[98:99] op_sel_hi:[1,0]
	v_pk_mul_f32 v[76:77], v[76:77], v[98:99] op_sel_hi:[1,0]
	v_lshlrev_b64 v[96:97], 13, v[96:97]
	v_pk_mul_f32 v[88:89], v[88:89], v[88:89]
	v_pk_mul_f32 v[84:85], v[84:85], v[84:85]
	v_pk_mul_f32 v[86:87], v[86:87], v[86:87]
	v_max_f32_e32 v78, 0, v78
	v_max_f32_e32 v79, 0, v79
	v_pk_mul_f32 v[76:77], v[76:77], v[76:77]
	v_cvt_pk_bf16_f32 v95, v88, v89
	v_lshl_add_u64 v[88:89], s[2:3], 0, v[96:97]
	v_cvt_pk_bf16_f32 v84, v84, v85
	v_cvt_pk_bf16_f32 v85, v86, v87
	v_cvt_pk_bf16_f32 v86, v76, v77
	v_pk_mul_f32 v[76:77], v[78:79], v[98:99] op_sel_hi:[1,0]
	v_lshl_add_u64 v[88:89], v[88:89], 0, s[14:15]
	v_pk_mul_f32 v[76:77], v[76:77], v[76:77]
	v_lshl_add_u64 v[88:89], v[88:89], 0, s[24:25]
	v_cvt_pk_bf16_f32 v87, v76, v77
	v_add_u32_e32 v76, 48, v140
	v_lshl_add_u64 v[88:89], v[88:89], 0, v[144:145]
	v_ashrrev_i32_e32 v77, 31, v76
	global_store_dwordx4 v[88:89], v[84:87], off offset:256
	v_max_f32_e32 v68, 0, v68
	v_max_f32_e32 v69, 0, v69
	v_lshlrev_b64 v[84:85], 13, v[76:77]
	v_max_f32_e32 v76, v80, v80
	v_mov_b32_e32 v80, v99
	v_max_f32_e32 v70, 0, v70
	v_max_f32_e32 v71, 0, v71
	v_max_f32_e32 v64, 0, v64
	v_max_f32_e32 v65, 0, v65
	v_pk_mul_f32 v[68:69], v[68:69], v[80:81] op_sel_hi:[1,0]
	v_pk_mul_f32 v[70:71], v[70:71], v[80:81] op_sel_hi:[1,0]
	v_pk_mul_f32 v[64:65], v[64:65], v[80:81] op_sel_hi:[1,0]
	v_pk_mul_f32 v[68:69], v[68:69], v[68:69]
	v_pk_mul_f32 v[70:71], v[70:71], v[70:71]
	v_max_f32_e32 v66, 0, v66
	v_max_f32_e32 v67, 0, v67
	v_pk_mul_f32 v[64:65], v[64:65], v[64:65]
	v_cvt_pk_bf16_f32 v68, v68, v69
	v_cvt_pk_bf16_f32 v69, v70, v71
	v_cvt_pk_bf16_f32 v70, v64, v65
	v_pk_mul_f32 v[64:65], v[66:67], v[80:81] op_sel_hi:[1,0]
	ds_read2_b32 v[66:67], v146 offset0:128 offset1:144
	v_max_f32_e32 v60, 0, v60
	v_max_f32_e32 v61, 0, v61
	v_max_f32_e32 v62, 0, v62
	v_max_f32_e32 v63, 0, v63
	v_max_f32_e32 v56, 0, v56
	v_max_f32_e32 v57, 0, v57
	v_pk_mul_f32 v[64:65], v[64:65], v[64:65]
	s_waitcnt lgkmcnt(0)
	v_pk_mul_f32 v[60:61], v[60:61], v[66:67] op_sel_hi:[1,0]
	v_pk_mul_f32 v[62:63], v[62:63], v[66:67] op_sel_hi:[1,0]
	v_pk_mul_f32 v[56:57], v[56:57], v[66:67] op_sel_hi:[1,0]
	v_cvt_pk_bf16_f32 v71, v64, v65
	v_add_u32_e32 v64, 0x80, v140
	v_pk_mul_f32 v[60:61], v[60:61], v[60:61]
	v_pk_mul_f32 v[62:63], v[62:63], v[62:63]
	v_max_f32_e32 v58, 0, v58
	v_max_f32_e32 v59, 0, v59
	v_pk_mul_f32 v[56:57], v[56:57], v[56:57]
	v_max_f32_e32 v52, 0, v52
	v_max_f32_e32 v53, 0, v53
	v_max_f32_e32 v54, 0, v54
	v_max_f32_e32 v55, 0, v55
	v_max_f32_e32 v44, 0, v44
	v_max_f32_e32 v45, 0, v45
	v_ashrrev_i32_e32 v65, 31, v64
	v_cvt_pk_bf16_f32 v60, v60, v61
	v_cvt_pk_bf16_f32 v61, v62, v63
	v_cvt_pk_bf16_f32 v62, v56, v57
	v_pk_mul_f32 v[56:57], v[58:59], v[66:67] op_sel_hi:[1,0]
	v_pk_mul_f32 v[52:53], v[52:53], v[66:67] op_sel_hi:[1,0]
	v_pk_mul_f32 v[54:55], v[54:55], v[66:67] op_sel_hi:[1,0]
	v_pk_mul_f32 v[44:45], v[44:45], v[66:67] op_sel_hi:[1,0]
	v_lshlrev_b64 v[64:65], 13, v[64:65]
	v_pk_mul_f32 v[56:57], v[56:57], v[56:57]
	v_pk_mul_f32 v[52:53], v[52:53], v[52:53]
	v_pk_mul_f32 v[54:55], v[54:55], v[54:55]
	v_max_f32_e32 v46, 0, v46
	v_max_f32_e32 v47, 0, v47
	v_pk_mul_f32 v[44:45], v[44:45], v[44:45]
	v_cvt_pk_bf16_f32 v63, v56, v57
	v_lshl_add_u64 v[56:57], s[2:3], 0, v[64:65]
	v_cvt_pk_bf16_f32 v52, v52, v53
	v_cvt_pk_bf16_f32 v53, v54, v55
	v_cvt_pk_bf16_f32 v54, v44, v45
	v_pk_mul_f32 v[44:45], v[46:47], v[66:67] op_sel_hi:[1,0]
	v_lshl_add_u64 v[56:57], v[56:57], 0, s[14:15]
	v_pk_mul_f32 v[44:45], v[44:45], v[44:45]
	v_lshl_add_u64 v[56:57], v[56:57], 0, s[24:25]
	v_cvt_pk_bf16_f32 v55, v44, v45
	v_add_u32_e32 v44, 0x90, v140
	v_lshl_add_u64 v[56:57], v[56:57], 0, v[144:145]
	v_ashrrev_i32_e32 v45, 31, v44
	global_store_dwordx4 v[56:57], v[52:55], off offset:256
	v_max_f32_e32 v36, 0, v36
	v_max_f32_e32 v37, 0, v37
	v_lshlrev_b64 v[52:53], 13, v[44:45]
	v_max_f32_e32 v44, v48, v48
	v_mov_b32_e32 v48, v67
	v_max_f32_e32 v38, 0, v38
	v_max_f32_e32 v39, 0, v39
	v_max_f32_e32 v32, 0, v32
	v_max_f32_e32 v33, 0, v33
	v_pk_mul_f32 v[36:37], v[36:37], v[48:49] op_sel_hi:[1,0]
	v_pk_mul_f32 v[38:39], v[38:39], v[48:49] op_sel_hi:[1,0]
	v_pk_mul_f32 v[32:33], v[32:33], v[48:49] op_sel_hi:[1,0]
	v_pk_mul_f32 v[36:37], v[36:37], v[36:37]
	v_pk_mul_f32 v[38:39], v[38:39], v[38:39]
	v_max_f32_e32 v34, 0, v34
	v_max_f32_e32 v35, 0, v35
	v_pk_mul_f32 v[32:33], v[32:33], v[32:33]
	v_cvt_pk_bf16_f32 v36, v36, v37
	v_cvt_pk_bf16_f32 v37, v38, v39
	v_cvt_pk_bf16_f32 v38, v32, v33
	v_pk_mul_f32 v[32:33], v[34:35], v[48:49] op_sel_hi:[1,0]
	ds_read2_b32 v[34:35], v146 offset0:160 offset1:176
	v_max_f32_e32 v28, 0, v28
	v_max_f32_e32 v29, 0, v29
	v_max_f32_e32 v30, 0, v30
	v_max_f32_e32 v31, 0, v31
	v_max_f32_e32 v24, 0, v24
	v_max_f32_e32 v25, 0, v25
	v_pk_mul_f32 v[32:33], v[32:33], v[32:33]
	s_waitcnt lgkmcnt(0)
;   DI void operator()(const f32x4 (&acc)[2][2][4][2], const pg8::Unit& u, int wr, int wc, int fr_, int fq_) const {
;     ...
;             } else {
;               if (n == 0) {
;                 const f32x4 v1 = acc[ai][bj][m][1];
;                 u32x4 o4;
;                 { const float t0 = fmaxf(v[0], 0.f) * rinv, t1 = fmaxf(v[1], 0.f) * rinv, t2 = fmaxf(v[2], 0.f) * rinv, t3 = fmaxf(v[3], 0.f) * rinv;
;                   o4.x = pack2(t0 * t0, t1 * t1); o4.y = pack2(t2 * t2, t3 * t3); }
;                 { const float t0 = fmaxf(v1[0], 0.f) * rinv, t1 = fmaxf(v1[1], 0.f) * rinv, t2 = fmaxf(v1[2], 0.f) * rinv, t3 = fmaxf(v1[3], 0.f) * rinv;
;                   o4.z = pack2(t0 * t0, t1 * t1); o4.w = pack2(t2 * t2, t3 * t3); }
;                 *(u32x4*)((u16*)big + (size_t)token * 4096 + u.pn * 256 + bj * 128 + wc * 32 + 8 * fq) = o4;
;               }
	v_pk_mul_f32 v[28:29], v[28:29], v[34:35] op_sel_hi:[1,0]
	v_pk_mul_f32 v[30:31], v[30:31], v[34:35] op_sel_hi:[1,0]
	v_pk_mul_f32 v[24:25], v[24:25], v[34:35] op_sel_hi:[1,0]
	v_cvt_pk_bf16_f32 v39, v32, v33
	v_add_u32_e32 v32, 0xa0, v140
	v_pk_mul_f32 v[28:29], v[28:29], v[28:29]
	v_pk_mul_f32 v[30:31], v[30:31], v[30:31]
	v_max_f32_e32 v26, 0, v26
	v_max_f32_e32 v27, 0, v27
	v_pk_mul_f32 v[24:25], v[24:25], v[24:25]
	v_max_f32_e32 v20, 0, v20
	v_max_f32_e32 v21, 0, v21
	v_max_f32_e32 v22, 0, v22
	v_max_f32_e32 v23, 0, v23
	v_max_f32_e32 v12, 0, v12
	v_max_f32_e32 v13, 0, v13
	v_ashrrev_i32_e32 v33, 31, v32
	v_cvt_pk_bf16_f32 v28, v28, v29
	v_cvt_pk_bf16_f32 v29, v30, v31
	v_cvt_pk_bf16_f32 v30, v24, v25
	v_pk_mul_f32 v[24:25], v[26:27], v[34:35] op_sel_hi:[1,0]
	v_pk_mul_f32 v[20:21], v[20:21], v[34:35] op_sel_hi:[1,0]
	v_pk_mul_f32 v[22:23], v[22:23], v[34:35] op_sel_hi:[1,0]
	v_pk_mul_f32 v[12:13], v[12:13], v[34:35] op_sel_hi:[1,0]
	v_lshlrev_b64 v[32:33], 13, v[32:33]
	v_pk_mul_f32 v[24:25], v[24:25], v[24:25]
	v_pk_mul_f32 v[20:21], v[20:21], v[20:21]
	v_pk_mul_f32 v[22:23], v[22:23], v[22:23]
	v_max_f32_e32 v14, 0, v14
	v_max_f32_e32 v15, 0, v15
	v_pk_mul_f32 v[12:13], v[12:13], v[12:13]
	v_cvt_pk_bf16_f32 v31, v24, v25
	v_lshl_add_u64 v[24:25], s[2:3], 0, v[32:33]
	v_cvt_pk_bf16_f32 v20, v20, v21
	v_cvt_pk_bf16_f32 v21, v22, v23
	v_cvt_pk_bf16_f32 v22, v12, v13
	v_pk_mul_f32 v[12:13], v[14:15], v[34:35] op_sel_hi:[1,0]
	v_lshl_add_u64 v[24:25], v[24:25], 0, s[14:15]
	v_pk_mul_f32 v[12:13], v[12:13], v[12:13]
	v_lshl_add_u64 v[24:25], v[24:25], 0, s[24:25]
	v_cvt_pk_bf16_f32 v23, v12, v13
	v_add_u32_e32 v12, 0xb0, v140
	v_lshl_add_u64 v[24:25], v[24:25], 0, v[144:145]
	v_ashrrev_i32_e32 v13, 31, v12
	v_max_f32_e32 v109, v113, v113
	v_max_f32_e32 v110, v114, v114
	v_max_f32_e32 v111, v115, v115
	v_max_f32_e32 v77, v81, v81
	v_max_f32_e32 v78, v82, v82
	v_max_f32_e32 v79, v83, v83
	v_max_f32_e32 v45, v49, v49
	v_max_f32_e32 v46, v50, v50
	v_max_f32_e32 v47, v51, v51
	global_store_dwordx4 v[24:25], v[20:23], off offset:256
	v_max_f32_e32 v14, v18, v18
	v_max_f32_e32 v15, v19, v19
	v_lshlrev_b64 v[20:21], 13, v[12:13]
	v_max_f32_e32 v12, v16, v16
	v_max_f32_e32 v13, v17, v17
	v_max_f32_e32 v108, 0, v108
	v_max_f32_e32 v109, 0, v109
	v_max_f32_e32 v110, 0, v110
	v_max_f32_e32 v111, 0, v111
	v_max_f32_e32 v104, 0, v104
	v_max_f32_e32 v105, 0, v105
	v_max_f32_e32 v76, 0, v76
	v_max_f32_e32 v77, 0, v77
	v_max_f32_e32 v78, 0, v78
	v_max_f32_e32 v79, 0, v79
	v_max_f32_e32 v72, 0, v72
	v_max_f32_e32 v73, 0, v73
	v_max_f32_e32 v44, 0, v44
	v_max_f32_e32 v45, 0, v45
	v_max_f32_e32 v46, 0, v46
	v_max_f32_e32 v47, 0, v47
	v_max_f32_e32 v40, 0, v40
	v_max_f32_e32 v41, 0, v41
	v_max_f32_e32 v12, 0, v12
	v_max_f32_e32 v13, 0, v13
	v_max_f32_e32 v14, 0, v14
	v_max_f32_e32 v15, 0, v15
	v_mov_b32_e32 v16, v35
	v_max_f32_e32 v8, 0, v8
	v_max_f32_e32 v9, 0, v9
	v_pk_mul_f32 v[108:109], v[108:109], v[112:113] op_sel_hi:[1,0]
	v_pk_mul_f32 v[110:111], v[110:111], v[112:113] op_sel_hi:[1,0]
	v_pk_mul_f32 v[104:105], v[104:105], v[112:113] op_sel_hi:[1,0]
	v_pk_mul_f32 v[76:77], v[76:77], v[80:81] op_sel_hi:[1,0]
	v_pk_mul_f32 v[78:79], v[78:79], v[80:81] op_sel_hi:[1,0]
	v_pk_mul_f32 v[72:73], v[72:73], v[80:81] op_sel_hi:[1,0]
	v_pk_mul_f32 v[44:45], v[44:45], v[48:49] op_sel_hi:[1,0]
	v_pk_mul_f32 v[46:47], v[46:47], v[48:49] op_sel_hi:[1,0]
	v_pk_mul_f32 v[40:41], v[40:41], v[48:49] op_sel_hi:[1,0]
	v_pk_mul_f32 v[12:13], v[12:13], v[16:17] op_sel_hi:[1,0]
	v_pk_mul_f32 v[14:15], v[14:15], v[16:17] op_sel_hi:[1,0]
	v_pk_mul_f32 v[8:9], v[8:9], v[16:17] op_sel_hi:[1,0]
	v_pk_mul_f32 v[108:109], v[108:109], v[108:109]
	v_pk_mul_f32 v[110:111], v[110:111], v[110:111]
	v_max_f32_e32 v106, 0, v106
	v_max_f32_e32 v107, 0, v107
	v_pk_mul_f32 v[104:105], v[104:105], v[104:105]
; #define PG8_WAIT_V(n) asm volatile("s_waitcnt vmcnt(" #n ")" ::: "memory")
; #define PG8_BAR __builtin_amdgcn_s_barrier()
; template <class Epi, class Sched>
; DI void gemm_phase(LAS unsigned char* lds, const Gemm g, const Sched& S, const Epi& E) {
;     ...
;     E(acc, cur, wr, wc, fr, fq);
;     if (!has_next) break;
; #pragma unroll
;     for (int a = 0; a < 2; ++a)
; #pragma unroll
;       for (int b = 0; b < 2; ++b)
; #pragma unroll
;         for (int m = 0; m < 4; ++m)
; #pragma unroll
;           for (int n = 0; n < 2; ++n) acc[a][b][m][n] = (f32x4){0.f, 0.f, 0.f, 0.f};
;     cur = nxt; cA = nA; cB = nB; ++ui;
;   }
;   PG8_WAIT_V(0);
;   if (wr == 0) PG8_BAR;
;   PG8_BAR;
;   DI void operator()(const f32x4 (&acc)[2][2][4][2], const pg8::Unit& u, int wr, int wc, int fr_, int fq_) const {
;     ...
;             } else {
;               if (n == 0) {
;                 const f32x4 v1 = acc[ai][bj][m][1];
;                 u32x4 o4;
;                 { const float t0 = fmaxf(v[0], 0.f) * rinv, t1 = fmaxf(v[1], 0.f) * rinv, t2 = fmaxf(v[2], 0.f) * rinv, t3 = fmaxf(v[3], 0.f) * rinv;
;                   o4.x = pack2(t0 * t0, t1 * t1); o4.y = pack2(t2 * t2, t3 * t3); }
;                 { const float t0 = fmaxf(v1[0], 0.f) * rinv, t1 = fmaxf(v1[1], 0.f) * rinv, t2 = fmaxf(v1[2], 0.f) * rinv, t3 = fmaxf(v1[3], 0.f) * rinv;
;                   o4.z = pack2(t0 * t0, t1 * t1); o4.w = pack2(t2 * t2, t3 * t3); }
;                 *(u32x4*)((u16*)big + (size_t)token * 4096 + u.pn * 256 + bj * 128 + wc * 32 + 8 * fq) = o4;
;               }
	v_pk_mul_f32 v[76:77], v[76:77], v[76:77]
	v_pk_mul_f32 v[78:79], v[78:79], v[78:79]
	v_max_f32_e32 v74, 0, v74
	v_max_f32_e32 v75, 0, v75
	v_pk_mul_f32 v[72:73], v[72:73], v[72:73]
	v_pk_mul_f32 v[44:45], v[44:45], v[44:45]
	v_pk_mul_f32 v[46:47], v[46:47], v[46:47]
	v_max_f32_e32 v42, 0, v42
	v_max_f32_e32 v43, 0, v43
	v_pk_mul_f32 v[40:41], v[40:41], v[40:41]
	v_pk_mul_f32 v[12:13], v[12:13], v[12:13]
	v_pk_mul_f32 v[14:15], v[14:15], v[14:15]
	v_max_f32_e32 v10, 0, v10
	v_max_f32_e32 v11, 0, v11
	v_pk_mul_f32 v[8:9], v[8:9], v[8:9]
	v_cvt_pk_bf16_f32 v108, v108, v109
	v_cvt_pk_bf16_f32 v109, v110, v111
	v_cvt_pk_bf16_f32 v110, v104, v105
	v_pk_mul_f32 v[104:105], v[106:107], v[112:113] op_sel_hi:[1,0]
	v_cvt_pk_bf16_f32 v76, v76, v77
	v_cvt_pk_bf16_f32 v77, v78, v79
	v_cvt_pk_bf16_f32 v78, v72, v73
	v_pk_mul_f32 v[72:73], v[74:75], v[80:81] op_sel_hi:[1,0]
	v_cvt_pk_bf16_f32 v44, v44, v45
	v_cvt_pk_bf16_f32 v45, v46, v47
	v_cvt_pk_bf16_f32 v46, v40, v41
	v_pk_mul_f32 v[40:41], v[42:43], v[48:49] op_sel_hi:[1,0]
	v_cvt_pk_bf16_f32 v12, v12, v13
	v_cvt_pk_bf16_f32 v13, v14, v15
	v_cvt_pk_bf16_f32 v14, v8, v9
	v_pk_mul_f32 v[8:9], v[10:11], v[16:17] op_sel_hi:[1,0]
	v_max_f32_e32 v4, 0, v4
	v_max_f32_e32 v5, 0, v5
	v_max_f32_e32 v6, 0, v6
	v_max_f32_e32 v7, 0, v7
	v_max_f32_e32 v0, 0, v0
	v_max_f32_e32 v1, 0, v1
	v_pk_mul_f32 v[104:105], v[104:105], v[104:105]
	v_pk_mul_f32 v[72:73], v[72:73], v[72:73]
	v_pk_mul_f32 v[40:41], v[40:41], v[40:41]
	v_pk_mul_f32 v[8:9], v[8:9], v[8:9]
	v_pk_mul_f32 v[4:5], v[4:5], v[16:17] op_sel_hi:[1,0]
	v_pk_mul_f32 v[6:7], v[6:7], v[16:17] op_sel_hi:[1,0]
	v_pk_mul_f32 v[0:1], v[0:1], v[16:17] op_sel_hi:[1,0]
	v_cvt_pk_bf16_f32 v111, v104, v105
	v_lshl_add_u64 v[104:105], s[2:3], 0, v[116:117]
	v_cvt_pk_bf16_f32 v79, v72, v73
	v_lshl_add_u64 v[72:73], s[2:3], 0, v[84:85]
	v_cvt_pk_bf16_f32 v47, v40, v41
	v_lshl_add_u64 v[40:41], s[2:3], 0, v[52:53]
	v_cvt_pk_bf16_f32 v15, v8, v9
	v_lshl_add_u64 v[8:9], s[2:3], 0, v[20:21]
	v_pk_mul_f32 v[4:5], v[4:5], v[4:5]
	v_pk_mul_f32 v[6:7], v[6:7], v[6:7]
	v_max_f32_e32 v2, 0, v2
	v_max_f32_e32 v3, 0, v3
	v_pk_mul_f32 v[0:1], v[0:1], v[0:1]
	v_lshl_add_u64 v[104:105], v[104:105], 0, s[14:15]
	v_lshl_add_u64 v[72:73], v[72:73], 0, s[14:15]
	v_lshl_add_u64 v[40:41], v[40:41], 0, s[14:15]
	v_lshl_add_u64 v[8:9], v[8:9], 0, s[14:15]
	v_cvt_pk_bf16_f32 v4, v4, v5
	v_cvt_pk_bf16_f32 v5, v6, v7
	v_cvt_pk_bf16_f32 v6, v0, v1
	v_pk_mul_f32 v[0:1], v[2:3], v[16:17] op_sel_hi:[1,0]
	v_lshl_add_u64 v[104:105], v[104:105], 0, s[24:25]
	v_lshl_add_u64 v[72:73], v[72:73], 0, s[24:25]
	v_lshl_add_u64 v[40:41], v[40:41], 0, s[24:25]
	v_lshl_add_u64 v[8:9], v[8:9], 0, s[24:25]
	v_pk_mul_f32 v[0:1], v[0:1], v[0:1]
	v_lshl_add_u64 v[104:105], v[104:105], 0, v[144:145]
	v_lshl_add_u64 v[72:73], v[72:73], 0, v[144:145]
	v_lshl_add_u64 v[40:41], v[40:41], 0, v[144:145]
	v_lshl_add_u64 v[8:9], v[8:9], 0, v[144:145]
	v_cvt_pk_bf16_f32 v7, v0, v1
	s_and_b64 vcc, exec, s[36:37]
	s_mov_b32 s43, s42
	s_mov_b32 s45, s4
	s_mov_b32 s44, s6
	s_mov_b64 s[16:17], s[12:13]
	s_mov_b64 s[14:15], s[10:11]
	v_readlane_b32 s51, v237, 11
	global_store_dwordx4 v[120:121], v[124:127], off
	global_store_dwordx4 v[104:105], v[108:111], off
	global_store_dwordx4 v[104:105], v[100:103], off offset:256
	global_store_dwordx4 v[88:89], v[92:95], off
	global_store_dwordx4 v[72:73], v[76:79], off
	global_store_dwordx4 v[72:73], v[68:71], off offset:256
	global_store_dwordx4 v[56:57], v[60:63], off
	global_store_dwordx4 v[40:41], v[44:47], off
	global_store_dwordx4 v[40:41], v[36:39], off offset:256
	global_store_dwordx4 v[24:25], v[28:31], off
	global_store_dwordx4 v[8:9], v[12:15], off
	global_store_dwordx4 v[8:9], v[4:7], off offset:256
	s_cbranch_vccz .LBB0_1822
	s_waitcnt vmcnt(0)
	s_cmpk_gt_u32 s9, 0xff
	s_cbranch_scc1 .LBB0_1833
	s_barrier

; #define PG8_STAGE(bufoff, gbase, voff) do { _Pragma("unroll") for (int _i = 0; _i < 2; ++_i) \
;     __builtin_amdgcn_global_load_lds((const unsigned*)((const char*)(gbase) + (voff)[_i]), (LAS unsigned*)(lds + (bufoff) + ldsw + _i * 8192), 16, 0, 0); } while (0)
; #define PG8_LDA(dst, b, h) do { _Pragma("unroll") for (int m = 0; m < 4; ++m) _Pragma("unroll") for (int k = 0; k < 2; ++k) dst[m][k] = *(const LAS bf16x8*)(lds + PG8_SA(b, h) + aoff + m * 2048 + k * 1024); } while (0)
; #define PG8_LDB(dst, b, h) do { _Pragma("unroll") for (int n = 0; n < 2; ++n) _Pragma("unroll") for (int k = 0; k < 2; ++k) dst[n][k] = *(const LAS bf16x8*)(lds + PG8_SB(b, h) + boff + n * 2048 + k * 1024); } while (0)
; #define PG8_MMA(ai, bj, At, Bt) do { __builtin_amdgcn_s_setprio(1); _Pragma("unroll") for (int m = 0; m < 4; ++m) _Pragma("unroll") for (int n = 0; n < 2; ++n) _Pragma("unroll") for (int k = 0; k < 2; ++k) \
;     acc[ai][bj][m][n] = __builtin_amdgcn_mfma_f32_16x16x32_bf16(Bt[n][k], At[m][k], acc[ai][bj][m][n], 0, 0, 0); __builtin_amdgcn_s_setprio(0); } while (0)
; #define PG8_WAIT_V(n) asm volatile("s_waitcnt vmcnt(" #n ")" ::: "memory")
; #define PG8_WAIT_L(n) asm volatile("s_waitcnt lgkmcnt(" #n ")" ::: "memory")
; #define PG8_BAR __builtin_amdgcn_s_barrier()
; #define PG8_SCHED __builtin_amdgcn_sched_barrier(0)
; template <class Epi, class Sched>
; DI void gemm_phase(LAS unsigned char* lds, const Gemm g, const Sched& S, const Epi& E) {
;     ...
;     for (int t = 0; t < nt; t += 2) {
;       const bool last = (t == nt - 2);
;       const char* a1 = cA + (size_t)(t + 1) * kstep;
;       const char* a2 = last ? nA : cA + (size_t)(t + 2) * kstep; const char* b2 = last ? nB : cB + (size_t)(t + 2) * kstep;
;       const char* a3 = a2 + kstep; const char* b3 = b2 + kstep;
;       PG8_LDB(B0, 0, 0); PG8_SCHED; PG8_LDA(At, 0, 0); PG8_STAGE(PG8_SA(1, 1), a1 + hstep, voffA);
;       PG8_WAIT_L(8); PG8_BAR; PG8_WAIT_L(0); PG8_MMA(0, 0, At, B0); PG8_BAR; PG8_SCHED;
;       PG8_LDB(B1, 0, 1); PG8_STAGE(PG8_SB(0, 0), b2, voffB);
;       PG8_BAR; PG8_WAIT_L(0); PG8_MMA(0, 1, At, B1); PG8_BAR;
;       PG8_LDA(At, 0, 1); PG8_STAGE(PG8_SA(0, 0), a2, voffA);
;       PG8_BAR; PG8_WAIT_L(0); PG8_MMA(1, 0, At, B0); PG8_BAR; PG8_SCHED;
;       PG8_STAGE(PG8_SB(0, 1), b2 + hstep, voffB);
;       PG8_WAIT_V(6); PG8_BAR; PG8_MMA(1, 1, At, B1); PG8_BAR;
.LBB0_1905:
	s_add_u32 s22, s20, 0xfff00080
	s_addc_u32 s23, s21, -1
	s_add_i32 s51, 0, 0x10000
	ds_read_b128 v[138:141], v224
	ds_read_b128 v[148:151], v224 offset:1024
	ds_read_b128 v[152:155], v224 offset:2048
	ds_read_b128 v[156:159], v224 offset:3072
	s_cmp_eq_u32 s50, 60
	s_cselect_b32 s29, s11, s23
	s_cselect_b32 s28, s17, s22
	s_cselect_b32 s23, s7, s49
	s_cselect_b32 s22, s19, s24
	s_add_i32 m0, s39, 0xc000
	ds_read_b128 v[160:163], v147
	ds_read_b128 v[164:167], v147 offset:1024
	ds_read_b128 v[168:171], v147 offset:2048
	ds_read_b128 v[172:175], v147 offset:3072
	ds_read_b128 v[176:179], v147 offset:4096
	ds_read_b128 v[196:199], v147 offset:5120
	ds_read_b128 v[200:203], v147 offset:6144
	ds_read_b128 v[204:207], v147 offset:7168
	global_load_lds_dwordx4 v134, s[20:21]
	s_add_i32 m0, s39, 0xe000
	s_nop 0
	global_load_lds_dwordx4 v136, s[20:21]
	s_waitcnt lgkmcnt(8)
	s_barrier
	s_waitcnt lgkmcnt(7)
	v_mfma_f32_16x16x32_bf16 v[124:127], v[138:141], v[160:163], v[124:127]
	v_mfma_f32_16x16x32_bf16 v[120:123], v[152:155], v[160:163], v[120:123]
	s_waitcnt lgkmcnt(5)
	v_mfma_f32_16x16x32_bf16 v[108:111], v[138:141], v[168:171], v[108:111]
	v_mfma_f32_16x16x32_bf16 v[104:107], v[152:155], v[168:171], v[104:107]
	s_waitcnt lgkmcnt(3)
	v_mfma_f32_16x16x32_bf16 v[92:95], v[138:141], v[176:179], v[92:95]
	v_mfma_f32_16x16x32_bf16 v[88:91], v[152:155], v[176:179], v[88:91]
	s_waitcnt lgkmcnt(1)
	v_mfma_f32_16x16x32_bf16 v[76:79], v[138:141], v[200:203], v[76:79]
	v_mfma_f32_16x16x32_bf16 v[72:75], v[152:155], v[200:203], v[72:75]
	v_mfma_f32_16x16x32_bf16 v[124:127], v[148:151], v[164:167], v[124:127]
	v_mfma_f32_16x16x32_bf16 v[120:123], v[156:159], v[164:167], v[120:123]
	v_mfma_f32_16x16x32_bf16 v[108:111], v[148:151], v[172:175], v[108:111]
	v_mfma_f32_16x16x32_bf16 v[104:107], v[156:159], v[172:175], v[104:107]
	v_mfma_f32_16x16x32_bf16 v[92:95], v[148:151], v[196:199], v[92:95]
	v_mfma_f32_16x16x32_bf16 v[88:91], v[156:159], v[196:199], v[88:91]
	s_waitcnt lgkmcnt(0)
	v_mfma_f32_16x16x32_bf16 v[76:79], v[148:151], v[204:207], v[76:79]
	v_mfma_f32_16x16x32_bf16 v[72:75], v[156:159], v[204:207], v[72:75]
	s_barrier
	s_add_i32 s54, 0, 0x14000
	s_add_i32 s51, s51, s38
	ds_read_b128 v[208:211], v225
	ds_read_b128 v[212:215], v225 offset:1024
	ds_read_b128 v[216:219], v225 offset:2048
	ds_read_b128 v[220:223], v225 offset:3072
	s_add_u32 vcc_lo, s22, s0
	s_addc_u32 vcc_hi, s23, s1
	s_mov_b32 m0, s51
	s_nop 0
	global_load_lds_dwordx4 v144, s[22:23]
	s_add_i32 m0, s51, 0x2000
	s_nop 0
	global_load_lds_dwordx4 v132, s[22:23]
	s_barrier
	s_waitcnt lgkmcnt(3)
	v_mfma_f32_16x16x32_bf16 v[116:119], v[208:211], v[160:163], v[116:119]
	s_waitcnt lgkmcnt(1)
	v_mfma_f32_16x16x32_bf16 v[112:115], v[216:219], v[160:163], v[112:115]
	v_mfma_f32_16x16x32_bf16 v[100:103], v[208:211], v[168:171], v[100:103]
	v_mfma_f32_16x16x32_bf16 v[96:99], v[216:219], v[168:171], v[96:99]
	v_mfma_f32_16x16x32_bf16 v[84:87], v[208:211], v[176:179], v[84:87]
	v_mfma_f32_16x16x32_bf16 v[80:83], v[216:219], v[176:179], v[80:83]
	v_mfma_f32_16x16x32_bf16 v[68:71], v[208:211], v[200:203], v[68:71]
	v_mfma_f32_16x16x32_bf16 v[64:67], v[216:219], v[200:203], v[64:67]
	v_mfma_f32_16x16x32_bf16 v[116:119], v[212:215], v[164:167], v[116:119]
	s_waitcnt lgkmcnt(0)
	v_mfma_f32_16x16x32_bf16 v[112:115], v[220:223], v[164:167], v[112:115]
	v_mfma_f32_16x16x32_bf16 v[100:103], v[212:215], v[172:175], v[100:103]
	v_mfma_f32_16x16x32_bf16 v[96:99], v[220:223], v[172:175], v[96:99]
	v_mfma_f32_16x16x32_bf16 v[84:87], v[212:215], v[196:199], v[84:87]
	v_mfma_f32_16x16x32_bf16 v[80:83], v[220:223], v[196:199], v[80:83]
	v_mfma_f32_16x16x32_bf16 v[68:71], v[212:215], v[204:207], v[68:71]
	v_mfma_f32_16x16x32_bf16 v[64:67], v[220:223], v[204:207], v[64:67]
	s_mov_b32 m0, s39
	s_add_u32 s100, s28, s0
	s_addc_u32 s101, s29, s1
	s_barrier
	ds_read_b128 v[160:163], v147 offset:16384
	ds_read_b128 v[164:167], v147 offset:17408
	ds_read_b128 v[168:171], v147 offset:18432
	ds_read_b128 v[172:175], v147 offset:19456
	ds_read_b128 v[176:179], v147 offset:20480
	ds_read_b128 v[196:199], v147 offset:21504
	ds_read_b128 v[200:203], v147 offset:22528
	ds_read_b128 v[204:207], v147 offset:23552
	global_load_lds_dwordx4 v128, s[28:29]
	s_mov_b32 m0, s40
	s_nop 0
	global_load_lds_dwordx4 v130, s[28:29]
	s_barrier
	s_waitcnt lgkmcnt(7)
	v_mfma_f32_16x16x32_bf16 v[60:63], v[138:141], v[160:163], v[60:63]
	v_mfma_f32_16x16x32_bf16 v[56:59], v[152:155], v[160:163], v[56:59]
	s_waitcnt lgkmcnt(5)
	v_mfma_f32_16x16x32_bf16 v[44:47], v[138:141], v[168:171], v[44:47]
	v_mfma_f32_16x16x32_bf16 v[40:43], v[152:155], v[168:171], v[40:43]
	s_waitcnt lgkmcnt(3)
	v_mfma_f32_16x16x32_bf16 v[28:31], v[138:141], v[176:179], v[28:31]
	v_mfma_f32_16x16x32_bf16 v[24:27], v[152:155], v[176:179], v[24:27]
	s_waitcnt lgkmcnt(1)
	v_mfma_f32_16x16x32_bf16 v[12:15], v[138:141], v[200:203], v[12:15]
	v_mfma_f32_16x16x32_bf16 v[8:11], v[152:155], v[200:203], v[8:11]
	v_mfma_f32_16x16x32_bf16 v[60:63], v[148:151], v[164:167], v[60:63]
	v_mfma_f32_16x16x32_bf16 v[56:59], v[156:159], v[164:167], v[56:59]
	v_mfma_f32_16x16x32_bf16 v[44:47], v[148:151], v[172:175], v[44:47]
	v_mfma_f32_16x16x32_bf16 v[40:43], v[156:159], v[172:175], v[40:43]
	v_mfma_f32_16x16x32_bf16 v[28:31], v[148:151], v[196:199], v[28:31]
	v_mfma_f32_16x16x32_bf16 v[24:27], v[156:159], v[196:199], v[24:27]
	s_waitcnt lgkmcnt(0)
	v_mfma_f32_16x16x32_bf16 v[12:15], v[148:151], v[204:207], v[12:15]
	v_mfma_f32_16x16x32_bf16 v[8:11], v[156:159], v[204:207], v[8:11]
	s_barrier
; #define PG8_STAGE(bufoff, gbase, voff) do { _Pragma("unroll") for (int _i = 0; _i < 2; ++_i) \
;     __builtin_amdgcn_global_load_lds((const unsigned*)((const char*)(gbase) + (voff)[_i]), (LAS unsigned*)(lds + (bufoff) + ldsw + _i * 8192), 16, 0, 0); } while (0)
; #define PG8_LDA(dst, b, h) do { _Pragma("unroll") for (int m = 0; m < 4; ++m) _Pragma("unroll") for (int k = 0; k < 2; ++k) dst[m][k] = *(const LAS bf16x8*)(lds + PG8_SA(b, h) + aoff + m * 2048 + k * 1024); } while (0)
; #define PG8_LDB(dst, b, h) do { _Pragma("unroll") for (int n = 0; n < 2; ++n) _Pragma("unroll") for (int k = 0; k < 2; ++k) dst[n][k] = *(const LAS bf16x8*)(lds + PG8_SB(b, h) + boff + n * 2048 + k * 1024); } while (0)
; #define PG8_MMA(ai, bj, At, Bt) do { __builtin_amdgcn_s_setprio(1); _Pragma("unroll") for (int m = 0; m < 4; ++m) _Pragma("unroll") for (int n = 0; n < 2; ++n) _Pragma("unroll") for (int k = 0; k < 2; ++k) \
;     acc[ai][bj][m][n] = __builtin_amdgcn_mfma_f32_16x16x32_bf16(Bt[n][k], At[m][k], acc[ai][bj][m][n], 0, 0, 0); __builtin_amdgcn_s_setprio(0); } while (0)
; #define PG8_WAIT_V(n) asm volatile("s_waitcnt vmcnt(" #n ")" ::: "memory")
; #define PG8_WAIT_L(n) asm volatile("s_waitcnt lgkmcnt(" #n ")" ::: "memory")
; #define PG8_BAR __builtin_amdgcn_s_barrier()
; #define PG8_SCHED __builtin_amdgcn_sched_barrier(0)
; template <class Epi, class Sched>
; DI void gemm_phase(LAS unsigned char* lds, const Gemm g, const Sched& S, const Epi& E) {
;     ...
;       PG8_WAIT_V(6); PG8_BAR; PG8_MMA(1, 1, At, B1); PG8_BAR;
;       PG8_LDB(B0, 1, 0); PG8_SCHED; PG8_LDA(At, 1, 0); PG8_STAGE(PG8_SA(0, 1), a2 + hstep, voffA);
;       PG8_WAIT_L(8); PG8_BAR; PG8_WAIT_L(0); PG8_MMA(0, 0, At, B0); PG8_BAR; PG8_SCHED;
;       PG8_LDB(B1, 1, 1); PG8_STAGE(PG8_SB(1, 0), b3, voffB);
;       PG8_BAR; PG8_WAIT_L(0); PG8_MMA(0, 1, At, B1); PG8_BAR;
;       PG8_LDA(At, 1, 1); PG8_STAGE(PG8_SA(1, 0), a3, voffA);
;       PG8_BAR; PG8_WAIT_L(0); PG8_MMA(1, 0, At, B0); PG8_BAR; PG8_SCHED;
	s_add_u32 s52, s22, 0x100000
	s_addc_u32 s53, s23, 0
	s_add_i32 s51, s54, s38
	s_mov_b32 m0, s51
	s_nop 0
	global_load_lds_dwordx4 v144, s[52:53]
	s_add_i32 m0, s51, 0x2000
	s_nop 0
	global_load_lds_dwordx4 v132, s[52:53]
	s_waitcnt vmcnt(6)
	s_barrier
	v_mfma_f32_16x16x32_bf16 v[52:55], v[208:211], v[160:163], v[52:55]
	v_mfma_f32_16x16x32_bf16 v[48:51], v[216:219], v[160:163], v[48:51]
	v_mfma_f32_16x16x32_bf16 v[36:39], v[208:211], v[168:171], v[36:39]
	v_mfma_f32_16x16x32_bf16 v[32:35], v[216:219], v[168:171], v[32:35]
	v_mfma_f32_16x16x32_bf16 v[20:23], v[208:211], v[176:179], v[20:23]
	v_mfma_f32_16x16x32_bf16 v[16:19], v[216:219], v[176:179], v[16:19]
	v_mfma_f32_16x16x32_bf16 v[4:7], v[208:211], v[200:203], v[4:7]
	v_mfma_f32_16x16x32_bf16 v[0:3], v[216:219], v[200:203], v[0:3]
	v_mfma_f32_16x16x32_bf16 v[52:55], v[212:215], v[164:167], v[52:55]
	v_mfma_f32_16x16x32_bf16 v[48:51], v[220:223], v[164:167], v[48:51]
	v_mfma_f32_16x16x32_bf16 v[36:39], v[212:215], v[172:175], v[36:39]
	v_mfma_f32_16x16x32_bf16 v[32:35], v[220:223], v[172:175], v[32:35]
	v_mfma_f32_16x16x32_bf16 v[20:23], v[212:215], v[196:199], v[20:23]
	v_mfma_f32_16x16x32_bf16 v[16:19], v[220:223], v[196:199], v[16:19]
	v_mfma_f32_16x16x32_bf16 v[4:7], v[212:215], v[204:207], v[4:7]
	v_mfma_f32_16x16x32_bf16 v[0:3], v[220:223], v[204:207], v[0:3]
	s_add_i32 s51, 0, 0x18000
	s_barrier
	ds_read_b128 v[138:141], v226
	ds_read_b128 v[148:151], v226 offset:1024
	ds_read_b128 v[152:155], v226 offset:2048
	ds_read_b128 v[156:159], v226 offset:3072
	s_add_u32 s28, s28, 0x100000
	s_addc_u32 s29, s29, 0
	s_mov_b32 m0, s41
	ds_read_b128 v[160:163], v147 offset:32768
	ds_read_b128 v[164:167], v147 offset:33792
	ds_read_b128 v[168:171], v147 offset:34816
	ds_read_b128 v[172:175], v147 offset:35840
	ds_read_b128 v[176:179], v147 offset:36864
	ds_read_b128 v[196:199], v147 offset:37888
	ds_read_b128 v[200:203], v147 offset:38912
	ds_read_b128 v[204:207], v147 offset:39936
	global_load_lds_dwordx4 v128, s[28:29]
	s_mov_b32 m0, s42
	s_nop 0
	global_load_lds_dwordx4 v130, s[28:29]
	s_waitcnt lgkmcnt(8)
	s_barrier
	s_waitcnt lgkmcnt(7)
	v_mfma_f32_16x16x32_bf16 v[124:127], v[138:141], v[160:163], v[124:127]
	v_mfma_f32_16x16x32_bf16 v[120:123], v[152:155], v[160:163], v[120:123]
	s_waitcnt lgkmcnt(5)
	v_mfma_f32_16x16x32_bf16 v[108:111], v[138:141], v[168:171], v[108:111]
	v_mfma_f32_16x16x32_bf16 v[104:107], v[152:155], v[168:171], v[104:107]
	s_waitcnt lgkmcnt(3)
	v_mfma_f32_16x16x32_bf16 v[92:95], v[138:141], v[176:179], v[92:95]
	v_mfma_f32_16x16x32_bf16 v[88:91], v[152:155], v[176:179], v[88:91]
	s_waitcnt lgkmcnt(1)
	v_mfma_f32_16x16x32_bf16 v[76:79], v[138:141], v[200:203], v[76:79]
	v_mfma_f32_16x16x32_bf16 v[72:75], v[152:155], v[200:203], v[72:75]
	v_mfma_f32_16x16x32_bf16 v[124:127], v[148:151], v[164:167], v[124:127]
	v_mfma_f32_16x16x32_bf16 v[120:123], v[156:159], v[164:167], v[120:123]
	v_mfma_f32_16x16x32_bf16 v[108:111], v[148:151], v[172:175], v[108:111]
	v_mfma_f32_16x16x32_bf16 v[104:107], v[156:159], v[172:175], v[104:107]
	v_mfma_f32_16x16x32_bf16 v[92:95], v[148:151], v[196:199], v[92:95]
	v_mfma_f32_16x16x32_bf16 v[88:91], v[156:159], v[196:199], v[88:91]
	s_waitcnt lgkmcnt(0)
	v_mfma_f32_16x16x32_bf16 v[76:79], v[148:151], v[204:207], v[76:79]
	v_mfma_f32_16x16x32_bf16 v[72:75], v[156:159], v[204:207], v[72:75]
	s_barrier
	s_add_i32 s28, 0, 0x1c000
	s_add_i32 s29, s51, s38
	s_mov_b32 m0, s29
	ds_read_b128 v[208:211], v227
	ds_read_b128 v[212:215], v227 offset:1024
	ds_read_b128 v[216:219], v227 offset:2048
	ds_read_b128 v[220:223], v227 offset:3072
	global_load_lds_dwordx4 v144, vcc
	s_add_i32 m0, s29, 0x2000
	s_nop 0
	global_load_lds_dwordx4 v132, vcc
	s_barrier
	s_waitcnt lgkmcnt(3)
	v_mfma_f32_16x16x32_bf16 v[116:119], v[208:211], v[160:163], v[116:119]
	s_waitcnt lgkmcnt(1)
	v_mfma_f32_16x16x32_bf16 v[112:115], v[216:219], v[160:163], v[112:115]
	v_mfma_f32_16x16x32_bf16 v[100:103], v[208:211], v[168:171], v[100:103]
	v_mfma_f32_16x16x32_bf16 v[96:99], v[216:219], v[168:171], v[96:99]
	v_mfma_f32_16x16x32_bf16 v[84:87], v[208:211], v[176:179], v[84:87]
	v_mfma_f32_16x16x32_bf16 v[80:83], v[216:219], v[176:179], v[80:83]
	v_mfma_f32_16x16x32_bf16 v[68:71], v[208:211], v[200:203], v[68:71]
	v_mfma_f32_16x16x32_bf16 v[64:67], v[216:219], v[200:203], v[64:67]
	v_mfma_f32_16x16x32_bf16 v[116:119], v[212:215], v[164:167], v[116:119]
	s_waitcnt lgkmcnt(0)
	v_mfma_f32_16x16x32_bf16 v[112:115], v[220:223], v[164:167], v[112:115]
	v_mfma_f32_16x16x32_bf16 v[100:103], v[212:215], v[172:175], v[100:103]
	v_mfma_f32_16x16x32_bf16 v[96:99], v[220:223], v[172:175], v[96:99]
	v_mfma_f32_16x16x32_bf16 v[84:87], v[212:215], v[196:199], v[84:87]
	v_mfma_f32_16x16x32_bf16 v[80:83], v[220:223], v[196:199], v[80:83]
	v_mfma_f32_16x16x32_bf16 v[68:71], v[212:215], v[204:207], v[68:71]
	v_mfma_f32_16x16x32_bf16 v[64:67], v[220:223], v[204:207], v[64:67]
	s_mov_b32 m0, s46
	s_barrier
	ds_read_b128 v[160:163], v147 offset:49152
	ds_read_b128 v[164:167], v147 offset:50176
	ds_read_b128 v[168:171], v147 offset:51200
	ds_read_b128 v[172:175], v147 offset:52224
	ds_read_b128 v[176:179], v147 offset:53248
	ds_read_b128 v[196:199], v147 offset:54272
	ds_read_b128 v[200:203], v147 offset:55296
	ds_read_b128 v[204:207], v147 offset:56320
	global_load_lds_dwordx4 v128, s[100:101]
	s_mov_b32 m0, s47
	s_nop 0
	global_load_lds_dwordx4 v130, s[100:101]
	s_barrier
; template <class Epi, class Sched>
; DI void gemm_phase(LAS unsigned char* lds, const Gemm g, const Sched& S, const Epi& E) {
;     ...
;       PG8_BAR; PG8_WAIT_L(0); PG8_MMA(1, 0, At, B0); PG8_BAR; PG8_SCHED;
;       PG8_STAGE(PG8_SB(1, 1), b3 + hstep, voffB);
;       PG8_WAIT_V(6); PG8_BAR; PG8_MMA(1, 1, At, B1); PG8_BAR;
;     }
;   DI void operator()(const f32x4 (&acc)[2][2][4][2], const pg8::Unit& u, int wr, int wc, int fr_, int fq_) const {
;     ...
;             } else if (EPI == EPI_RESID) {
;               if (n == 0) {
;                 const int f8 = u.pn * 256 + bj * 128 + wc * 32 + 8 * fq;
;                 const f32x4 v1 = acc[ai][bj][m][1];
;                 f32x4 r0, r1;
;                 if (rsrc) {
;                   r0 = *(const f32x4*)(rsrc + (size_t)token * 1024 + f8); r1 = *(const f32x4*)(rsrc + (size_t)token * 1024 + f8 + 4);
;                 } else {
;                   const u32x4 xu = *(const u32x4*)(xr + (size_t)token * 1024 + f8);
;                   r0 = (f32x4){bf2f(xu.x & 0xffffu), bf2f(xu.x >> 16), bf2f(xu.y & 0xffffu), bf2f(xu.y >> 16)};
;                   r1 = (f32x4){bf2f(xu.z & 0xffffu), bf2f(xu.z >> 16), bf2f(xu.w & 0xffffu), bf2f(xu.w >> 16)};
;                 }
;                 r0 += v; r1 += v1;
;                 st_bf8(xr + (size_t)token * 1024 + f8, r0, r1, 1.f);
;                 ssq += r0[0] * r0[0] + r0[1] * r0[1] + r0[2] * r0[2] + r0[3] * r0[3] + r1[0] * r1[0] + r1[1] * r1[1] + r1[2] * r1[2] + r1[3] * r1[3];
;               }
;             } else {
;               if (n == 0) {
;                 const f32x4 v1 = acc[ai][bj][m][1];
;                 u32x4 o4;
;                 { const float t0 = fmaxf(v[0], 0.f) * rinv, t1 = fmaxf(v[1], 0.f) * rinv, t2 = fmaxf(v[2], 0.f) * rinv, t3 = fmaxf(v[3], 0.f) * rinv;
;                   o4.x = pack2(t0 * t0, t1 * t1); o4.y = pack2(t2 * t2, t3 * t3); }
;                 { const float t0 = fmaxf(v1[0], 0.f) * rinv, t1 = fmaxf(v1[1], 0.f) * rinv, t2 = fmaxf(v1[2], 0.f) * rinv, t3 = fmaxf(v1[3], 0.f) * rinv;
;                   o4.z = pack2(t0 * t0, t1 * t1); o4.w = pack2(t2 * t2, t3 * t3); }
;                 *(u32x4*)((u16*)big + (size_t)token * 4096 + u.pn * 256 + bj * 128 + wc * 32 + 8 * fq) = o4;
;               }
;             }
;           }
;         if (EPI == EPI_RESID) {
;           ssq += shx(ssq, 16, t_ & 63);
;           ssq += shx(ssq, 32, t_ & 63);
	s_waitcnt lgkmcnt(7)
	v_mfma_f32_16x16x32_bf16 v[60:63], v[138:141], v[160:163], v[60:63]
	v_mfma_f32_16x16x32_bf16 v[56:59], v[152:155], v[160:163], v[56:59]
	s_waitcnt lgkmcnt(5)
	v_mfma_f32_16x16x32_bf16 v[44:47], v[138:141], v[168:171], v[44:47]
	v_mfma_f32_16x16x32_bf16 v[40:43], v[152:155], v[168:171], v[40:43]
	s_waitcnt lgkmcnt(3)
	v_mfma_f32_16x16x32_bf16 v[28:31], v[138:141], v[176:179], v[28:31]
	v_mfma_f32_16x16x32_bf16 v[24:27], v[152:155], v[176:179], v[24:27]
	s_waitcnt lgkmcnt(1)
	v_mfma_f32_16x16x32_bf16 v[12:15], v[138:141], v[200:203], v[12:15]
	v_mfma_f32_16x16x32_bf16 v[8:11], v[152:155], v[200:203], v[8:11]
	v_mfma_f32_16x16x32_bf16 v[60:63], v[148:151], v[164:167], v[60:63]
	v_mfma_f32_16x16x32_bf16 v[56:59], v[156:159], v[164:167], v[56:59]
	v_mfma_f32_16x16x32_bf16 v[44:47], v[148:151], v[172:175], v[44:47]
	v_mfma_f32_16x16x32_bf16 v[40:43], v[156:159], v[172:175], v[40:43]
	v_mfma_f32_16x16x32_bf16 v[28:31], v[148:151], v[196:199], v[28:31]
	v_mfma_f32_16x16x32_bf16 v[24:27], v[156:159], v[196:199], v[24:27]
	s_waitcnt lgkmcnt(0)
	v_mfma_f32_16x16x32_bf16 v[12:15], v[148:151], v[204:207], v[12:15]
	v_mfma_f32_16x16x32_bf16 v[8:11], v[156:159], v[204:207], v[8:11]
	s_barrier
	s_add_u32 s22, s22, 0x100080
	s_addc_u32 s23, s23, 0
	s_add_i32 s28, s28, s38
	s_mov_b32 m0, s28
	s_nop 0
	global_load_lds_dwordx4 v144, s[22:23]
	s_add_i32 m0, s28, 0x2000
	s_nop 0
	global_load_lds_dwordx4 v132, s[22:23]
	s_waitcnt vmcnt(6)
	s_barrier
	v_mfma_f32_16x16x32_bf16 v[52:55], v[208:211], v[160:163], v[52:55]
	v_mfma_f32_16x16x32_bf16 v[48:51], v[216:219], v[160:163], v[48:51]
	v_mfma_f32_16x16x32_bf16 v[36:39], v[208:211], v[168:171], v[36:39]
	v_mfma_f32_16x16x32_bf16 v[32:35], v[216:219], v[168:171], v[32:35]
	v_mfma_f32_16x16x32_bf16 v[20:23], v[208:211], v[176:179], v[20:23]
	v_mfma_f32_16x16x32_bf16 v[16:19], v[216:219], v[176:179], v[16:19]
	v_mfma_f32_16x16x32_bf16 v[4:7], v[208:211], v[200:203], v[4:7]
	v_mfma_f32_16x16x32_bf16 v[0:3], v[216:219], v[200:203], v[0:3]
	v_mfma_f32_16x16x32_bf16 v[52:55], v[212:215], v[164:167], v[52:55]
	v_mfma_f32_16x16x32_bf16 v[48:51], v[220:223], v[164:167], v[48:51]
	v_mfma_f32_16x16x32_bf16 v[36:39], v[212:215], v[172:175], v[36:39]
	v_mfma_f32_16x16x32_bf16 v[32:35], v[220:223], v[172:175], v[32:35]
	v_mfma_f32_16x16x32_bf16 v[20:23], v[212:215], v[196:199], v[20:23]
	v_mfma_f32_16x16x32_bf16 v[16:19], v[220:223], v[196:199], v[16:19]
	v_mfma_f32_16x16x32_bf16 v[4:7], v[212:215], v[204:207], v[4:7]
	v_mfma_f32_16x16x32_bf16 v[0:3], v[220:223], v[204:207], v[0:3]
	s_add_i32 s50, s50, 2
	s_add_u32 s20, s20, 0x100
	s_addc_u32 s21, s21, 0
	s_add_u32 s24, s24, 0x100
	s_addc_u32 s49, s49, 0
	s_cmp_gt_u32 s50, 61
	s_barrier
	s_cbranch_scc0 .LBB0_1905
	s_lshl_b32 s7, s18, 8
	v_mov_b32_e32 v139, v182
	s_add_i32 s7, s7, s44
	s_nop 0
	v_and_or_b32 v140, v139, 15, s7
	s_lshl_b32 s7, s16, 8
	v_bfe_u32 v141, v139, 4, 2
	s_or_b32 s7, s7, s45
	v_lshl_or_b32 v138, v141, 3, s7
	v_cmp_eq_u32_e32 vcc, 0, v141
	v_ashrrev_i32_e32 v141, 31, v140
	v_lshlrev_b32_e32 v139, 2, v139
	s_movk_i32 s7, 0x80
	v_lshlrev_b64 v[142:143], 11, v[140:141]
	v_bitop3_b32 v149, v139, 64, v190 bitop3:0x6c
	v_bitop3_b32 v148, v139, s7, v190 bitop3:0x6c
	v_ashrrev_i32_e32 v139, 31, v138
	v_lshl_add_u64 v[142:143], s[4:5], 0, v[142:143]
	v_lshl_add_u64 v[142:143], v[138:139], 1, v[142:143]
	global_load_dwordx4 v[150:153], v[142:143], off
	s_lshl_b32 s16, s16, 2
	s_ashr_i32 s17, s16, 31
	s_waitcnt vmcnt(0)
	v_lshlrev_b32_e32 v154, 16, v150
	v_and_b32_e32 v155, 0xffff0000, v150
	v_lshlrev_b32_e32 v150, 16, v151
	v_and_b32_e32 v151, 0xffff0000, v151
	v_lshlrev_b32_e32 v156, 16, v152
	v_and_b32_e32 v157, 0xffff0000, v152
	v_lshlrev_b32_e32 v152, 16, v153
	v_and_b32_e32 v153, 0xffff0000, v153
	v_pk_add_f32 v[126:127], v[126:127], v[150:151]
	v_pk_add_f32 v[124:125], v[124:125], v[154:155]
	v_pk_add_f32 v[150:151], v[122:123], v[152:153]
	v_pk_add_f32 v[152:153], v[120:121], v[156:157]
	v_cvt_pk_bf16_f32 v120, v124, v125
	v_cvt_pk_bf16_f32 v121, v126, v127
	v_cvt_pk_bf16_f32 v122, v152, v153
	v_cvt_pk_bf16_f32 v123, v150, v151
	global_store_dwordx4 v[142:143], v[120:123], off
	global_load_dwordx4 v[120:123], v[142:143], off offset:256
	v_mul_f32_e32 v154, v125, v125
	v_fmac_f32_e32 v154, v124, v124
	v_fmac_f32_e32 v154, v126, v126
	v_fmac_f32_e32 v154, v127, v127
	v_fmac_f32_e32 v154, v152, v152
	v_fmac_f32_e32 v154, v153, v153
	v_fmac_f32_e32 v154, v150, v150
	v_fmac_f32_e32 v154, v151, v151
	s_waitcnt vmcnt(0)
	v_lshlrev_b32_e32 v124, 16, v120
	v_and_b32_e32 v125, 0xffff0000, v120
	v_lshlrev_b32_e32 v120, 16, v121
	v_and_b32_e32 v121, 0xffff0000, v121
	v_lshlrev_b32_e32 v126, 16, v122
	v_and_b32_e32 v127, 0xffff0000, v122
	v_lshlrev_b32_e32 v122, 16, v123
	v_and_b32_e32 v123, 0xffff0000, v123
	v_pk_add_f32 v[118:119], v[118:119], v[120:121]
	v_pk_add_f32 v[116:117], v[116:117], v[124:125]
	v_pk_add_f32 v[120:121], v[114:115], v[122:123]
	v_pk_add_f32 v[122:123], v[112:113], v[126:127]
	v_cvt_pk_bf16_f32 v112, v116, v117
	v_cvt_pk_bf16_f32 v113, v118, v119
	v_cvt_pk_bf16_f32 v114, v122, v123
	v_cvt_pk_bf16_f32 v115, v120, v121
	global_store_dwordx4 v[142:143], v[112:115], off offset:256
	s_nop 1
	v_mul_f32_e32 v112, v117, v117
	v_fmac_f32_e32 v112, v116, v116
	v_fmac_f32_e32 v112, v118, v118
	v_fmac_f32_e32 v112, v119, v119
	v_fmac_f32_e32 v112, v122, v122
	v_fmac_f32_e32 v112, v123, v123
	v_fmac_f32_e32 v112, v120, v120
	v_fmac_f32_e32 v112, v121, v121
	v_add_f32_e32 v112, v154, v112
	ds_bpermute_b32 v113, v149, v112
	s_waitcnt lgkmcnt(0)
	v_add_f32_e32 v112, v112, v113
	ds_bpermute_b32 v113, v148, v112
	s_and_saveexec_b64 s[18:19], vcc
	s_cbranch_execz .LBB0_1908
	s_waitcnt lgkmcnt(0)
	v_add_f32_e32 v114, v112, v113
	v_lshlrev_b64 v[112:113], 6, v[140:141]
	v_lshl_add_u64 v[112:113], s[2:3], 0, v[112:113]
	v_lshl_add_u64 v[112:113], s[16:17], 2, v[112:113]
	s_lshl_b32 s24, s43, 2
	v_lshl_add_u64 v[112:113], v[112:113], 0, s[24:25]
	global_store_dword v[112:113], v114, off
